# GEMM3: wave's two column groups made adjacent (LDS read remap); merge epilogue MRG loads/stores cover full 128B lines via DPP row rotate pairing
# speedup vs baseline: 1.0064x; 1.0064x over previous
;     __device__ __forceinline__ const char* aptr(const Unit& u, const Gemm& g) const { return (const char*)g.A + (long)(u.pm >> 4) * g.adj; }
;     __device__ __forceinline__ const char* bptr(const Unit&, const Gemm& g) const { return (const char*)g.Bt; }
; #define PG8_STAGE(bufoff, gbase, voff) do { _Pragma("unroll") for (int _i = 0; _i < 2; ++_i) \
;         __builtin_amdgcn_global_load_lds((const unsigned*)((const char*)(gbase) + (voff)[_i]), (PG8_LAS unsigned*)(lds + (bufoff) + ldsw + _i * 8192), 16, 0, 0); } while (0)
; #define PG8_WAIT_V(n) asm volatile("s_waitcnt vmcnt(" #n ")" ::: "memory")
; #define PG8_BAR __builtin_amdgcn_s_barrier()
; template <class Epi, class Sched, bool ALIGN_EPI = false, bool SP2 = false>
; __device__ __forceinline__ void gemm_phase(PG8_LAS unsigned char* lds, const Gemm g, const Sched& S, const Epi& E) {
;     ...
;     const int aoff = lds_byte(wr * 64 + fr, fq * 8), boff = lds_byte(wc * 32 + fr, fq * 8);
;     ...
;     f32x4 acc[2][2][4][2];
; #pragma unroll
;     for (int a = 0; a < 2; ++a)
; #pragma unroll
;         for (int b = 0; b < 2; ++b)
; #pragma unroll
;             for (int m = 0; m < 4; ++m)
; #pragma unroll
;                 for (int n = 0; n < 2; ++n) acc[a][b][m][n] = (f32x4){0.f, 0.f, 0.f, 0.f};
;     bf16x8 At[4][2], B0[2][2], B1[2][2];
;     const char* cA = S.aptr(cur, g) + (size_t)cur.pm * tstep; const char* cB = S.bptr(cur, g) + (size_t)cur.pn * tstep;
;     S.a_ready(cur);
;     if constexpr (SP2) {
;         PG8_STAGE(PG8_SB(0, 0), cB, voffB); PG8_STAGE(PG8_SB(0, 1), cB + hstep, voffB); PG8_STAGE(PG8_SA(0, 0), cA, voffA); PG8_STAGE(PG8_SA(0, 1), cA + hstep, voffA);
;         if (wr == 1) PG8_BAR;
;         PG8_WAIT_V(2); PG8_BAR;
;         PG8_STAGE(PG8_SB(1, 0), cB + kstep, voffB); PG8_STAGE(PG8_SA(1, 0), cA + kstep, voffA); PG8_STAGE(PG8_SB(1, 1), cB + hstep + kstep, voffB);
;         PG8_WAIT_V(6); PG8_BAR;
;     } else {
;         PG8_STAGE(PG8_SB(0, 0), cB, voffB); PG8_STAGE(PG8_SA(0, 0), cA, voffA); PG8_STAGE(PG8_SB(0, 1), cB + hstep, voffB); PG8_STAGE(PG8_SA(0, 1), cA + hstep, voffA);
;         if (wr == 1) PG8_BAR;
;         PG8_WAIT_V(4); PG8_BAR;
;         PG8_STAGE(PG8_SB(1, 0), cB + kstep, voffB); PG8_STAGE(PG8_SA(1, 0), cA + kstep, voffA); PG8_STAGE(PG8_SB(1, 1), cB + hstep + kstep, voffB);
;         PG8_WAIT_V(6); PG8_BAR;
.LBB0_468:
	s_and_b64 s[10:11], s[24:25], exec
	s_cselect_b32 s61, 0x200, 2
	s_cselect_b32 s62, s86, 32
	s_add_u32 s43, s90, s28
	s_mul_i32 s10, s87, 0xc00
	s_addc_u32 s49, s91, s29
	s_ashr_i32 s11, s10, 31
	s_lshl_b64 s[10:11], s[10:11], 2
	s_waitcnt lgkmcnt(0)
	s_add_u32 s63, s30, s10
	s_addc_u32 s64, s31, s11
	s_add_u32 s10, s90, s26
	s_addc_u32 s11, s91, s27
	s_lshl_b32 s26, s97, 5
	s_and_b32 s26, s26, 0xe0
	s_add_i32 s26, s26, s46
	v_bfe_u32 v16, v13, 4, 2
	s_and_b64 s[24:25], s[24:25], exec
	v_and_b32_e32 v15, 15, v13
	v_lshlrev_b32_e32 v192, 4, v16
	v_lshlrev_b32_e32 v13, 2, v13
	s_cselect_b32 s30, s80, s26
	s_and_b32 s26, s48, 3
	v_lshlrev_b32_e32 v17, 3, v16
	v_lshl_or_b32 v16, v15, 6, v192
	s_lshl_b32 s24, s47, 13
	v_and_b32_e32 v13, 32, v13
	s_add_i32 m0, s55, 0x18000
	v_lshl_add_u64 v[6:7], v[6:7], 0, s[36:37]
	v_bitop3_b32 v18, v16, s24, v13 bitop3:0xde
	s_lshl_b32 s24, s26, 13
	s_waitcnt vmcnt(2)
	s_barrier
	global_load_lds_dwordx4 v[6:7], off
	v_lshl_add_u64 v[4:5], v[4:5], 0, s[36:37]
	s_add_i32 m0, s55, 0x1a000
	s_add_i32 s65, s55, 0x8000
	s_add_i32 s66, s55, 0xa000
	v_bitop3_b32 v246, v16, s24, v13 bitop3:0xde
	global_load_lds_dwordx4 v[4:5], off
	v_lshl_add_u64 v[0:1], v[0:1], 0, s[36:37]
	s_mov_b32 m0, s65
	s_add_u32 s24, s50, 0x40080
	global_load_lds_dwordx4 v[0:1], off
	v_lshl_add_u64 v[0:1], v[2:3], 0, s[36:37]
	s_mov_b32 m0, s66
	s_addc_u32 s25, s51, 0
	global_load_lds_dwordx4 v[0:1], off
	s_add_i32 m0, s55, 0x1c000
	v_lshl_add_u64 v[0:1], s[24:25], 0, v[198:199]
	global_load_lds_dwordx4 v[0:1], off
	v_lshl_add_u64 v[0:1], s[24:25], 0, v[194:195]
	s_add_i32 m0, s55, 0x1e000
	s_cmpk_lt_u32 s45, 0x100
	global_load_lds_dwordx4 v[0:1], off
	v_lshl_or_b32 v247, s26, 6, v17
	s_cselect_b64 s[24:25], -1, 0
	s_and_b32 s27, s45, 0xfffff00
	s_lshl_b32 s26, s26, 6
	s_or_b32 s26, s26, s27
	s_add_u32 s67, s41, 0xeb00000
	s_addc_u32 s68, s44, 0
	v_or3_b32 v0, s26, v192, v15
	s_add_u32 s26, s41, 0x1b700000
	s_addc_u32 s27, s44, 0
	s_add_u32 s69, s19, 0xe00000
	s_addc_u32 s70, s40, 0
	s_add_u32 s28, s19, 0x1000000
	s_addc_u32 s29, s40, 0
	v_lshlrev_b32_e32 v248, 4, v0
	s_add_u32 s71, s43, 0xd700000
	v_lshlrev_b32_e32 v0, 14, v12
	s_addc_u32 s72, s49, 0
	s_ashr_i32 s19, s30, 5
	v_and_b32_e32 v0, 0xffff8000, v0
	s_mul_hi_i32 s31, s19, 0x1c00000
	s_mul_i32 s19, s19, 0x1c00000
	v_lshl_add_u32 v0, v11, 11, v0
	v_and_b32_e32 v1, 1, v12
	s_add_u32 s19, s71, s19
	v_lshl_or_b32 v0, v1, 6, v0
	s_addc_u32 s31, s72, s31
	s_lshl_b32 s30, s30, 17
	v_lshl_add_u32 v204, v14, 1, v0
	v_lshlrev_b32_e32 v0, 14, v8
	s_and_b32 s30, s30, 0x3e0000
	v_and_b32_e32 v0, 0xffff8000, v0
	s_add_u32 s19, s19, s30
	v_lshl_add_u32 v0, v9, 11, v0
	v_and_b32_e32 v1, 1, v8
	s_waitcnt vmcnt(6)
	s_addc_u32 s31, s31, 0
	v_lshl_or_b32 v0, v1, 6, v0
	s_add_u32 s30, s19, 0x800000
	v_lshl_add_u32 v206, v10, 1, v0
	v_mov_b32_e32 v0, 0
	v_lshl_or_b32 v245, s47, 6, v15
	s_addc_u32 s31, s31, 0
	v_lshl_add_u64 v[202:203], s[10:11], 0, v[192:193]
	v_mov_b32_e32 v205, v193
	v_mov_b32_e32 v207, v193
	s_mov_b32 s43, 0
	v_add_u32_e32 v249, 0, v18
	s_mov_b32 s73, 0
	v_mov_b64_e32 v[0:1], 0
	v_mov_b64_e32 v[2:3], 0
	v_mov_b64_e32 v[4:5], 0
	v_mov_b64_e32 v[6:7], 0
	v_mov_b64_e32 v[8:9], 0
	v_mov_b64_e32 v[10:11], 0
	v_mov_b64_e32 v[12:13], 0
	v_mov_b64_e32 v[14:15], 0
	v_mov_b64_e32 v[16:17], 0
	v_mov_b64_e32 v[18:19], 0
	v_mov_b64_e32 v[20:21], 0
	v_mov_b64_e32 v[22:23], 0
	v_mov_b64_e32 v[24:25], 0
	v_mov_b64_e32 v[26:27], 0
	v_mov_b64_e32 v[28:29], 0
	v_mov_b64_e32 v[30:31], 0
	v_mov_b64_e32 v[32:33], 0
	v_mov_b64_e32 v[34:35], 0
	v_mov_b64_e32 v[36:37], 0
	v_mov_b64_e32 v[38:39], 0
	v_mov_b64_e32 v[40:41], 0
	v_mov_b64_e32 v[42:43], 0
	v_mov_b64_e32 v[44:45], 0
	v_mov_b64_e32 v[46:47], 0
	v_mov_b64_e32 v[48:49], 0
	v_mov_b64_e32 v[50:51], 0
	v_mov_b64_e32 v[52:53], 0
	v_mov_b64_e32 v[54:55], 0
	v_mov_b64_e32 v[56:57], 0
	v_mov_b64_e32 v[58:59], 0
	v_mov_b64_e32 v[60:61], 0
	v_mov_b64_e32 v[62:63], 0
	v_mov_b64_e32 v[64:65], 0
	v_mov_b64_e32 v[66:67], 0
	v_mov_b64_e32 v[68:69], 0
	v_mov_b64_e32 v[70:71], 0
	v_mov_b64_e32 v[72:73], 0
	v_mov_b64_e32 v[74:75], 0
	v_mov_b64_e32 v[76:77], 0
	v_mov_b64_e32 v[78:79], 0
	v_mov_b64_e32 v[80:81], 0
	v_mov_b64_e32 v[82:83], 0
	v_mov_b64_e32 v[84:85], 0
	v_mov_b64_e32 v[86:87], 0
	v_mov_b64_e32 v[88:89], 0
	v_mov_b64_e32 v[90:91], 0
	v_mov_b64_e32 v[92:93], 0
	v_mov_b64_e32 v[94:95], 0
	v_mov_b64_e32 v[96:97], 0
	v_mov_b64_e32 v[98:99], 0
	v_mov_b64_e32 v[100:101], 0
	v_mov_b64_e32 v[102:103], 0
	v_mov_b64_e32 v[104:105], 0
	v_mov_b64_e32 v[106:107], 0
	v_mov_b64_e32 v[108:109], 0
	v_mov_b64_e32 v[110:111], 0
	v_mov_b64_e32 v[112:113], 0
	v_mov_b64_e32 v[114:115], 0
	v_mov_b64_e32 v[116:117], 0
	v_mov_b64_e32 v[118:119], 0
	v_mov_b64_e32 v[120:121], 0
	v_mov_b64_e32 v[122:123], 0
	v_mov_b64_e32 v[124:125], 0
	v_mov_b64_e32 v[126:127], 0
	s_mov_b64 s[44:45], s[34:35]
	s_mov_b32 s4, 0x10000
	s_mov_b32 s5, 0x12000
	s_mov_b32 s6, 0x14000
	s_mov_b32 s7, 0x16000
	s_mov_b32 s79, 0x18000
	s_mov_b32 s85, 0x1a000
	s_mov_b32 s87, 0x1c000
	s_barrier
	s_branch .LBB0_471

; #define PG8_STAGE(bufoff, gbase, voff) do { _Pragma("unroll") for (int _i = 0; _i < 2; ++_i) \
;         __builtin_amdgcn_global_load_lds((const unsigned*)((const char*)(gbase) + (voff)[_i]), (PG8_LAS unsigned*)(lds + (bufoff) + ldsw + _i * 8192), 16, 0, 0); } while (0)
; #define PG8_LDA(dst, b, h) do { _Pragma("unroll") for (int m = 0; m < 4; ++m) _Pragma("unroll") for (int k = 0; k < 2; ++k) dst[m][k] = *(const PG8_LAS bf16x8*)(lds + PG8_SA(b, h) + aoff + m * 2048 + k * 1024); } while (0)
; #define PG8_LDB(dst, b, h) do { _Pragma("unroll") for (int n = 0; n < 2; ++n) _Pragma("unroll") for (int k = 0; k < 2; ++k) dst[n][k] = *(const PG8_LAS bf16x8*)(lds + PG8_SB(b, h) + boff + n * 2048 + k * 1024); } while (0)
; #define PG8_MMA(ai, bj, At, Bt) do { __builtin_amdgcn_s_setprio(1); _Pragma("unroll") for (int m = 0; m < 4; ++m) _Pragma("unroll") for (int n = 0; n < 2; ++n) _Pragma("unroll") for (int k = 0; k < 2; ++k) \
;         acc[ai][bj][m][n] = __builtin_amdgcn_mfma_f32_16x16x32_bf16(Bt[n][k], At[m][k], acc[ai][bj][m][n], 0, 0, 0); __builtin_amdgcn_s_setprio(0); } while (0)
; #define PG8_WAIT_V(n) asm volatile("s_waitcnt vmcnt(" #n ")" ::: "memory")
; #define PG8_WAIT_L(n) asm volatile("s_waitcnt lgkmcnt(" #n ")" ::: "memory")
; #define PG8_BAR __builtin_amdgcn_s_barrier()
; #define PG8_SCHED __builtin_amdgcn_sched_barrier(0)
; template <class Epi, class Sched, bool ALIGN_EPI = false, bool SP2 = false>
; __device__ __forceinline__ void gemm_phase(PG8_LAS unsigned char* lds, const Gemm g, const Sched& S, const Epi& E) {
;     ...
;             PG8_LDB(B0, 0, 0); PG8_LDB(B1, 0, 1); PG8_SCHED; PG8_LDA(At, 0, 0); PG8_STAGE(PG8_SA(1, 1), a1 + hstep, voffA);
;             PG8_WAIT_V(8); PG8_WAIT_L(0); PG8_BAR; PG8_MMA(0, 0, At, B0); PG8_MMA(0, 1, At, B1); PG8_BAR; PG8_SCHED;
;             PG8_LDA(At, 0, 1); PG8_STAGE(PG8_SB(0, 0), b2, voffB); PG8_STAGE(PG8_SB(0, 1), b2 + hstep, voffB); PG8_STAGE(PG8_SA(0, 0), a2, voffA);
;             PG8_WAIT_V(8); PG8_WAIT_L(0); PG8_BAR; PG8_MMA(1, 0, At, B0); PG8_MMA(1, 1, At, B1); PG8_BAR; PG8_SCHED;
.LBB0_488:
	s_add_u32 s10, s34, 0xfffc0080
	s_addc_u32 s11, s35, -1
	s_add_i32 s77, 0, 0x10000
	s_cmp_eq_u32 s76, 4
	s_cselect_b32 s53, s45, s11
	s_cselect_b32 s52, s44, s10
	s_cselect_b32 s51, s49, s75
	s_cselect_b32 s50, s48, s19
	s_add_i32 s78, 0, 0x14000
	v_add_u32_e32 v140, s77, v246
	v_add_u32_e32 v156, s77, v246
	v_add_u32_e32 v156, 0x1000, v156
	ds_read_b128 v[128:131], v140
	ds_read_b128 v[132:135], v140 offset:1024
	ds_read_b128 v[136:139], v140 offset:2048
	ds_read_b128 v[140:143], v140 offset:3072
	ds_read_b128 v[144:147], v156
	ds_read_b128 v[148:151], v156 offset:1024
	ds_read_b128 v[152:155], v156 offset:2048
	ds_read_b128 v[156:159], v156 offset:3072
	v_lshl_add_u64 v[208:209], s[34:35], 0, v[204:205]
	s_add_i32 m0, s55, 0xc000
	ds_read_b128 v[160:163], v249
	ds_read_b128 v[164:167], v249 offset:1024
	ds_read_b128 v[168:171], v249 offset:2048
	ds_read_b128 v[172:175], v249 offset:3072
	ds_read_b128 v[176:179], v249 offset:4096
	ds_read_b128 v[180:183], v249 offset:5120
	ds_read_b128 v[184:187], v249 offset:6144
	ds_read_b128 v[188:191], v249 offset:7168
	global_load_lds_dwordx4 v[208:209], off
	v_lshl_add_u64 v[208:209], s[34:35], 0, v[206:207]
	s_add_i32 m0, s55, 0xe000
	s_nop 0
	global_load_lds_dwordx4 v[208:209], off
	s_waitcnt vmcnt(8)
	s_waitcnt lgkmcnt(0)
	s_barrier
	s_setprio 1
	s_waitcnt lgkmcnt(0)
	v_mfma_f32_16x16x32_bf16 v[124:127], v[128:131], v[160:163], v[124:127]
	v_mfma_f32_16x16x32_bf16 v[120:123], v[136:139], v[160:163], v[120:123]
	v_mfma_f32_16x16x32_bf16 v[116:119], v[128:131], v[168:171], v[116:119]
	v_mfma_f32_16x16x32_bf16 v[112:115], v[136:139], v[168:171], v[112:115]
	v_mfma_f32_16x16x32_bf16 v[108:111], v[128:131], v[176:179], v[108:111]
	v_mfma_f32_16x16x32_bf16 v[104:107], v[136:139], v[176:179], v[104:107]
	v_mfma_f32_16x16x32_bf16 v[100:103], v[128:131], v[184:187], v[100:103]
	v_mfma_f32_16x16x32_bf16 v[96:99], v[136:139], v[184:187], v[96:99]
	v_mfma_f32_16x16x32_bf16 v[124:127], v[132:135], v[164:167], v[124:127]
	v_mfma_f32_16x16x32_bf16 v[120:123], v[140:143], v[164:167], v[120:123]
	v_mfma_f32_16x16x32_bf16 v[116:119], v[132:135], v[172:175], v[116:119]
	v_mfma_f32_16x16x32_bf16 v[112:115], v[140:143], v[172:175], v[112:115]
	v_mfma_f32_16x16x32_bf16 v[108:111], v[132:135], v[180:183], v[108:111]
	v_mfma_f32_16x16x32_bf16 v[104:107], v[140:143], v[180:183], v[104:107]
	v_mfma_f32_16x16x32_bf16 v[100:103], v[132:135], v[188:191], v[100:103]
	v_mfma_f32_16x16x32_bf16 v[96:99], v[140:143], v[188:191], v[96:99]
	s_setprio 0
	s_setprio 1
	v_mfma_f32_16x16x32_bf16 v[92:95], v[144:147], v[160:163], v[92:95]
	v_mfma_f32_16x16x32_bf16 v[88:91], v[152:155], v[160:163], v[88:91]
	v_mfma_f32_16x16x32_bf16 v[84:87], v[144:147], v[168:171], v[84:87]
	v_mfma_f32_16x16x32_bf16 v[80:83], v[152:155], v[168:171], v[80:83]
	v_mfma_f32_16x16x32_bf16 v[76:79], v[144:147], v[176:179], v[76:79]
	v_mfma_f32_16x16x32_bf16 v[72:75], v[152:155], v[176:179], v[72:75]
	v_mfma_f32_16x16x32_bf16 v[68:71], v[144:147], v[184:187], v[68:71]
	v_mfma_f32_16x16x32_bf16 v[64:67], v[152:155], v[184:187], v[64:67]
	v_mfma_f32_16x16x32_bf16 v[92:95], v[148:151], v[164:167], v[92:95]
	v_mfma_f32_16x16x32_bf16 v[88:91], v[156:159], v[164:167], v[88:91]
	v_mfma_f32_16x16x32_bf16 v[84:87], v[148:151], v[172:175], v[84:87]
	v_mfma_f32_16x16x32_bf16 v[80:83], v[156:159], v[172:175], v[80:83]
	v_mfma_f32_16x16x32_bf16 v[76:79], v[148:151], v[180:183], v[76:79]
	v_mfma_f32_16x16x32_bf16 v[72:75], v[156:159], v[180:183], v[72:75]
	v_mfma_f32_16x16x32_bf16 v[68:71], v[148:151], v[188:191], v[68:71]
	v_mfma_f32_16x16x32_bf16 v[64:67], v[156:159], v[188:191], v[64:67]
	s_setprio 0
	s_barrier
	s_add_i32 s10, s77, s14
	v_lshl_add_u64 v[208:209], s[50:51], 0, v[198:199]
	s_mov_b32 m0, s10
	ds_read_b128 v[160:163], v249 offset:16384
	ds_read_b128 v[164:167], v249 offset:17408
	ds_read_b128 v[168:171], v249 offset:18432
	ds_read_b128 v[172:175], v249 offset:19456
	ds_read_b128 v[176:179], v249 offset:20480
	ds_read_b128 v[180:183], v249 offset:21504
	ds_read_b128 v[184:187], v249 offset:22528
	ds_read_b128 v[188:191], v249 offset:23552
	global_load_lds_dwordx4 v[208:209], off
	s_add_i32 m0, s10, 0x2000
	s_add_u32 s10, s50, 0x40000
	v_lshl_add_u64 v[210:211], s[50:51], 0, v[194:195]
	s_addc_u32 s11, s51, 0
	s_add_i32 s77, s78, s14
	global_load_lds_dwordx4 v[210:211], off
	v_lshl_add_u64 v[212:213], s[10:11], 0, v[198:199]
	s_mov_b32 m0, s77
	v_lshl_add_u64 v[214:215], s[52:53], 0, v[196:197]
	global_load_lds_dwordx4 v[212:213], off
	v_lshl_add_u64 v[212:213], s[10:11], 0, v[194:195]
	s_add_i32 m0, s77, 0x2000
	s_nop 0
	global_load_lds_dwordx4 v[212:213], off
	v_lshl_add_u64 v[212:213], s[52:53], 0, v[200:201]
	s_mov_b32 m0, s55
	s_nop 0
	global_load_lds_dwordx4 v[212:213], off
	s_mov_b32 m0, s58
	s_nop 0
	global_load_lds_dwordx4 v[214:215], off
	s_waitcnt vmcnt(8)
	s_waitcnt lgkmcnt(0)
	s_barrier
; #define PG8_STAGE(bufoff, gbase, voff) do { _Pragma("unroll") for (int _i = 0; _i < 2; ++_i) \
;         __builtin_amdgcn_global_load_lds((const unsigned*)((const char*)(gbase) + (voff)[_i]), (PG8_LAS unsigned*)(lds + (bufoff) + ldsw + _i * 8192), 16, 0, 0); } while (0)
; #define PG8_LDA(dst, b, h) do { _Pragma("unroll") for (int m = 0; m < 4; ++m) _Pragma("unroll") for (int k = 0; k < 2; ++k) dst[m][k] = *(const PG8_LAS bf16x8*)(lds + PG8_SA(b, h) + aoff + m * 2048 + k * 1024); } while (0)
; #define PG8_LDB(dst, b, h) do { _Pragma("unroll") for (int n = 0; n < 2; ++n) _Pragma("unroll") for (int k = 0; k < 2; ++k) dst[n][k] = *(const PG8_LAS bf16x8*)(lds + PG8_SB(b, h) + boff + n * 2048 + k * 1024); } while (0)
; #define PG8_MMA(ai, bj, At, Bt) do { __builtin_amdgcn_s_setprio(1); _Pragma("unroll") for (int m = 0; m < 4; ++m) _Pragma("unroll") for (int n = 0; n < 2; ++n) _Pragma("unroll") for (int k = 0; k < 2; ++k) \
;         acc[ai][bj][m][n] = __builtin_amdgcn_mfma_f32_16x16x32_bf16(Bt[n][k], At[m][k], acc[ai][bj][m][n], 0, 0, 0); __builtin_amdgcn_s_setprio(0); } while (0)
; #define PG8_WAIT_V(n) asm volatile("s_waitcnt vmcnt(" #n ")" ::: "memory")
; #define PG8_WAIT_L(n) asm volatile("s_waitcnt lgkmcnt(" #n ")" ::: "memory")
; #define PG8_BAR __builtin_amdgcn_s_barrier()
; #define PG8_SCHED __builtin_amdgcn_sched_barrier(0)
; template <class Epi, class Sched, bool ALIGN_EPI = false, bool SP2 = false>
; __device__ __forceinline__ void gemm_phase(PG8_LAS unsigned char* lds, const Gemm g, const Sched& S, const Epi& E) {
;     ...
;             PG8_WAIT_V(8); PG8_WAIT_L(0); PG8_BAR; PG8_MMA(1, 0, At, B0); PG8_MMA(1, 1, At, B1); PG8_BAR; PG8_SCHED;
;             PG8_LDB(B0, 1, 0); PG8_LDB(B1, 1, 1); PG8_SCHED; PG8_LDA(At, 1, 0); PG8_STAGE(PG8_SA(0, 1), a2 + hstep, voffA);
;             PG8_WAIT_V(8); PG8_WAIT_L(0); PG8_BAR; PG8_MMA(0, 0, At, B0); PG8_MMA(0, 1, At, B1); PG8_BAR; PG8_SCHED;
	s_setprio 1
	s_waitcnt lgkmcnt(0)
	v_mfma_f32_16x16x32_bf16 v[60:63], v[128:131], v[160:163], v[60:63]
	v_mfma_f32_16x16x32_bf16 v[56:59], v[136:139], v[160:163], v[56:59]
	v_mfma_f32_16x16x32_bf16 v[52:55], v[128:131], v[168:171], v[52:55]
	v_mfma_f32_16x16x32_bf16 v[48:51], v[136:139], v[168:171], v[48:51]
	v_mfma_f32_16x16x32_bf16 v[44:47], v[128:131], v[176:179], v[44:47]
	v_mfma_f32_16x16x32_bf16 v[40:43], v[136:139], v[176:179], v[40:43]
	v_mfma_f32_16x16x32_bf16 v[36:39], v[128:131], v[184:187], v[36:39]
	v_mfma_f32_16x16x32_bf16 v[32:35], v[136:139], v[184:187], v[32:35]
	v_mfma_f32_16x16x32_bf16 v[60:63], v[132:135], v[164:167], v[60:63]
	v_mfma_f32_16x16x32_bf16 v[56:59], v[140:143], v[164:167], v[56:59]
	v_mfma_f32_16x16x32_bf16 v[52:55], v[132:135], v[172:175], v[52:55]
	v_mfma_f32_16x16x32_bf16 v[48:51], v[140:143], v[172:175], v[48:51]
	v_mfma_f32_16x16x32_bf16 v[44:47], v[132:135], v[180:183], v[44:47]
	v_mfma_f32_16x16x32_bf16 v[40:43], v[140:143], v[180:183], v[40:43]
	v_mfma_f32_16x16x32_bf16 v[36:39], v[132:135], v[188:191], v[36:39]
	v_mfma_f32_16x16x32_bf16 v[32:35], v[140:143], v[188:191], v[32:35]
	s_setprio 0
	s_setprio 1
	v_mfma_f32_16x16x32_bf16 v[28:31], v[144:147], v[160:163], v[28:31]
	v_mfma_f32_16x16x32_bf16 v[24:27], v[152:155], v[160:163], v[24:27]
	v_mfma_f32_16x16x32_bf16 v[20:23], v[144:147], v[168:171], v[20:23]
	v_mfma_f32_16x16x32_bf16 v[16:19], v[152:155], v[168:171], v[16:19]
	v_mfma_f32_16x16x32_bf16 v[12:15], v[144:147], v[176:179], v[12:15]
	v_mfma_f32_16x16x32_bf16 v[8:11], v[152:155], v[176:179], v[8:11]
	v_mfma_f32_16x16x32_bf16 v[4:7], v[144:147], v[184:187], v[4:7]
	v_mfma_f32_16x16x32_bf16 v[0:3], v[152:155], v[184:187], v[0:3]
	v_mfma_f32_16x16x32_bf16 v[28:31], v[148:151], v[164:167], v[28:31]
	v_mfma_f32_16x16x32_bf16 v[24:27], v[156:159], v[164:167], v[24:27]
	v_mfma_f32_16x16x32_bf16 v[20:23], v[148:151], v[172:175], v[20:23]
	v_mfma_f32_16x16x32_bf16 v[16:19], v[156:159], v[172:175], v[16:19]
	v_mfma_f32_16x16x32_bf16 v[12:15], v[148:151], v[180:183], v[12:15]
	v_mfma_f32_16x16x32_bf16 v[8:11], v[156:159], v[180:183], v[8:11]
	v_mfma_f32_16x16x32_bf16 v[4:7], v[148:151], v[188:191], v[4:7]
	v_mfma_f32_16x16x32_bf16 v[0:3], v[156:159], v[188:191], v[0:3]
	s_setprio 0
	s_barrier
	s_add_i32 s77, 0, 0x18000
	s_add_i32 s78, 0, 0x1c000
	v_add_u32_e32 v140, s77, v246
	v_add_u32_e32 v156, s77, v246
	v_add_u32_e32 v156, 0x1000, v156
	ds_read_b128 v[128:131], v140
	ds_read_b128 v[132:135], v140 offset:1024
	ds_read_b128 v[136:139], v140 offset:2048
	ds_read_b128 v[140:143], v140 offset:3072
	ds_read_b128 v[144:147], v156
	ds_read_b128 v[148:151], v156 offset:1024
	ds_read_b128 v[152:155], v156 offset:2048
	ds_read_b128 v[156:159], v156 offset:3072
	s_add_u32 s10, s52, 0x40000
	s_addc_u32 s11, s53, 0
	s_mov_b32 m0, s59
	v_lshl_add_u64 v[216:217], s[10:11], 0, v[200:201]
	ds_read_b128 v[160:163], v249 offset:32768
	ds_read_b128 v[164:167], v249 offset:33792
	ds_read_b128 v[168:171], v249 offset:34816
	ds_read_b128 v[172:175], v249 offset:35840
	ds_read_b128 v[176:179], v249 offset:36864
	ds_read_b128 v[180:183], v249 offset:37888
	ds_read_b128 v[184:187], v249 offset:38912
	ds_read_b128 v[188:191], v249 offset:39936
	global_load_lds_dwordx4 v[216:217], off
	v_lshl_add_u64 v[216:217], s[10:11], 0, v[196:197]
	s_mov_b32 m0, s60
	s_nop 0
	global_load_lds_dwordx4 v[216:217], off
	s_waitcnt vmcnt(8)
	s_waitcnt lgkmcnt(0)
	s_barrier
	s_setprio 1
	s_waitcnt lgkmcnt(0)
	v_mfma_f32_16x16x32_bf16 v[124:127], v[128:131], v[160:163], v[124:127]
	v_mfma_f32_16x16x32_bf16 v[120:123], v[136:139], v[160:163], v[120:123]
	v_mfma_f32_16x16x32_bf16 v[116:119], v[128:131], v[168:171], v[116:119]
	v_mfma_f32_16x16x32_bf16 v[112:115], v[136:139], v[168:171], v[112:115]
	v_mfma_f32_16x16x32_bf16 v[108:111], v[128:131], v[176:179], v[108:111]
	v_mfma_f32_16x16x32_bf16 v[104:107], v[136:139], v[176:179], v[104:107]
	v_mfma_f32_16x16x32_bf16 v[100:103], v[128:131], v[184:187], v[100:103]
	v_mfma_f32_16x16x32_bf16 v[96:99], v[136:139], v[184:187], v[96:99]
	v_mfma_f32_16x16x32_bf16 v[124:127], v[132:135], v[164:167], v[124:127]
	v_mfma_f32_16x16x32_bf16 v[120:123], v[140:143], v[164:167], v[120:123]
	v_mfma_f32_16x16x32_bf16 v[116:119], v[132:135], v[172:175], v[116:119]
	v_mfma_f32_16x16x32_bf16 v[112:115], v[140:143], v[172:175], v[112:115]
	v_mfma_f32_16x16x32_bf16 v[108:111], v[132:135], v[180:183], v[108:111]
	v_mfma_f32_16x16x32_bf16 v[104:107], v[140:143], v[180:183], v[104:107]
	v_mfma_f32_16x16x32_bf16 v[100:103], v[132:135], v[188:191], v[100:103]
	v_mfma_f32_16x16x32_bf16 v[96:99], v[140:143], v[188:191], v[96:99]
	s_setprio 0
	s_setprio 1
	v_mfma_f32_16x16x32_bf16 v[92:95], v[144:147], v[160:163], v[92:95]
	v_mfma_f32_16x16x32_bf16 v[88:91], v[152:155], v[160:163], v[88:91]
	v_mfma_f32_16x16x32_bf16 v[84:87], v[144:147], v[168:171], v[84:87]
	v_mfma_f32_16x16x32_bf16 v[80:83], v[152:155], v[168:171], v[80:83]
	v_mfma_f32_16x16x32_bf16 v[76:79], v[144:147], v[176:179], v[76:79]
	v_mfma_f32_16x16x32_bf16 v[72:75], v[152:155], v[176:179], v[72:75]
	v_mfma_f32_16x16x32_bf16 v[68:71], v[144:147], v[184:187], v[68:71]
	v_mfma_f32_16x16x32_bf16 v[64:67], v[152:155], v[184:187], v[64:67]
	v_mfma_f32_16x16x32_bf16 v[92:95], v[148:151], v[164:167], v[92:95]
	v_mfma_f32_16x16x32_bf16 v[88:91], v[156:159], v[164:167], v[88:91]
	v_mfma_f32_16x16x32_bf16 v[84:87], v[148:151], v[172:175], v[84:87]
	v_mfma_f32_16x16x32_bf16 v[80:83], v[156:159], v[172:175], v[80:83]
	v_mfma_f32_16x16x32_bf16 v[76:79], v[148:151], v[180:183], v[76:79]
	v_mfma_f32_16x16x32_bf16 v[72:75], v[156:159], v[180:183], v[72:75]
	v_mfma_f32_16x16x32_bf16 v[68:71], v[148:151], v[188:191], v[68:71]
	v_mfma_f32_16x16x32_bf16 v[64:67], v[156:159], v[188:191], v[64:67]
	s_setprio 0
	s_barrier
; #define PG8_WAIT_V(n) asm volatile("s_waitcnt vmcnt(" #n ")" ::: "memory")
; template <class Epi, class Sched, bool ALIGN_EPI = false, bool SP2 = false>
; __device__ __forceinline__ void gemm_phase(PG8_LAS unsigned char* lds, const Gemm g, const Sched& S, const Epi& E) {
;     ...
;             PG8_LDA(At, 1, 1); PG8_STAGE(PG8_SB(1, 0), b3, voffB); PG8_STAGE(PG8_SB(1, 1), b3 + hstep, voffB); PG8_STAGE(PG8_SA(1, 0), a3, voffA);
;             PG8_WAIT_V(8); PG8_WAIT_L(0); PG8_BAR; PG8_MMA(1, 0, At, B0); PG8_MMA(1, 1, At, B1); PG8_BAR; PG8_SCHED;
;     __device__ __forceinline__ void operator()(const f32x4 (&acc)[2][2][4][2], const Unit& u, int wr, int wc, int fr, int fq) const {
;         const int br = u.kind / 3, part = u.kind % 3;
;         unsigned voff = (unsigned)((wr * 4 + wc) * 64 + fq * 16 + fr) * 16u; asm volatile("" : "+v"(voff));
;         unsigned char* const tmpb = ws + WS_SLAB + (size_t)(tslot >> 5) * SLAB + SL_TMP + (size_t)(tslot & 31) * 131072;
;         const int row0 = u.pm * BM + wr * 64 + fr, col0 = u.pn * BM + 32 * wc + 8 * fq;
;         if (part == 1) {
;             float rx[2][4];
; #pragma unroll
;             for (int ai = 0; ai < 2; ++ai)
; #pragma unroll
;                 for (int m = 0; m < 4; ++m) rx[ai][m] = row_rstd(ssp, row0 + ai * HALF + m * 16, fq);
; #pragma unroll
;             for (int bj = 0; bj < 2; ++bj) {
;                 const f32x4 bv0 = *(const f32x4*)(gb + br * 1024 + col0 + 128 * bj), bv1 = *(const f32x4*)(gb + br * 1024 + col0 + 128 * bj + 4);
; #pragma unroll
;                 for (int ai = 0; ai < 2; ++ai)
; #pragma unroll
;                     for (int m = 0; m < 4; ++m) {
;                         const f32x4 a0 = acc[ai][bj][m][0] * rx[ai][m] + bv0, a1 = acc[ai][bj][m][1] * rx[ai][m] + bv1; f32x4 o0, o1;
; #pragma unroll
;                         for (int e = 0; e < 4; ++e) { o0[e] = sigm(a0[e]); o1[e] = sigm(a1[e]); }
;                         *(u32x4*)(tmpb + ((ai * 4 + m) * 2 + bj) * 8192 + voff) = pack8(o0, o1); }
;                 asm volatile("" ::: "memory"); }
;         } else {
;             bf16_t* const MRG = (bf16_t*)(ws + WS_SLAB + (size_t)(u.pm >> 4) * SLAB + SL_MRG); const int lrow0 = row0 & (SEQ - 1);
; #pragma unroll
;             for (int ai = 0; ai < 2; ++ai) {
;                 u32x4 gw[4][2], pw[4][2];
; #pragma unroll
;                 for (int m = 0; m < 4; ++m)
; #pragma unroll
	s_add_i32 s10, s77, s14
	v_lshl_add_u64 v[208:209], v[208:209], 0, s[36:37]
	s_mov_b32 m0, s10
	ds_read_b128 v[160:163], v249 offset:49152
	ds_read_b128 v[164:167], v249 offset:50176
	ds_read_b128 v[168:171], v249 offset:51200
	ds_read_b128 v[172:175], v249 offset:52224
	ds_read_b128 v[176:179], v249 offset:53248
	ds_read_b128 v[180:183], v249 offset:54272
	ds_read_b128 v[184:187], v249 offset:55296
	ds_read_b128 v[188:191], v249 offset:56320
	global_load_lds_dwordx4 v[208:209], off
	s_add_i32 m0, s10, 0x2000
	s_add_u32 s10, s50, 0x40080
	v_lshl_add_u64 v[208:209], v[210:211], 0, s[36:37]
	s_addc_u32 s11, s51, 0
	s_add_i32 s50, s78, s14
	global_load_lds_dwordx4 v[208:209], off
	v_lshl_add_u64 v[208:209], s[10:11], 0, v[198:199]
	s_mov_b32 m0, s50
	s_nop 0
	global_load_lds_dwordx4 v[208:209], off
	v_lshl_add_u64 v[208:209], s[10:11], 0, v[194:195]
	s_add_i32 m0, s50, 0x2000
	s_nop 0
	global_load_lds_dwordx4 v[208:209], off
	v_lshl_add_u64 v[208:209], v[212:213], 0, s[36:37]
	s_mov_b32 m0, s65
	s_nop 0
	global_load_lds_dwordx4 v[208:209], off
	v_lshl_add_u64 v[208:209], v[214:215], 0, s[36:37]
	s_mov_b32 m0, s66
	s_nop 0
	global_load_lds_dwordx4 v[208:209], off
	s_waitcnt vmcnt(8)
	s_waitcnt lgkmcnt(0)
	s_barrier
	s_setprio 1
	s_waitcnt lgkmcnt(0)
	v_mfma_f32_16x16x32_bf16 v[60:63], v[128:131], v[160:163], v[60:63]
	v_mfma_f32_16x16x32_bf16 v[56:59], v[136:139], v[160:163], v[56:59]
	v_mfma_f32_16x16x32_bf16 v[52:55], v[128:131], v[168:171], v[52:55]
	v_mfma_f32_16x16x32_bf16 v[48:51], v[136:139], v[168:171], v[48:51]
	v_mfma_f32_16x16x32_bf16 v[44:47], v[128:131], v[176:179], v[44:47]
	v_mfma_f32_16x16x32_bf16 v[40:43], v[136:139], v[176:179], v[40:43]
	v_mfma_f32_16x16x32_bf16 v[36:39], v[128:131], v[184:187], v[36:39]
	v_mfma_f32_16x16x32_bf16 v[32:35], v[136:139], v[184:187], v[32:35]
	v_mfma_f32_16x16x32_bf16 v[60:63], v[132:135], v[164:167], v[60:63]
	v_mfma_f32_16x16x32_bf16 v[56:59], v[140:143], v[164:167], v[56:59]
	v_mfma_f32_16x16x32_bf16 v[52:55], v[132:135], v[172:175], v[52:55]
	v_mfma_f32_16x16x32_bf16 v[48:51], v[140:143], v[172:175], v[48:51]
	v_mfma_f32_16x16x32_bf16 v[44:47], v[132:135], v[180:183], v[44:47]
	v_mfma_f32_16x16x32_bf16 v[40:43], v[140:143], v[180:183], v[40:43]
	v_mfma_f32_16x16x32_bf16 v[36:39], v[132:135], v[188:191], v[36:39]
	v_mfma_f32_16x16x32_bf16 v[32:35], v[140:143], v[188:191], v[32:35]
	s_setprio 0
	s_setprio 1
	v_mfma_f32_16x16x32_bf16 v[28:31], v[144:147], v[160:163], v[28:31]
	v_mfma_f32_16x16x32_bf16 v[24:27], v[152:155], v[160:163], v[24:27]
	v_mfma_f32_16x16x32_bf16 v[20:23], v[144:147], v[168:171], v[20:23]
	v_mfma_f32_16x16x32_bf16 v[16:19], v[152:155], v[168:171], v[16:19]
	v_mfma_f32_16x16x32_bf16 v[12:15], v[144:147], v[176:179], v[12:15]
	v_mfma_f32_16x16x32_bf16 v[8:11], v[152:155], v[176:179], v[8:11]
	v_mfma_f32_16x16x32_bf16 v[4:7], v[144:147], v[184:187], v[4:7]
	v_mfma_f32_16x16x32_bf16 v[0:3], v[152:155], v[184:187], v[0:3]
	v_mfma_f32_16x16x32_bf16 v[28:31], v[148:151], v[164:167], v[28:31]
	v_mfma_f32_16x16x32_bf16 v[24:27], v[156:159], v[164:167], v[24:27]
	v_mfma_f32_16x16x32_bf16 v[20:23], v[148:151], v[172:175], v[20:23]
	v_mfma_f32_16x16x32_bf16 v[16:19], v[156:159], v[172:175], v[16:19]
	v_mfma_f32_16x16x32_bf16 v[12:15], v[148:151], v[180:183], v[12:15]
	v_mfma_f32_16x16x32_bf16 v[8:11], v[156:159], v[180:183], v[8:11]
	v_mfma_f32_16x16x32_bf16 v[4:7], v[148:151], v[188:191], v[4:7]
	v_mfma_f32_16x16x32_bf16 v[0:3], v[156:159], v[188:191], v[0:3]
	s_setprio 0
	s_barrier
	s_add_i32 s76, s76, 2
	s_add_u32 s34, s34, 0x100
	s_addc_u32 s35, s35, 0
	s_add_u32 s19, s19, 0x100
	s_addc_u32 s75, s75, 0
	s_cmp_gt_u32 s76, 5
	s_cbranch_scc0 .LBB0_488
	s_and_b64 vcc, exec, s[24:25]
	s_cbranch_vccz .LBB0_491
	s_barrier
.LBB0_491:
	s_mul_i32 s10, s43, 0xab
	s_bfe_u32 s52, s10, 0x70009
	s_mul_i32 s10, s52, 3
	s_sub_i32 s10, s43, s10
	s_and_b32 s19, s10, 0xff
	s_cmp_lg_u32 s19, 0
	s_cselect_b64 s[34:35], -1, 0
	s_cmp_eq_u32 s19, 0
	s_cbranch_scc1 .LBB0_560
	v_mov_b32_e32 v192, v248
	v_lshl_add_u32 v210, s42, 8, v245
	v_lshl_or_b32 v208, s18, 8, v247
	s_cmp_lg_u32 s19, 1
	s_mov_b64 s[18:19], -1
	s_cbranch_scc0 .LBB0_558
	s_ashr_i32 s10, s42, 4
	s_mul_hi_i32 s11, s10, 0x1c00000
	s_mul_i32 s10, s10, 0x1c00000
	s_add_u32 s10, s71, s10
	s_addc_u32 s11, s72, s11
	v_lshlrev_b32_e32 v128, 1, v208
	v_mov_b32_e32 v129, v193
	v_lshlrev_b32_e32 v130, 11, v210
	s_cmp_gt_u32 s43, 2
	v_lshl_add_u64 v[128:129], s[10:11], 0, v[128:129]
	v_and_b32_e32 v130, 0x7e7800, v130
	v_mov_b32_e32 v131, v193
	s_cselect_b64 s[50:51], -1, 0
	v_lshl_add_u64 v[212:213], v[128:129], 0, v[130:131]
	v_lshl_add_u64 v[214:215], s[30:31], 0, v[192:193]
	v_and_b32_e32 v128, 8, v229
	v_mov_b32_e32 v129, 0xffffc040
	v_mov_b32_e32 v131, 0x4040
	v_cmp_ne_u32_e64 s[42:43], 0, v128
	s_nop 1
	v_cndmask_b32_e64 v232, 0, v129, s[42:43]
	v_cndmask_b32_e64 v234, v131, 0, s[42:43]
	v_ashrrev_i32_e32 v233, 31, v232
	v_mov_b32_e32 v235, v193
	v_lshl_add_u64 v[252:253], v[212:213], 0, v[234:235]
	v_lshl_add_u64 v[212:213], v[212:213], 0, v[232:233]
	s_and_b64 vcc, exec, s[50:51]
	s_cbranch_vccnz .Le2_rmw
; __device__ __forceinline__ u32x4 pack8(const f32x4& a, const f32x4& b) { u32x4 w; w.x = pk2(a[0], a[1]); w.y = pk2(a[2], a[3]); w.z = pk2(b[0], b[1]); w.w = pk2(b[2], b[3]); return w; }
; __device__ __forceinline__ void unpack8(const u32x4& w, f32x4& a, f32x4& b) { a[0] = bflo(w.x); a[1] = bfhi(w.x); a[2] = bflo(w.y); a[3] = bfhi(w.y); b[0] = bflo(w.z); b[1] = bfhi(w.z); b[2] = bflo(w.w); b[3] = bfhi(w.w); }
;     __device__ __forceinline__ void operator()(const f32x4 (&acc)[2][2][4][2], const Unit& u, int wr, int wc, int fr, int fq) const {
;     ...
;                     for (int bj = 0; bj < 2; ++bj) { gw[m][bj] = *(const u32x4*)(tmpb + ((ai * 4 + m) * 2 + bj) * 8192 + voff);
;                         if (br > 0) pw[m][bj] = *(const u32x4*)(MRG + (size_t)(lrow0 + ai * HALF + m * 16) * 1024 + col0 + 128 * bj); }
; #pragma unroll
;                 for (int m = 0; m < 4; ++m)
; #pragma unroll
;                     for (int bj = 0; bj < 2; ++bj) { f32x4 g0, g1; unpack8(gw[m][bj], g0, g1);
;                         f32x4 v0 = acc[ai][bj][m][0] * g0, v1 = acc[ai][bj][m][1] * g1;
;                         if (br > 0) { f32x4 p0, p1; unpack8(pw[m][bj], p0, p1); v0 += p0; v1 += p1; }
;                         *(u32x4*)(MRG + (size_t)(lrow0 + ai * HALF + m * 16) * 1024 + col0 + 128 * bj) = pack8(v0, v1); }
	global_load_dwordx4 v[128:131], v[214:215], off
	s_mov_b64 s[10:11], 0x2000
	v_lshl_add_u64 v[224:225], v[214:215], 0, s[10:11]
	global_load_dwordx4 v[132:135], v[224:225], off
	s_mov_b64 s[10:11], 0x4000
	v_lshl_add_u64 v[224:225], v[214:215], 0, s[10:11]
	global_load_dwordx4 v[136:139], v[224:225], off
	s_mov_b64 s[10:11], 0x6000
	v_lshl_add_u64 v[224:225], v[214:215], 0, s[10:11]
	global_load_dwordx4 v[140:143], v[224:225], off
	s_mov_b64 s[10:11], 0x8000
	v_lshl_add_u64 v[224:225], v[214:215], 0, s[10:11]
	global_load_dwordx4 v[144:147], v[224:225], off
	s_mov_b64 s[10:11], 0xa000
	v_lshl_add_u64 v[224:225], v[214:215], 0, s[10:11]
	global_load_dwordx4 v[148:151], v[224:225], off
	s_mov_b64 s[10:11], 0xc000
	v_lshl_add_u64 v[224:225], v[214:215], 0, s[10:11]
	global_load_dwordx4 v[152:155], v[224:225], off
	s_mov_b64 s[10:11], 0xe000
	v_lshl_add_u64 v[224:225], v[214:215], 0, s[10:11]
	global_load_dwordx4 v[156:159], v[224:225], off
	s_waitcnt vmcnt(7)
	v_lshlrev_b32_e32 v216, 16, v128
	v_and_b32_e32 v217, 0xffff0000, v128
	v_lshlrev_b32_e32 v218, 16, v129
	v_and_b32_e32 v219, 0xffff0000, v129
	v_lshlrev_b32_e32 v220, 16, v130
	v_and_b32_e32 v221, 0xffff0000, v130
	v_lshlrev_b32_e32 v222, 16, v131
	v_and_b32_e32 v223, 0xffff0000, v131
	v_pk_mul_f32 v[124:125], v[124:125], v[216:217]
	v_pk_mul_f32 v[126:127], v[126:127], v[218:219]
	v_pk_mul_f32 v[120:121], v[120:121], v[220:221]
	v_pk_mul_f32 v[122:123], v[122:123], v[222:223]
	v_cvt_pk_bf16_f32 v128, v124, v125
	v_cvt_pk_bf16_f32 v129, v126, v127
	v_cvt_pk_bf16_f32 v130, v120, v121
	v_cvt_pk_bf16_f32 v131, v122, v123
	s_waitcnt vmcnt(6)
	v_lshlrev_b32_e32 v216, 16, v132
	v_and_b32_e32 v217, 0xffff0000, v132
	v_lshlrev_b32_e32 v218, 16, v133
	v_and_b32_e32 v219, 0xffff0000, v133
	v_lshlrev_b32_e32 v220, 16, v134
	v_and_b32_e32 v221, 0xffff0000, v134
	v_lshlrev_b32_e32 v222, 16, v135
	v_and_b32_e32 v223, 0xffff0000, v135
	v_pk_mul_f32 v[92:93], v[92:93], v[216:217]
	v_pk_mul_f32 v[94:95], v[94:95], v[218:219]
	v_pk_mul_f32 v[88:89], v[88:89], v[220:221]
	v_pk_mul_f32 v[90:91], v[90:91], v[222:223]
	v_cvt_pk_bf16_f32 v132, v92, v93
	v_cvt_pk_bf16_f32 v133, v94, v95
	v_cvt_pk_bf16_f32 v134, v88, v89
	v_cvt_pk_bf16_f32 v135, v90, v91
	s_waitcnt vmcnt(5)
	v_lshlrev_b32_e32 v216, 16, v136
	v_and_b32_e32 v217, 0xffff0000, v136
	v_lshlrev_b32_e32 v218, 16, v137
	v_and_b32_e32 v219, 0xffff0000, v137
	v_lshlrev_b32_e32 v220, 16, v138
	v_and_b32_e32 v221, 0xffff0000, v138
	v_lshlrev_b32_e32 v222, 16, v139
	v_and_b32_e32 v223, 0xffff0000, v139
	v_pk_mul_f32 v[116:117], v[116:117], v[216:217]
	v_pk_mul_f32 v[118:119], v[118:119], v[218:219]
	v_pk_mul_f32 v[112:113], v[112:113], v[220:221]
	v_pk_mul_f32 v[114:115], v[114:115], v[222:223]
	v_cvt_pk_bf16_f32 v136, v116, v117
	v_cvt_pk_bf16_f32 v137, v118, v119
	v_cvt_pk_bf16_f32 v138, v112, v113
	v_cvt_pk_bf16_f32 v139, v114, v115
	s_waitcnt vmcnt(4)
	v_lshlrev_b32_e32 v216, 16, v140
	v_and_b32_e32 v217, 0xffff0000, v140
	v_lshlrev_b32_e32 v218, 16, v141
	v_and_b32_e32 v219, 0xffff0000, v141
	v_lshlrev_b32_e32 v220, 16, v142
	v_and_b32_e32 v221, 0xffff0000, v142
	v_lshlrev_b32_e32 v222, 16, v143
	v_and_b32_e32 v223, 0xffff0000, v143
	v_pk_mul_f32 v[84:85], v[84:85], v[216:217]
	v_pk_mul_f32 v[86:87], v[86:87], v[218:219]
	v_pk_mul_f32 v[80:81], v[80:81], v[220:221]
	v_pk_mul_f32 v[82:83], v[82:83], v[222:223]
	v_cvt_pk_bf16_f32 v140, v84, v85
	v_cvt_pk_bf16_f32 v141, v86, v87
	v_cvt_pk_bf16_f32 v142, v80, v81
	v_cvt_pk_bf16_f32 v143, v82, v83
	s_mov_b64 s[10:11], 0x10000
	v_lshl_add_u64 v[224:225], v[214:215], 0, s[10:11]
	global_load_dwordx4 v[124:127], v[224:225], off
	s_mov_b64 s[10:11], 0x12000
	v_lshl_add_u64 v[224:225], v[214:215], 0, s[10:11]
	global_load_dwordx4 v[92:95], v[224:225], off
	s_mov_b64 s[10:11], 0x14000
	v_lshl_add_u64 v[224:225], v[214:215], 0, s[10:11]
	global_load_dwordx4 v[116:119], v[224:225], off
	s_mov_b64 s[10:11], 0x16000
	v_lshl_add_u64 v[224:225], v[214:215], 0, s[10:11]
	global_load_dwordx4 v[84:87], v[224:225], off
	v_mov_b32_dpp v232, v132 row_ror:8 row_mask:0xf bank_mask:0xf
	v_mov_b32_dpp v233, v133 row_ror:8 row_mask:0xf bank_mask:0xf
	v_mov_b32_dpp v234, v134 row_ror:8 row_mask:0xf bank_mask:0xf
	v_mov_b32_dpp v235, v135 row_ror:8 row_mask:0xf bank_mask:0xf
	v_cndmask_b32_e64 v132, v128, v232, s[42:43]
	v_cndmask_b32_e64 v133, v129, v233, s[42:43]
	v_cndmask_b32_e64 v134, v130, v234, s[42:43]
	v_cndmask_b32_e64 v135, v131, v235, s[42:43]
	v_cndmask_b32_e64 v232, v232, v128, s[42:43]
	v_cndmask_b32_e64 v233, v233, v129, s[42:43]
	v_cndmask_b32_e64 v234, v234, v130, s[42:43]
	v_cndmask_b32_e64 v235, v235, v131, s[42:43]
	global_store_dwordx4 v[212:213], v[132:135], off
	global_store_dwordx4 v[252:253], v[232:235], off
	s_mov_b64 s[10:11], 0x8000
	v_lshl_add_u64 v[224:225], v[212:213], 0, s[10:11]
	s_mov_b64 s[10:11], 0x8000
	v_lshl_add_u64 v[250:251], v[252:253], 0, s[10:11]
	v_mov_b32_dpp v232, v140 row_ror:8 row_mask:0xf bank_mask:0xf
	v_mov_b32_dpp v233, v141 row_ror:8 row_mask:0xf bank_mask:0xf
	v_mov_b32_dpp v234, v142 row_ror:8 row_mask:0xf bank_mask:0xf
	v_mov_b32_dpp v235, v143 row_ror:8 row_mask:0xf bank_mask:0xf
	v_cndmask_b32_e64 v140, v136, v232, s[42:43]
	v_cndmask_b32_e64 v141, v137, v233, s[42:43]
	v_cndmask_b32_e64 v142, v138, v234, s[42:43]
	v_cndmask_b32_e64 v143, v139, v235, s[42:43]
	v_cndmask_b32_e64 v232, v232, v136, s[42:43]
	v_cndmask_b32_e64 v233, v233, v137, s[42:43]
	v_cndmask_b32_e64 v234, v234, v138, s[42:43]
	v_cndmask_b32_e64 v235, v235, v139, s[42:43]
	global_store_dwordx4 v[224:225], v[140:143], off
	global_store_dwordx4 v[250:251], v[232:235], off
	s_nop 1
	s_waitcnt vmcnt(11)
; __device__ __forceinline__ u32x4 pack8(const f32x4& a, const f32x4& b) { u32x4 w; w.x = pk2(a[0], a[1]); w.y = pk2(a[2], a[3]); w.z = pk2(b[0], b[1]); w.w = pk2(b[2], b[3]); return w; }
; __device__ __forceinline__ void unpack8(const u32x4& w, f32x4& a, f32x4& b) { a[0] = bflo(w.x); a[1] = bfhi(w.x); a[2] = bflo(w.y); a[3] = bfhi(w.y); b[0] = bflo(w.z); b[1] = bfhi(w.z); b[2] = bflo(w.w); b[3] = bfhi(w.w); }
;     __device__ __forceinline__ void operator()(const f32x4 (&acc)[2][2][4][2], const Unit& u, int wr, int wc, int fr, int fq) const {
;     ...
;                     for (int bj = 0; bj < 2; ++bj) { gw[m][bj] = *(const u32x4*)(tmpb + ((ai * 4 + m) * 2 + bj) * 8192 + voff);
;                         if (br > 0) pw[m][bj] = *(const u32x4*)(MRG + (size_t)(lrow0 + ai * HALF + m * 16) * 1024 + col0 + 128 * bj); }
; #pragma unroll
;                 for (int m = 0; m < 4; ++m)
; #pragma unroll
;                     for (int bj = 0; bj < 2; ++bj) { f32x4 g0, g1; unpack8(gw[m][bj], g0, g1);
;                         f32x4 v0 = acc[ai][bj][m][0] * g0, v1 = acc[ai][bj][m][1] * g1;
;                         if (br > 0) { f32x4 p0, p1; unpack8(pw[m][bj], p0, p1); v0 += p0; v1 += p1; }
;                         *(u32x4*)(MRG + (size_t)(lrow0 + ai * HALF + m * 16) * 1024 + col0 + 128 * bj) = pack8(v0, v1); }
	v_lshlrev_b32_e32 v216, 16, v144
	v_and_b32_e32 v217, 0xffff0000, v144
	v_lshlrev_b32_e32 v218, 16, v145
	v_and_b32_e32 v219, 0xffff0000, v145
	v_lshlrev_b32_e32 v220, 16, v146
	v_and_b32_e32 v221, 0xffff0000, v146
	v_lshlrev_b32_e32 v222, 16, v147
	v_and_b32_e32 v223, 0xffff0000, v147
	v_pk_mul_f32 v[108:109], v[108:109], v[216:217]
	v_pk_mul_f32 v[110:111], v[110:111], v[218:219]
	v_pk_mul_f32 v[104:105], v[104:105], v[220:221]
	v_pk_mul_f32 v[106:107], v[106:107], v[222:223]
	v_cvt_pk_bf16_f32 v144, v108, v109
	v_cvt_pk_bf16_f32 v145, v110, v111
	v_cvt_pk_bf16_f32 v146, v104, v105
	v_cvt_pk_bf16_f32 v147, v106, v107
	s_waitcnt vmcnt(10)
	v_lshlrev_b32_e32 v216, 16, v148
	v_and_b32_e32 v217, 0xffff0000, v148
	v_lshlrev_b32_e32 v218, 16, v149
	v_and_b32_e32 v219, 0xffff0000, v149
	v_lshlrev_b32_e32 v220, 16, v150
	v_and_b32_e32 v221, 0xffff0000, v150
	v_lshlrev_b32_e32 v222, 16, v151
	v_and_b32_e32 v223, 0xffff0000, v151
	v_pk_mul_f32 v[76:77], v[76:77], v[216:217]
	v_pk_mul_f32 v[78:79], v[78:79], v[218:219]
	v_pk_mul_f32 v[72:73], v[72:73], v[220:221]
	v_pk_mul_f32 v[74:75], v[74:75], v[222:223]
	v_cvt_pk_bf16_f32 v148, v76, v77
	v_cvt_pk_bf16_f32 v149, v78, v79
	v_cvt_pk_bf16_f32 v150, v72, v73
	v_cvt_pk_bf16_f32 v151, v74, v75
	s_waitcnt vmcnt(9)
	v_lshlrev_b32_e32 v216, 16, v152
	v_and_b32_e32 v217, 0xffff0000, v152
	v_lshlrev_b32_e32 v218, 16, v153
	v_and_b32_e32 v219, 0xffff0000, v153
	v_lshlrev_b32_e32 v220, 16, v154
	v_and_b32_e32 v221, 0xffff0000, v154
	v_lshlrev_b32_e32 v222, 16, v155
	v_and_b32_e32 v223, 0xffff0000, v155
	v_pk_mul_f32 v[100:101], v[100:101], v[216:217]
	v_pk_mul_f32 v[102:103], v[102:103], v[218:219]
	v_pk_mul_f32 v[96:97], v[96:97], v[220:221]
	v_pk_mul_f32 v[98:99], v[98:99], v[222:223]
	v_cvt_pk_bf16_f32 v152, v100, v101
	v_cvt_pk_bf16_f32 v153, v102, v103
	v_cvt_pk_bf16_f32 v154, v96, v97
	v_cvt_pk_bf16_f32 v155, v98, v99
	s_waitcnt vmcnt(8)
	v_lshlrev_b32_e32 v216, 16, v156
	v_and_b32_e32 v217, 0xffff0000, v156
	v_lshlrev_b32_e32 v218, 16, v157
	v_and_b32_e32 v219, 0xffff0000, v157
	v_lshlrev_b32_e32 v220, 16, v158
	v_and_b32_e32 v221, 0xffff0000, v158
	v_lshlrev_b32_e32 v222, 16, v159
	v_and_b32_e32 v223, 0xffff0000, v159
	v_pk_mul_f32 v[68:69], v[68:69], v[216:217]
	v_pk_mul_f32 v[70:71], v[70:71], v[218:219]
	v_pk_mul_f32 v[64:65], v[64:65], v[220:221]
	v_pk_mul_f32 v[66:67], v[66:67], v[222:223]
	v_cvt_pk_bf16_f32 v156, v68, v69
	v_cvt_pk_bf16_f32 v157, v70, v71
	v_cvt_pk_bf16_f32 v158, v64, v65
	v_cvt_pk_bf16_f32 v159, v66, v67
	s_mov_b64 s[10:11], 0x18000
	v_lshl_add_u64 v[224:225], v[214:215], 0, s[10:11]
	global_load_dwordx4 v[108:111], v[224:225], off
	s_mov_b64 s[10:11], 0x1a000
	v_lshl_add_u64 v[224:225], v[214:215], 0, s[10:11]
	global_load_dwordx4 v[76:79], v[224:225], off
	s_mov_b64 s[10:11], 0x1c000
	v_lshl_add_u64 v[224:225], v[214:215], 0, s[10:11]
	global_load_dwordx4 v[100:103], v[224:225], off
	s_mov_b64 s[10:11], 0x1e000
	v_lshl_add_u64 v[224:225], v[214:215], 0, s[10:11]
	global_load_dwordx4 v[68:71], v[224:225], off
	s_mov_b64 s[10:11], 0x10000
	v_lshl_add_u64 v[224:225], v[212:213], 0, s[10:11]
	s_mov_b64 s[10:11], 0x10000
	v_lshl_add_u64 v[250:251], v[252:253], 0, s[10:11]
	v_mov_b32_dpp v232, v148 row_ror:8 row_mask:0xf bank_mask:0xf
	v_mov_b32_dpp v233, v149 row_ror:8 row_mask:0xf bank_mask:0xf
	v_mov_b32_dpp v234, v150 row_ror:8 row_mask:0xf bank_mask:0xf
	v_mov_b32_dpp v235, v151 row_ror:8 row_mask:0xf bank_mask:0xf
	v_cndmask_b32_e64 v148, v144, v232, s[42:43]
	v_cndmask_b32_e64 v149, v145, v233, s[42:43]
	v_cndmask_b32_e64 v150, v146, v234, s[42:43]
	v_cndmask_b32_e64 v151, v147, v235, s[42:43]
	v_cndmask_b32_e64 v232, v232, v144, s[42:43]
	v_cndmask_b32_e64 v233, v233, v145, s[42:43]
	v_cndmask_b32_e64 v234, v234, v146, s[42:43]
	v_cndmask_b32_e64 v235, v235, v147, s[42:43]
	global_store_dwordx4 v[224:225], v[148:151], off
	global_store_dwordx4 v[250:251], v[232:235], off
	s_mov_b64 s[10:11], 0x18000
	v_lshl_add_u64 v[224:225], v[212:213], 0, s[10:11]
	s_mov_b64 s[10:11], 0x18000
	v_lshl_add_u64 v[250:251], v[252:253], 0, s[10:11]
	v_mov_b32_dpp v232, v156 row_ror:8 row_mask:0xf bank_mask:0xf
	v_mov_b32_dpp v233, v157 row_ror:8 row_mask:0xf bank_mask:0xf
	v_mov_b32_dpp v234, v158 row_ror:8 row_mask:0xf bank_mask:0xf
	v_mov_b32_dpp v235, v159 row_ror:8 row_mask:0xf bank_mask:0xf
	v_cndmask_b32_e64 v156, v152, v232, s[42:43]
	v_cndmask_b32_e64 v157, v153, v233, s[42:43]
	v_cndmask_b32_e64 v158, v154, v234, s[42:43]
	v_cndmask_b32_e64 v159, v155, v235, s[42:43]
	v_cndmask_b32_e64 v232, v232, v152, s[42:43]
	v_cndmask_b32_e64 v233, v233, v153, s[42:43]
	v_cndmask_b32_e64 v234, v234, v154, s[42:43]
	v_cndmask_b32_e64 v235, v235, v155, s[42:43]
	global_store_dwordx4 v[224:225], v[156:159], off
	global_store_dwordx4 v[250:251], v[232:235], off
	s_nop 1
	s_waitcnt vmcnt(15)
	v_lshlrev_b32_e32 v216, 16, v124
	v_and_b32_e32 v217, 0xffff0000, v124
	v_lshlrev_b32_e32 v218, 16, v125
	v_and_b32_e32 v219, 0xffff0000, v125
	v_lshlrev_b32_e32 v220, 16, v126
	v_and_b32_e32 v221, 0xffff0000, v126
	v_lshlrev_b32_e32 v222, 16, v127
	v_and_b32_e32 v223, 0xffff0000, v127
	v_pk_mul_f32 v[60:61], v[60:61], v[216:217]
	v_pk_mul_f32 v[62:63], v[62:63], v[218:219]
	v_pk_mul_f32 v[56:57], v[56:57], v[220:221]
	v_pk_mul_f32 v[58:59], v[58:59], v[222:223]
	v_cvt_pk_bf16_f32 v124, v60, v61
	v_cvt_pk_bf16_f32 v125, v62, v63
	v_cvt_pk_bf16_f32 v126, v56, v57
	v_cvt_pk_bf16_f32 v127, v58, v59
	s_waitcnt vmcnt(14)
; __device__ __forceinline__ u32x4 pack8(const f32x4& a, const f32x4& b) { u32x4 w; w.x = pk2(a[0], a[1]); w.y = pk2(a[2], a[3]); w.z = pk2(b[0], b[1]); w.w = pk2(b[2], b[3]); return w; }
; __device__ __forceinline__ void unpack8(const u32x4& w, f32x4& a, f32x4& b) { a[0] = bflo(w.x); a[1] = bfhi(w.x); a[2] = bflo(w.y); a[3] = bfhi(w.y); b[0] = bflo(w.z); b[1] = bfhi(w.z); b[2] = bflo(w.w); b[3] = bfhi(w.w); }
;     __device__ __forceinline__ void operator()(const f32x4 (&acc)[2][2][4][2], const Unit& u, int wr, int wc, int fr, int fq) const {
;     ...
;                     for (int bj = 0; bj < 2; ++bj) { gw[m][bj] = *(const u32x4*)(tmpb + ((ai * 4 + m) * 2 + bj) * 8192 + voff);
;                         if (br > 0) pw[m][bj] = *(const u32x4*)(MRG + (size_t)(lrow0 + ai * HALF + m * 16) * 1024 + col0 + 128 * bj); }
; #pragma unroll
;                 for (int m = 0; m < 4; ++m)
; #pragma unroll
;                     for (int bj = 0; bj < 2; ++bj) { f32x4 g0, g1; unpack8(gw[m][bj], g0, g1);
;                         f32x4 v0 = acc[ai][bj][m][0] * g0, v1 = acc[ai][bj][m][1] * g1;
;                         if (br > 0) { f32x4 p0, p1; unpack8(pw[m][bj], p0, p1); v0 += p0; v1 += p1; }
;                         *(u32x4*)(MRG + (size_t)(lrow0 + ai * HALF + m * 16) * 1024 + col0 + 128 * bj) = pack8(v0, v1); }
	v_lshlrev_b32_e32 v216, 16, v92
	v_and_b32_e32 v217, 0xffff0000, v92
	v_lshlrev_b32_e32 v218, 16, v93
	v_and_b32_e32 v219, 0xffff0000, v93
	v_lshlrev_b32_e32 v220, 16, v94
	v_and_b32_e32 v221, 0xffff0000, v94
	v_lshlrev_b32_e32 v222, 16, v95
	v_and_b32_e32 v223, 0xffff0000, v95
	v_pk_mul_f32 v[28:29], v[28:29], v[216:217]
	v_pk_mul_f32 v[30:31], v[30:31], v[218:219]
	v_pk_mul_f32 v[24:25], v[24:25], v[220:221]
	v_pk_mul_f32 v[26:27], v[26:27], v[222:223]
	v_cvt_pk_bf16_f32 v92, v28, v29
	v_cvt_pk_bf16_f32 v93, v30, v31
	v_cvt_pk_bf16_f32 v94, v24, v25
	v_cvt_pk_bf16_f32 v95, v26, v27
	s_waitcnt vmcnt(13)
	v_lshlrev_b32_e32 v216, 16, v116
	v_and_b32_e32 v217, 0xffff0000, v116
	v_lshlrev_b32_e32 v218, 16, v117
	v_and_b32_e32 v219, 0xffff0000, v117
	v_lshlrev_b32_e32 v220, 16, v118
	v_and_b32_e32 v221, 0xffff0000, v118
	v_lshlrev_b32_e32 v222, 16, v119
	v_and_b32_e32 v223, 0xffff0000, v119
	v_pk_mul_f32 v[52:53], v[52:53], v[216:217]
	v_pk_mul_f32 v[54:55], v[54:55], v[218:219]
	v_pk_mul_f32 v[48:49], v[48:49], v[220:221]
	v_pk_mul_f32 v[50:51], v[50:51], v[222:223]
	v_cvt_pk_bf16_f32 v116, v52, v53
	v_cvt_pk_bf16_f32 v117, v54, v55
	v_cvt_pk_bf16_f32 v118, v48, v49
	v_cvt_pk_bf16_f32 v119, v50, v51
	s_waitcnt vmcnt(12)
	v_lshlrev_b32_e32 v216, 16, v84
	v_and_b32_e32 v217, 0xffff0000, v84
	v_lshlrev_b32_e32 v218, 16, v85
	v_and_b32_e32 v219, 0xffff0000, v85
	v_lshlrev_b32_e32 v220, 16, v86
	v_and_b32_e32 v221, 0xffff0000, v86
	v_lshlrev_b32_e32 v222, 16, v87
	v_and_b32_e32 v223, 0xffff0000, v87
	v_pk_mul_f32 v[20:21], v[20:21], v[216:217]
	v_pk_mul_f32 v[22:23], v[22:23], v[218:219]
	v_pk_mul_f32 v[16:17], v[16:17], v[220:221]
	v_pk_mul_f32 v[18:19], v[18:19], v[222:223]
	v_cvt_pk_bf16_f32 v84, v20, v21
	v_cvt_pk_bf16_f32 v85, v22, v23
	v_cvt_pk_bf16_f32 v86, v16, v17
	v_cvt_pk_bf16_f32 v87, v18, v19
	s_mov_b64 s[10:11], 0x40000
	v_lshl_add_u64 v[224:225], v[212:213], 0, s[10:11]
	s_mov_b64 s[10:11], 0x40000
	v_lshl_add_u64 v[250:251], v[252:253], 0, s[10:11]
	v_mov_b32_dpp v232, v92 row_ror:8 row_mask:0xf bank_mask:0xf
	v_mov_b32_dpp v233, v93 row_ror:8 row_mask:0xf bank_mask:0xf
	v_mov_b32_dpp v234, v94 row_ror:8 row_mask:0xf bank_mask:0xf
	v_mov_b32_dpp v235, v95 row_ror:8 row_mask:0xf bank_mask:0xf
	v_cndmask_b32_e64 v92, v124, v232, s[42:43]
	v_cndmask_b32_e64 v93, v125, v233, s[42:43]
	v_cndmask_b32_e64 v94, v126, v234, s[42:43]
	v_cndmask_b32_e64 v95, v127, v235, s[42:43]
	v_cndmask_b32_e64 v232, v232, v124, s[42:43]
	v_cndmask_b32_e64 v233, v233, v125, s[42:43]
	v_cndmask_b32_e64 v234, v234, v126, s[42:43]
	v_cndmask_b32_e64 v235, v235, v127, s[42:43]
	global_store_dwordx4 v[224:225], v[92:95], off
	global_store_dwordx4 v[250:251], v[232:235], off
	s_mov_b64 s[10:11], 0x48000
	v_lshl_add_u64 v[224:225], v[212:213], 0, s[10:11]
	s_mov_b64 s[10:11], 0x48000
	v_lshl_add_u64 v[250:251], v[252:253], 0, s[10:11]
	v_mov_b32_dpp v232, v84 row_ror:8 row_mask:0xf bank_mask:0xf
	v_mov_b32_dpp v233, v85 row_ror:8 row_mask:0xf bank_mask:0xf
	v_mov_b32_dpp v234, v86 row_ror:8 row_mask:0xf bank_mask:0xf
	v_mov_b32_dpp v235, v87 row_ror:8 row_mask:0xf bank_mask:0xf
	v_cndmask_b32_e64 v84, v116, v232, s[42:43]
	v_cndmask_b32_e64 v85, v117, v233, s[42:43]
	v_cndmask_b32_e64 v86, v118, v234, s[42:43]
	v_cndmask_b32_e64 v87, v119, v235, s[42:43]
	v_cndmask_b32_e64 v232, v232, v116, s[42:43]
	v_cndmask_b32_e64 v233, v233, v117, s[42:43]
	v_cndmask_b32_e64 v234, v234, v118, s[42:43]
	v_cndmask_b32_e64 v235, v235, v119, s[42:43]
	global_store_dwordx4 v[224:225], v[84:87], off
	global_store_dwordx4 v[250:251], v[232:235], off
	s_nop 1
	s_waitcnt vmcnt(11)
	v_lshlrev_b32_e32 v216, 16, v108
	v_and_b32_e32 v217, 0xffff0000, v108
	v_lshlrev_b32_e32 v218, 16, v109
	v_and_b32_e32 v219, 0xffff0000, v109
	v_lshlrev_b32_e32 v220, 16, v110
	v_and_b32_e32 v221, 0xffff0000, v110
	v_lshlrev_b32_e32 v222, 16, v111
	v_and_b32_e32 v223, 0xffff0000, v111
	v_pk_mul_f32 v[44:45], v[44:45], v[216:217]
	v_pk_mul_f32 v[46:47], v[46:47], v[218:219]
	v_pk_mul_f32 v[40:41], v[40:41], v[220:221]
	v_pk_mul_f32 v[42:43], v[42:43], v[222:223]
	v_cvt_pk_bf16_f32 v108, v44, v45
	v_cvt_pk_bf16_f32 v109, v46, v47
	v_cvt_pk_bf16_f32 v110, v40, v41
	v_cvt_pk_bf16_f32 v111, v42, v43
	s_waitcnt vmcnt(10)
	v_lshlrev_b32_e32 v216, 16, v76
	v_and_b32_e32 v217, 0xffff0000, v76
	v_lshlrev_b32_e32 v218, 16, v77
	v_and_b32_e32 v219, 0xffff0000, v77
	v_lshlrev_b32_e32 v220, 16, v78
	v_and_b32_e32 v221, 0xffff0000, v78
	v_lshlrev_b32_e32 v222, 16, v79
	v_and_b32_e32 v223, 0xffff0000, v79
	v_pk_mul_f32 v[12:13], v[12:13], v[216:217]
	v_pk_mul_f32 v[14:15], v[14:15], v[218:219]
	v_pk_mul_f32 v[8:9], v[8:9], v[220:221]
	v_pk_mul_f32 v[10:11], v[10:11], v[222:223]
	v_cvt_pk_bf16_f32 v76, v12, v13
	v_cvt_pk_bf16_f32 v77, v14, v15
	v_cvt_pk_bf16_f32 v78, v8, v9
	v_cvt_pk_bf16_f32 v79, v10, v11
	s_waitcnt vmcnt(9)
	v_lshlrev_b32_e32 v216, 16, v100
	v_and_b32_e32 v217, 0xffff0000, v100
	v_lshlrev_b32_e32 v218, 16, v101
	v_and_b32_e32 v219, 0xffff0000, v101
	v_lshlrev_b32_e32 v220, 16, v102
	v_and_b32_e32 v221, 0xffff0000, v102
	v_lshlrev_b32_e32 v222, 16, v103
	v_and_b32_e32 v223, 0xffff0000, v103
	v_pk_mul_f32 v[36:37], v[36:37], v[216:217]
	v_pk_mul_f32 v[38:39], v[38:39], v[218:219]
	v_pk_mul_f32 v[32:33], v[32:33], v[220:221]
	v_pk_mul_f32 v[34:35], v[34:35], v[222:223]
	v_cvt_pk_bf16_f32 v100, v36, v37
	v_cvt_pk_bf16_f32 v101, v38, v39
	v_cvt_pk_bf16_f32 v102, v32, v33
	v_cvt_pk_bf16_f32 v103, v34, v35
	s_waitcnt vmcnt(8)
; __device__ __forceinline__ u32x4 pack8(const f32x4& a, const f32x4& b) { u32x4 w; w.x = pk2(a[0], a[1]); w.y = pk2(a[2], a[3]); w.z = pk2(b[0], b[1]); w.w = pk2(b[2], b[3]); return w; }
; __device__ __forceinline__ void unpack8(const u32x4& w, f32x4& a, f32x4& b) { a[0] = bflo(w.x); a[1] = bfhi(w.x); a[2] = bflo(w.y); a[3] = bfhi(w.y); b[0] = bflo(w.z); b[1] = bfhi(w.z); b[2] = bflo(w.w); b[3] = bfhi(w.w); }
;     __device__ __forceinline__ void operator()(const f32x4 (&acc)[2][2][4][2], const Unit& u, int wr, int wc, int fr, int fq) const {
;     ...
;                     for (int bj = 0; bj < 2; ++bj) { gw[m][bj] = *(const u32x4*)(tmpb + ((ai * 4 + m) * 2 + bj) * 8192 + voff);
;                         if (br > 0) pw[m][bj] = *(const u32x4*)(MRG + (size_t)(lrow0 + ai * HALF + m * 16) * 1024 + col0 + 128 * bj); }
; #pragma unroll
;                 for (int m = 0; m < 4; ++m)
; #pragma unroll
;                     for (int bj = 0; bj < 2; ++bj) { f32x4 g0, g1; unpack8(gw[m][bj], g0, g1);
;                         f32x4 v0 = acc[ai][bj][m][0] * g0, v1 = acc[ai][bj][m][1] * g1;
;                         if (br > 0) { f32x4 p0, p1; unpack8(pw[m][bj], p0, p1); v0 += p0; v1 += p1; }
;                         *(u32x4*)(MRG + (size_t)(lrow0 + ai * HALF + m * 16) * 1024 + col0 + 128 * bj) = pack8(v0, v1); }
	v_lshlrev_b32_e32 v216, 16, v68
	v_and_b32_e32 v217, 0xffff0000, v68
	v_lshlrev_b32_e32 v218, 16, v69
	v_and_b32_e32 v219, 0xffff0000, v69
	v_lshlrev_b32_e32 v220, 16, v70
	v_and_b32_e32 v221, 0xffff0000, v70
	v_lshlrev_b32_e32 v222, 16, v71
	v_and_b32_e32 v223, 0xffff0000, v71
	v_pk_mul_f32 v[4:5], v[4:5], v[216:217]
	v_pk_mul_f32 v[6:7], v[6:7], v[218:219]
	v_pk_mul_f32 v[0:1], v[0:1], v[220:221]
	v_pk_mul_f32 v[2:3], v[2:3], v[222:223]
	v_cvt_pk_bf16_f32 v68, v4, v5
	v_cvt_pk_bf16_f32 v69, v6, v7
	v_cvt_pk_bf16_f32 v70, v0, v1
	v_cvt_pk_bf16_f32 v71, v2, v3
	s_mov_b64 s[10:11], 0x50000
	v_lshl_add_u64 v[224:225], v[212:213], 0, s[10:11]
	s_mov_b64 s[10:11], 0x50000
	v_lshl_add_u64 v[250:251], v[252:253], 0, s[10:11]
	v_mov_b32_dpp v232, v76 row_ror:8 row_mask:0xf bank_mask:0xf
	v_mov_b32_dpp v233, v77 row_ror:8 row_mask:0xf bank_mask:0xf
	v_mov_b32_dpp v234, v78 row_ror:8 row_mask:0xf bank_mask:0xf
	v_mov_b32_dpp v235, v79 row_ror:8 row_mask:0xf bank_mask:0xf
	v_cndmask_b32_e64 v76, v108, v232, s[42:43]
	v_cndmask_b32_e64 v77, v109, v233, s[42:43]
	v_cndmask_b32_e64 v78, v110, v234, s[42:43]
	v_cndmask_b32_e64 v79, v111, v235, s[42:43]
	v_cndmask_b32_e64 v232, v232, v108, s[42:43]
	v_cndmask_b32_e64 v233, v233, v109, s[42:43]
	v_cndmask_b32_e64 v234, v234, v110, s[42:43]
	v_cndmask_b32_e64 v235, v235, v111, s[42:43]
	global_store_dwordx4 v[224:225], v[76:79], off
	global_store_dwordx4 v[250:251], v[232:235], off
	s_mov_b64 s[10:11], 0x58000
	v_lshl_add_u64 v[224:225], v[212:213], 0, s[10:11]
	s_mov_b64 s[10:11], 0x58000
	v_lshl_add_u64 v[250:251], v[252:253], 0, s[10:11]
	v_mov_b32_dpp v232, v68 row_ror:8 row_mask:0xf bank_mask:0xf
	v_mov_b32_dpp v233, v69 row_ror:8 row_mask:0xf bank_mask:0xf
	v_mov_b32_dpp v234, v70 row_ror:8 row_mask:0xf bank_mask:0xf
	v_mov_b32_dpp v235, v71 row_ror:8 row_mask:0xf bank_mask:0xf
	v_cndmask_b32_e64 v68, v100, v232, s[42:43]
	v_cndmask_b32_e64 v69, v101, v233, s[42:43]
	v_cndmask_b32_e64 v70, v102, v234, s[42:43]
	v_cndmask_b32_e64 v71, v103, v235, s[42:43]
	v_cndmask_b32_e64 v232, v232, v100, s[42:43]
	v_cndmask_b32_e64 v233, v233, v101, s[42:43]
	v_cndmask_b32_e64 v234, v234, v102, s[42:43]
	v_cndmask_b32_e64 v235, v235, v103, s[42:43]
	global_store_dwordx4 v[224:225], v[68:71], off
	global_store_dwordx4 v[250:251], v[232:235], off
	s_nop 1
	s_branch .Le2_done
.Le2_rmw:
	global_load_dwordx4 v[128:131], v[214:215], off
	global_load_dwordx4 v[132:135], v[212:213], off
	s_mov_b64 s[10:11], 0x2000
	v_lshl_add_u64 v[224:225], v[214:215], 0, s[10:11]
	global_load_dwordx4 v[136:139], v[224:225], off
	global_load_dwordx4 v[140:143], v[252:253], off
	s_mov_b64 s[10:11], 0x4000
	v_lshl_add_u64 v[224:225], v[214:215], 0, s[10:11]
	global_load_dwordx4 v[144:147], v[224:225], off
	s_mov_b64 s[10:11], 0x8000
	v_lshl_add_u64 v[250:251], v[212:213], 0, s[10:11]
	global_load_dwordx4 v[148:151], v[250:251], off
	s_mov_b64 s[10:11], 0x6000
	v_lshl_add_u64 v[224:225], v[214:215], 0, s[10:11]
	global_load_dwordx4 v[152:155], v[224:225], off
	s_mov_b64 s[10:11], 0x8000
	v_lshl_add_u64 v[250:251], v[252:253], 0, s[10:11]
	global_load_dwordx4 v[156:159], v[250:251], off
	s_mov_b64 s[10:11], 0x8000
	v_lshl_add_u64 v[224:225], v[214:215], 0, s[10:11]
	global_load_dwordx4 v[160:163], v[224:225], off
	s_mov_b64 s[10:11], 0x10000
	v_lshl_add_u64 v[250:251], v[212:213], 0, s[10:11]
	global_load_dwordx4 v[164:167], v[250:251], off
	s_mov_b64 s[10:11], 0xa000
	v_lshl_add_u64 v[224:225], v[214:215], 0, s[10:11]
	global_load_dwordx4 v[168:171], v[224:225], off
	s_mov_b64 s[10:11], 0x10000
	v_lshl_add_u64 v[250:251], v[252:253], 0, s[10:11]
	global_load_dwordx4 v[172:175], v[250:251], off
	s_mov_b64 s[10:11], 0xc000
	v_lshl_add_u64 v[224:225], v[214:215], 0, s[10:11]
	global_load_dwordx4 v[176:179], v[224:225], off
	s_mov_b64 s[10:11], 0x18000
	v_lshl_add_u64 v[250:251], v[212:213], 0, s[10:11]
	global_load_dwordx4 v[180:183], v[250:251], off
	s_mov_b64 s[10:11], 0xe000
	v_lshl_add_u64 v[224:225], v[214:215], 0, s[10:11]
	global_load_dwordx4 v[184:187], v[224:225], off
	s_mov_b64 s[10:11], 0x18000
	v_lshl_add_u64 v[250:251], v[252:253], 0, s[10:11]
	global_load_dwordx4 v[188:191], v[250:251], off
	s_waitcnt vmcnt(12)
	v_cndmask_b32_e64 v232, v132, v140, s[42:43]
	v_cndmask_b32_e64 v233, v133, v141, s[42:43]
	v_cndmask_b32_e64 v234, v134, v142, s[42:43]
	v_cndmask_b32_e64 v235, v135, v143, s[42:43]
	v_cndmask_b32_e64 v132, v140, v132, s[42:43]
	v_cndmask_b32_e64 v133, v141, v133, s[42:43]
	v_cndmask_b32_e64 v134, v142, v134, s[42:43]
	v_cndmask_b32_e64 v135, v143, v135, s[42:43]
	v_lshlrev_b32_e32 v216, 16, v128
	v_and_b32_e32 v217, 0xffff0000, v128
	v_lshlrev_b32_e32 v218, 16, v129
	v_and_b32_e32 v219, 0xffff0000, v129
	v_lshlrev_b32_e32 v220, 16, v130
	v_and_b32_e32 v221, 0xffff0000, v130
	v_lshlrev_b32_e32 v222, 16, v131
	v_and_b32_e32 v223, 0xffff0000, v131
	v_pk_mul_f32 v[124:125], v[124:125], v[216:217]
	v_pk_mul_f32 v[126:127], v[126:127], v[218:219]
	v_pk_mul_f32 v[120:121], v[120:121], v[220:221]
	v_pk_mul_f32 v[122:123], v[122:123], v[222:223]
	v_lshlrev_b32_e32 v216, 16, v232
	v_and_b32_e32 v217, 0xffff0000, v232
	v_lshlrev_b32_e32 v218, 16, v233
	v_and_b32_e32 v219, 0xffff0000, v233
	v_lshlrev_b32_e32 v220, 16, v234
	v_and_b32_e32 v221, 0xffff0000, v234
	v_lshlrev_b32_e32 v222, 16, v235
	v_and_b32_e32 v223, 0xffff0000, v235
	v_pk_add_f32 v[124:125], v[124:125], v[216:217]
	v_pk_add_f32 v[126:127], v[126:127], v[218:219]
	v_pk_add_f32 v[120:121], v[120:121], v[220:221]
	v_pk_add_f32 v[122:123], v[122:123], v[222:223]
	v_cvt_pk_bf16_f32 v128, v124, v125
	v_cvt_pk_bf16_f32 v129, v126, v127
	v_cvt_pk_bf16_f32 v130, v120, v121
	v_cvt_pk_bf16_f32 v131, v122, v123
	v_mov_b32_dpp v140, v132 row_ror:8 row_mask:0xf bank_mask:0xf
	v_mov_b32_dpp v141, v133 row_ror:8 row_mask:0xf bank_mask:0xf
	v_mov_b32_dpp v142, v134 row_ror:8 row_mask:0xf bank_mask:0xf
	v_mov_b32_dpp v143, v135 row_ror:8 row_mask:0xf bank_mask:0xf
	v_lshlrev_b32_e32 v216, 16, v136
	v_and_b32_e32 v217, 0xffff0000, v136
	v_lshlrev_b32_e32 v218, 16, v137
	v_and_b32_e32 v219, 0xffff0000, v137
	v_lshlrev_b32_e32 v220, 16, v138
	v_and_b32_e32 v221, 0xffff0000, v138
	v_lshlrev_b32_e32 v222, 16, v139
	v_and_b32_e32 v223, 0xffff0000, v139
	v_pk_mul_f32 v[92:93], v[92:93], v[216:217]
	v_pk_mul_f32 v[94:95], v[94:95], v[218:219]
	v_pk_mul_f32 v[88:89], v[88:89], v[220:221]
	v_pk_mul_f32 v[90:91], v[90:91], v[222:223]
	v_lshlrev_b32_e32 v216, 16, v140
	v_and_b32_e32 v217, 0xffff0000, v140
	v_lshlrev_b32_e32 v218, 16, v141
	v_and_b32_e32 v219, 0xffff0000, v141
	v_lshlrev_b32_e32 v220, 16, v142
	v_and_b32_e32 v221, 0xffff0000, v142
	v_lshlrev_b32_e32 v222, 16, v143
	v_and_b32_e32 v223, 0xffff0000, v143
	v_pk_add_f32 v[92:93], v[92:93], v[216:217]
	v_pk_add_f32 v[94:95], v[94:95], v[218:219]
	v_pk_add_f32 v[88:89], v[88:89], v[220:221]
	v_pk_add_f32 v[90:91], v[90:91], v[222:223]
	v_cvt_pk_bf16_f32 v136, v92, v93
	v_cvt_pk_bf16_f32 v137, v94, v95
	v_cvt_pk_bf16_f32 v138, v88, v89
	v_cvt_pk_bf16_f32 v139, v90, v91
	s_waitcnt vmcnt(8)
; __device__ __forceinline__ u32x4 pack8(const f32x4& a, const f32x4& b) { u32x4 w; w.x = pk2(a[0], a[1]); w.y = pk2(a[2], a[3]); w.z = pk2(b[0], b[1]); w.w = pk2(b[2], b[3]); return w; }
; __device__ __forceinline__ void unpack8(const u32x4& w, f32x4& a, f32x4& b) { a[0] = bflo(w.x); a[1] = bfhi(w.x); a[2] = bflo(w.y); a[3] = bfhi(w.y); b[0] = bflo(w.z); b[1] = bfhi(w.z); b[2] = bflo(w.w); b[3] = bfhi(w.w); }
;     __device__ __forceinline__ void operator()(const f32x4 (&acc)[2][2][4][2], const Unit& u, int wr, int wc, int fr, int fq) const {
;     ...
;                     for (int bj = 0; bj < 2; ++bj) { gw[m][bj] = *(const u32x4*)(tmpb + ((ai * 4 + m) * 2 + bj) * 8192 + voff);
;                         if (br > 0) pw[m][bj] = *(const u32x4*)(MRG + (size_t)(lrow0 + ai * HALF + m * 16) * 1024 + col0 + 128 * bj); }
; #pragma unroll
;                 for (int m = 0; m < 4; ++m)
; #pragma unroll
;                     for (int bj = 0; bj < 2; ++bj) { f32x4 g0, g1; unpack8(gw[m][bj], g0, g1);
;                         f32x4 v0 = acc[ai][bj][m][0] * g0, v1 = acc[ai][bj][m][1] * g1;
;                         if (br > 0) { f32x4 p0, p1; unpack8(pw[m][bj], p0, p1); v0 += p0; v1 += p1; }
;                         *(u32x4*)(MRG + (size_t)(lrow0 + ai * HALF + m * 16) * 1024 + col0 + 128 * bj) = pack8(v0, v1); }
	v_cndmask_b32_e64 v232, v148, v156, s[42:43]
	v_cndmask_b32_e64 v233, v149, v157, s[42:43]
	v_cndmask_b32_e64 v234, v150, v158, s[42:43]
	v_cndmask_b32_e64 v235, v151, v159, s[42:43]
	v_cndmask_b32_e64 v148, v156, v148, s[42:43]
	v_cndmask_b32_e64 v149, v157, v149, s[42:43]
	v_cndmask_b32_e64 v150, v158, v150, s[42:43]
	v_cndmask_b32_e64 v151, v159, v151, s[42:43]
	v_lshlrev_b32_e32 v216, 16, v144
	v_and_b32_e32 v217, 0xffff0000, v144
	v_lshlrev_b32_e32 v218, 16, v145
	v_and_b32_e32 v219, 0xffff0000, v145
	v_lshlrev_b32_e32 v220, 16, v146
	v_and_b32_e32 v221, 0xffff0000, v146
	v_lshlrev_b32_e32 v222, 16, v147
	v_and_b32_e32 v223, 0xffff0000, v147
	v_pk_mul_f32 v[116:117], v[116:117], v[216:217]
	v_pk_mul_f32 v[118:119], v[118:119], v[218:219]
	v_pk_mul_f32 v[112:113], v[112:113], v[220:221]
	v_pk_mul_f32 v[114:115], v[114:115], v[222:223]
	v_lshlrev_b32_e32 v216, 16, v232
	v_and_b32_e32 v217, 0xffff0000, v232
	v_lshlrev_b32_e32 v218, 16, v233
	v_and_b32_e32 v219, 0xffff0000, v233
	v_lshlrev_b32_e32 v220, 16, v234
	v_and_b32_e32 v221, 0xffff0000, v234
	v_lshlrev_b32_e32 v222, 16, v235
	v_and_b32_e32 v223, 0xffff0000, v235
	v_pk_add_f32 v[116:117], v[116:117], v[216:217]
	v_pk_add_f32 v[118:119], v[118:119], v[218:219]
	v_pk_add_f32 v[112:113], v[112:113], v[220:221]
	v_pk_add_f32 v[114:115], v[114:115], v[222:223]
	v_cvt_pk_bf16_f32 v144, v116, v117
	v_cvt_pk_bf16_f32 v145, v118, v119
	v_cvt_pk_bf16_f32 v146, v112, v113
	v_cvt_pk_bf16_f32 v147, v114, v115
	v_mov_b32_dpp v156, v148 row_ror:8 row_mask:0xf bank_mask:0xf
	v_mov_b32_dpp v157, v149 row_ror:8 row_mask:0xf bank_mask:0xf
	v_mov_b32_dpp v158, v150 row_ror:8 row_mask:0xf bank_mask:0xf
	v_mov_b32_dpp v159, v151 row_ror:8 row_mask:0xf bank_mask:0xf
	v_lshlrev_b32_e32 v216, 16, v152
	v_and_b32_e32 v217, 0xffff0000, v152
	v_lshlrev_b32_e32 v218, 16, v153
	v_and_b32_e32 v219, 0xffff0000, v153
	v_lshlrev_b32_e32 v220, 16, v154
	v_and_b32_e32 v221, 0xffff0000, v154
	v_lshlrev_b32_e32 v222, 16, v155
	v_and_b32_e32 v223, 0xffff0000, v155
	v_pk_mul_f32 v[84:85], v[84:85], v[216:217]
	v_pk_mul_f32 v[86:87], v[86:87], v[218:219]
	v_pk_mul_f32 v[80:81], v[80:81], v[220:221]
	v_pk_mul_f32 v[82:83], v[82:83], v[222:223]
	v_lshlrev_b32_e32 v216, 16, v156
	v_and_b32_e32 v217, 0xffff0000, v156
	v_lshlrev_b32_e32 v218, 16, v157
	v_and_b32_e32 v219, 0xffff0000, v157
	v_lshlrev_b32_e32 v220, 16, v158
	v_and_b32_e32 v221, 0xffff0000, v158
	v_lshlrev_b32_e32 v222, 16, v159
	v_and_b32_e32 v223, 0xffff0000, v159
	v_pk_add_f32 v[84:85], v[84:85], v[216:217]
	v_pk_add_f32 v[86:87], v[86:87], v[218:219]
	v_pk_add_f32 v[80:81], v[80:81], v[220:221]
	v_pk_add_f32 v[82:83], v[82:83], v[222:223]
	v_cvt_pk_bf16_f32 v152, v84, v85
	v_cvt_pk_bf16_f32 v153, v86, v87
	v_cvt_pk_bf16_f32 v154, v80, v81
	v_cvt_pk_bf16_f32 v155, v82, v83
	s_mov_b64 s[10:11], 0x10000
	v_lshl_add_u64 v[224:225], v[214:215], 0, s[10:11]
	global_load_dwordx4 v[124:127], v[224:225], off
	s_mov_b64 s[10:11], 0x40000
	v_lshl_add_u64 v[250:251], v[212:213], 0, s[10:11]
	global_load_dwordx4 v[120:123], v[250:251], off
	s_mov_b64 s[10:11], 0x12000
	v_lshl_add_u64 v[224:225], v[214:215], 0, s[10:11]
	global_load_dwordx4 v[92:95], v[224:225], off
	s_mov_b64 s[10:11], 0x40000
	v_lshl_add_u64 v[250:251], v[252:253], 0, s[10:11]
	global_load_dwordx4 v[88:91], v[250:251], off
	s_mov_b64 s[10:11], 0x14000
	v_lshl_add_u64 v[224:225], v[214:215], 0, s[10:11]
	global_load_dwordx4 v[116:119], v[224:225], off
	s_mov_b64 s[10:11], 0x48000
	v_lshl_add_u64 v[250:251], v[212:213], 0, s[10:11]
	global_load_dwordx4 v[112:115], v[250:251], off
	s_mov_b64 s[10:11], 0x16000
	v_lshl_add_u64 v[224:225], v[214:215], 0, s[10:11]
	global_load_dwordx4 v[84:87], v[224:225], off
	s_mov_b64 s[10:11], 0x48000
	v_lshl_add_u64 v[250:251], v[252:253], 0, s[10:11]
	global_load_dwordx4 v[80:83], v[250:251], off
	v_mov_b32_dpp v232, v136 row_ror:8 row_mask:0xf bank_mask:0xf
	v_mov_b32_dpp v233, v137 row_ror:8 row_mask:0xf bank_mask:0xf
	v_mov_b32_dpp v234, v138 row_ror:8 row_mask:0xf bank_mask:0xf
	v_mov_b32_dpp v235, v139 row_ror:8 row_mask:0xf bank_mask:0xf
	v_cndmask_b32_e64 v136, v128, v232, s[42:43]
	v_cndmask_b32_e64 v137, v129, v233, s[42:43]
	v_cndmask_b32_e64 v138, v130, v234, s[42:43]
	v_cndmask_b32_e64 v139, v131, v235, s[42:43]
	v_cndmask_b32_e64 v232, v232, v128, s[42:43]
	v_cndmask_b32_e64 v233, v233, v129, s[42:43]
	v_cndmask_b32_e64 v234, v234, v130, s[42:43]
	v_cndmask_b32_e64 v235, v235, v131, s[42:43]
	global_store_dwordx4 v[212:213], v[136:139], off
	global_store_dwordx4 v[252:253], v[232:235], off
	s_mov_b64 s[10:11], 0x8000
	v_lshl_add_u64 v[224:225], v[212:213], 0, s[10:11]
	s_mov_b64 s[10:11], 0x8000
	v_lshl_add_u64 v[250:251], v[252:253], 0, s[10:11]
	v_mov_b32_dpp v232, v152 row_ror:8 row_mask:0xf bank_mask:0xf
	v_mov_b32_dpp v233, v153 row_ror:8 row_mask:0xf bank_mask:0xf
	v_mov_b32_dpp v234, v154 row_ror:8 row_mask:0xf bank_mask:0xf
	v_mov_b32_dpp v235, v155 row_ror:8 row_mask:0xf bank_mask:0xf
	v_cndmask_b32_e64 v152, v144, v232, s[42:43]
	v_cndmask_b32_e64 v153, v145, v233, s[42:43]
	v_cndmask_b32_e64 v154, v146, v234, s[42:43]
	v_cndmask_b32_e64 v155, v147, v235, s[42:43]
	v_cndmask_b32_e64 v232, v232, v144, s[42:43]
	v_cndmask_b32_e64 v233, v233, v145, s[42:43]
	v_cndmask_b32_e64 v234, v234, v146, s[42:43]
	v_cndmask_b32_e64 v235, v235, v147, s[42:43]
	global_store_dwordx4 v[224:225], v[152:155], off
	global_store_dwordx4 v[250:251], v[232:235], off
	s_nop 1
	s_waitcnt vmcnt(16)
; __device__ __forceinline__ u32x4 pack8(const f32x4& a, const f32x4& b) { u32x4 w; w.x = pk2(a[0], a[1]); w.y = pk2(a[2], a[3]); w.z = pk2(b[0], b[1]); w.w = pk2(b[2], b[3]); return w; }
; __device__ __forceinline__ void unpack8(const u32x4& w, f32x4& a, f32x4& b) { a[0] = bflo(w.x); a[1] = bfhi(w.x); a[2] = bflo(w.y); a[3] = bfhi(w.y); b[0] = bflo(w.z); b[1] = bfhi(w.z); b[2] = bflo(w.w); b[3] = bfhi(w.w); }
;     __device__ __forceinline__ void operator()(const f32x4 (&acc)[2][2][4][2], const Unit& u, int wr, int wc, int fr, int fq) const {
;     ...
;                     for (int bj = 0; bj < 2; ++bj) { gw[m][bj] = *(const u32x4*)(tmpb + ((ai * 4 + m) * 2 + bj) * 8192 + voff);
;                         if (br > 0) pw[m][bj] = *(const u32x4*)(MRG + (size_t)(lrow0 + ai * HALF + m * 16) * 1024 + col0 + 128 * bj); }
; #pragma unroll
;                 for (int m = 0; m < 4; ++m)
; #pragma unroll
;                     for (int bj = 0; bj < 2; ++bj) { f32x4 g0, g1; unpack8(gw[m][bj], g0, g1);
;                         f32x4 v0 = acc[ai][bj][m][0] * g0, v1 = acc[ai][bj][m][1] * g1;
;                         if (br > 0) { f32x4 p0, p1; unpack8(pw[m][bj], p0, p1); v0 += p0; v1 += p1; }
;                         *(u32x4*)(MRG + (size_t)(lrow0 + ai * HALF + m * 16) * 1024 + col0 + 128 * bj) = pack8(v0, v1); }
	v_cndmask_b32_e64 v232, v164, v172, s[42:43]
	v_cndmask_b32_e64 v233, v165, v173, s[42:43]
	v_cndmask_b32_e64 v234, v166, v174, s[42:43]
	v_cndmask_b32_e64 v235, v167, v175, s[42:43]
	v_cndmask_b32_e64 v164, v172, v164, s[42:43]
	v_cndmask_b32_e64 v165, v173, v165, s[42:43]
	v_cndmask_b32_e64 v166, v174, v166, s[42:43]
	v_cndmask_b32_e64 v167, v175, v167, s[42:43]
	v_lshlrev_b32_e32 v216, 16, v160
	v_and_b32_e32 v217, 0xffff0000, v160
	v_lshlrev_b32_e32 v218, 16, v161
	v_and_b32_e32 v219, 0xffff0000, v161
	v_lshlrev_b32_e32 v220, 16, v162
	v_and_b32_e32 v221, 0xffff0000, v162
	v_lshlrev_b32_e32 v222, 16, v163
	v_and_b32_e32 v223, 0xffff0000, v163
	v_pk_mul_f32 v[108:109], v[108:109], v[216:217]
	v_pk_mul_f32 v[110:111], v[110:111], v[218:219]
	v_pk_mul_f32 v[104:105], v[104:105], v[220:221]
	v_pk_mul_f32 v[106:107], v[106:107], v[222:223]
	v_lshlrev_b32_e32 v216, 16, v232
	v_and_b32_e32 v217, 0xffff0000, v232
	v_lshlrev_b32_e32 v218, 16, v233
	v_and_b32_e32 v219, 0xffff0000, v233
	v_lshlrev_b32_e32 v220, 16, v234
	v_and_b32_e32 v221, 0xffff0000, v234
	v_lshlrev_b32_e32 v222, 16, v235
	v_and_b32_e32 v223, 0xffff0000, v235
	v_pk_add_f32 v[108:109], v[108:109], v[216:217]
	v_pk_add_f32 v[110:111], v[110:111], v[218:219]
	v_pk_add_f32 v[104:105], v[104:105], v[220:221]
	v_pk_add_f32 v[106:107], v[106:107], v[222:223]
	v_cvt_pk_bf16_f32 v160, v108, v109
	v_cvt_pk_bf16_f32 v161, v110, v111
	v_cvt_pk_bf16_f32 v162, v104, v105
	v_cvt_pk_bf16_f32 v163, v106, v107
	v_mov_b32_dpp v172, v164 row_ror:8 row_mask:0xf bank_mask:0xf
	v_mov_b32_dpp v173, v165 row_ror:8 row_mask:0xf bank_mask:0xf
	v_mov_b32_dpp v174, v166 row_ror:8 row_mask:0xf bank_mask:0xf
	v_mov_b32_dpp v175, v167 row_ror:8 row_mask:0xf bank_mask:0xf
	v_lshlrev_b32_e32 v216, 16, v168
	v_and_b32_e32 v217, 0xffff0000, v168
	v_lshlrev_b32_e32 v218, 16, v169
	v_and_b32_e32 v219, 0xffff0000, v169
	v_lshlrev_b32_e32 v220, 16, v170
	v_and_b32_e32 v221, 0xffff0000, v170
	v_lshlrev_b32_e32 v222, 16, v171
	v_and_b32_e32 v223, 0xffff0000, v171
	v_pk_mul_f32 v[76:77], v[76:77], v[216:217]
	v_pk_mul_f32 v[78:79], v[78:79], v[218:219]
	v_pk_mul_f32 v[72:73], v[72:73], v[220:221]
	v_pk_mul_f32 v[74:75], v[74:75], v[222:223]
	v_lshlrev_b32_e32 v216, 16, v172
	v_and_b32_e32 v217, 0xffff0000, v172
	v_lshlrev_b32_e32 v218, 16, v173
	v_and_b32_e32 v219, 0xffff0000, v173
	v_lshlrev_b32_e32 v220, 16, v174
	v_and_b32_e32 v221, 0xffff0000, v174
	v_lshlrev_b32_e32 v222, 16, v175
	v_and_b32_e32 v223, 0xffff0000, v175
	v_pk_add_f32 v[76:77], v[76:77], v[216:217]
	v_pk_add_f32 v[78:79], v[78:79], v[218:219]
	v_pk_add_f32 v[72:73], v[72:73], v[220:221]
	v_pk_add_f32 v[74:75], v[74:75], v[222:223]
	v_cvt_pk_bf16_f32 v168, v76, v77
	v_cvt_pk_bf16_f32 v169, v78, v79
	v_cvt_pk_bf16_f32 v170, v72, v73
	v_cvt_pk_bf16_f32 v171, v74, v75
	s_waitcnt vmcnt(12)
	v_cndmask_b32_e64 v232, v180, v188, s[42:43]
	v_cndmask_b32_e64 v233, v181, v189, s[42:43]
	v_cndmask_b32_e64 v234, v182, v190, s[42:43]
	v_cndmask_b32_e64 v235, v183, v191, s[42:43]
	v_cndmask_b32_e64 v180, v188, v180, s[42:43]
	v_cndmask_b32_e64 v181, v189, v181, s[42:43]
	v_cndmask_b32_e64 v182, v190, v182, s[42:43]
	v_cndmask_b32_e64 v183, v191, v183, s[42:43]
	v_lshlrev_b32_e32 v216, 16, v176
	v_and_b32_e32 v217, 0xffff0000, v176
	v_lshlrev_b32_e32 v218, 16, v177
	v_and_b32_e32 v219, 0xffff0000, v177
	v_lshlrev_b32_e32 v220, 16, v178
	v_and_b32_e32 v221, 0xffff0000, v178
	v_lshlrev_b32_e32 v222, 16, v179
	v_and_b32_e32 v223, 0xffff0000, v179
	v_pk_mul_f32 v[100:101], v[100:101], v[216:217]
	v_pk_mul_f32 v[102:103], v[102:103], v[218:219]
	v_pk_mul_f32 v[96:97], v[96:97], v[220:221]
	v_pk_mul_f32 v[98:99], v[98:99], v[222:223]
	v_lshlrev_b32_e32 v216, 16, v232
	v_and_b32_e32 v217, 0xffff0000, v232
	v_lshlrev_b32_e32 v218, 16, v233
	v_and_b32_e32 v219, 0xffff0000, v233
	v_lshlrev_b32_e32 v220, 16, v234
	v_and_b32_e32 v221, 0xffff0000, v234
	v_lshlrev_b32_e32 v222, 16, v235
	v_and_b32_e32 v223, 0xffff0000, v235
	v_pk_add_f32 v[100:101], v[100:101], v[216:217]
	v_pk_add_f32 v[102:103], v[102:103], v[218:219]
	v_pk_add_f32 v[96:97], v[96:97], v[220:221]
	v_pk_add_f32 v[98:99], v[98:99], v[222:223]
	v_cvt_pk_bf16_f32 v176, v100, v101
	v_cvt_pk_bf16_f32 v177, v102, v103
	v_cvt_pk_bf16_f32 v178, v96, v97
	v_cvt_pk_bf16_f32 v179, v98, v99
	v_mov_b32_dpp v188, v180 row_ror:8 row_mask:0xf bank_mask:0xf
	v_mov_b32_dpp v189, v181 row_ror:8 row_mask:0xf bank_mask:0xf
	v_mov_b32_dpp v190, v182 row_ror:8 row_mask:0xf bank_mask:0xf
	v_mov_b32_dpp v191, v183 row_ror:8 row_mask:0xf bank_mask:0xf
	v_lshlrev_b32_e32 v216, 16, v184
	v_and_b32_e32 v217, 0xffff0000, v184
	v_lshlrev_b32_e32 v218, 16, v185
	v_and_b32_e32 v219, 0xffff0000, v185
	v_lshlrev_b32_e32 v220, 16, v186
	v_and_b32_e32 v221, 0xffff0000, v186
	v_lshlrev_b32_e32 v222, 16, v187
	v_and_b32_e32 v223, 0xffff0000, v187
	v_pk_mul_f32 v[68:69], v[68:69], v[216:217]
	v_pk_mul_f32 v[70:71], v[70:71], v[218:219]
	v_pk_mul_f32 v[64:65], v[64:65], v[220:221]
	v_pk_mul_f32 v[66:67], v[66:67], v[222:223]
	v_lshlrev_b32_e32 v216, 16, v188
	v_and_b32_e32 v217, 0xffff0000, v188
	v_lshlrev_b32_e32 v218, 16, v189
	v_and_b32_e32 v219, 0xffff0000, v189
	v_lshlrev_b32_e32 v220, 16, v190
	v_and_b32_e32 v221, 0xffff0000, v190
	v_lshlrev_b32_e32 v222, 16, v191
	v_and_b32_e32 v223, 0xffff0000, v191
	v_pk_add_f32 v[68:69], v[68:69], v[216:217]
	v_pk_add_f32 v[70:71], v[70:71], v[218:219]
	v_pk_add_f32 v[64:65], v[64:65], v[220:221]
	v_pk_add_f32 v[66:67], v[66:67], v[222:223]
	v_cvt_pk_bf16_f32 v184, v68, v69
	v_cvt_pk_bf16_f32 v185, v70, v71
	v_cvt_pk_bf16_f32 v186, v64, v65
	v_cvt_pk_bf16_f32 v187, v66, v67
	s_mov_b64 s[10:11], 0x18000
; __device__ __forceinline__ u32x4 pack8(const f32x4& a, const f32x4& b) { u32x4 w; w.x = pk2(a[0], a[1]); w.y = pk2(a[2], a[3]); w.z = pk2(b[0], b[1]); w.w = pk2(b[2], b[3]); return w; }
; __device__ __forceinline__ void unpack8(const u32x4& w, f32x4& a, f32x4& b) { a[0] = bflo(w.x); a[1] = bfhi(w.x); a[2] = bflo(w.y); a[3] = bfhi(w.y); b[0] = bflo(w.z); b[1] = bfhi(w.z); b[2] = bflo(w.w); b[3] = bfhi(w.w); }
;     __device__ __forceinline__ void operator()(const f32x4 (&acc)[2][2][4][2], const Unit& u, int wr, int wc, int fr, int fq) const {
;     ...
;                     for (int bj = 0; bj < 2; ++bj) { gw[m][bj] = *(const u32x4*)(tmpb + ((ai * 4 + m) * 2 + bj) * 8192 + voff);
;                         if (br > 0) pw[m][bj] = *(const u32x4*)(MRG + (size_t)(lrow0 + ai * HALF + m * 16) * 1024 + col0 + 128 * bj); }
; #pragma unroll
;                 for (int m = 0; m < 4; ++m)
; #pragma unroll
;                     for (int bj = 0; bj < 2; ++bj) { f32x4 g0, g1; unpack8(gw[m][bj], g0, g1);
;                         f32x4 v0 = acc[ai][bj][m][0] * g0, v1 = acc[ai][bj][m][1] * g1;
;                         if (br > 0) { f32x4 p0, p1; unpack8(pw[m][bj], p0, p1); v0 += p0; v1 += p1; }
;                         *(u32x4*)(MRG + (size_t)(lrow0 + ai * HALF + m * 16) * 1024 + col0 + 128 * bj) = pack8(v0, v1); }
	v_lshl_add_u64 v[224:225], v[214:215], 0, s[10:11]
	global_load_dwordx4 v[108:111], v[224:225], off
	s_mov_b64 s[10:11], 0x50000
	v_lshl_add_u64 v[250:251], v[212:213], 0, s[10:11]
	global_load_dwordx4 v[104:107], v[250:251], off
	s_mov_b64 s[10:11], 0x1a000
	v_lshl_add_u64 v[224:225], v[214:215], 0, s[10:11]
	global_load_dwordx4 v[76:79], v[224:225], off
	s_mov_b64 s[10:11], 0x50000
	v_lshl_add_u64 v[250:251], v[252:253], 0, s[10:11]
	global_load_dwordx4 v[72:75], v[250:251], off
	s_mov_b64 s[10:11], 0x1c000
	v_lshl_add_u64 v[224:225], v[214:215], 0, s[10:11]
	global_load_dwordx4 v[100:103], v[224:225], off
	s_mov_b64 s[10:11], 0x58000
	v_lshl_add_u64 v[250:251], v[212:213], 0, s[10:11]
	global_load_dwordx4 v[96:99], v[250:251], off
	s_mov_b64 s[10:11], 0x1e000
	v_lshl_add_u64 v[224:225], v[214:215], 0, s[10:11]
	global_load_dwordx4 v[68:71], v[224:225], off
	s_mov_b64 s[10:11], 0x58000
	v_lshl_add_u64 v[250:251], v[252:253], 0, s[10:11]
	global_load_dwordx4 v[64:67], v[250:251], off
	s_mov_b64 s[10:11], 0x10000
	v_lshl_add_u64 v[224:225], v[212:213], 0, s[10:11]
	s_mov_b64 s[10:11], 0x10000
	v_lshl_add_u64 v[250:251], v[252:253], 0, s[10:11]
	v_mov_b32_dpp v232, v168 row_ror:8 row_mask:0xf bank_mask:0xf
	v_mov_b32_dpp v233, v169 row_ror:8 row_mask:0xf bank_mask:0xf
	v_mov_b32_dpp v234, v170 row_ror:8 row_mask:0xf bank_mask:0xf
	v_mov_b32_dpp v235, v171 row_ror:8 row_mask:0xf bank_mask:0xf
	v_cndmask_b32_e64 v168, v160, v232, s[42:43]
	v_cndmask_b32_e64 v169, v161, v233, s[42:43]
	v_cndmask_b32_e64 v170, v162, v234, s[42:43]
	v_cndmask_b32_e64 v171, v163, v235, s[42:43]
	v_cndmask_b32_e64 v232, v232, v160, s[42:43]
	v_cndmask_b32_e64 v233, v233, v161, s[42:43]
	v_cndmask_b32_e64 v234, v234, v162, s[42:43]
	v_cndmask_b32_e64 v235, v235, v163, s[42:43]
	global_store_dwordx4 v[224:225], v[168:171], off
	global_store_dwordx4 v[250:251], v[232:235], off
	s_mov_b64 s[10:11], 0x18000
	v_lshl_add_u64 v[224:225], v[212:213], 0, s[10:11]
	s_mov_b64 s[10:11], 0x18000
	v_lshl_add_u64 v[250:251], v[252:253], 0, s[10:11]
	v_mov_b32_dpp v232, v184 row_ror:8 row_mask:0xf bank_mask:0xf
	v_mov_b32_dpp v233, v185 row_ror:8 row_mask:0xf bank_mask:0xf
	v_mov_b32_dpp v234, v186 row_ror:8 row_mask:0xf bank_mask:0xf
	v_mov_b32_dpp v235, v187 row_ror:8 row_mask:0xf bank_mask:0xf
	v_cndmask_b32_e64 v184, v176, v232, s[42:43]
	v_cndmask_b32_e64 v185, v177, v233, s[42:43]
	v_cndmask_b32_e64 v186, v178, v234, s[42:43]
	v_cndmask_b32_e64 v187, v179, v235, s[42:43]
	v_cndmask_b32_e64 v232, v232, v176, s[42:43]
	v_cndmask_b32_e64 v233, v233, v177, s[42:43]
	v_cndmask_b32_e64 v234, v234, v178, s[42:43]
	v_cndmask_b32_e64 v235, v235, v179, s[42:43]
	global_store_dwordx4 v[224:225], v[184:187], off
	global_store_dwordx4 v[250:251], v[232:235], off
	s_nop 1
	s_waitcnt vmcnt(20)
	v_cndmask_b32_e64 v232, v120, v88, s[42:43]
	v_cndmask_b32_e64 v233, v121, v89, s[42:43]
	v_cndmask_b32_e64 v234, v122, v90, s[42:43]
	v_cndmask_b32_e64 v235, v123, v91, s[42:43]
	v_cndmask_b32_e64 v120, v88, v120, s[42:43]
	v_cndmask_b32_e64 v121, v89, v121, s[42:43]
	v_cndmask_b32_e64 v122, v90, v122, s[42:43]
	v_cndmask_b32_e64 v123, v91, v123, s[42:43]
	v_lshlrev_b32_e32 v216, 16, v124
	v_and_b32_e32 v217, 0xffff0000, v124
	v_lshlrev_b32_e32 v218, 16, v125
	v_and_b32_e32 v219, 0xffff0000, v125
	v_lshlrev_b32_e32 v220, 16, v126
	v_and_b32_e32 v221, 0xffff0000, v126
	v_lshlrev_b32_e32 v222, 16, v127
	v_and_b32_e32 v223, 0xffff0000, v127
	v_pk_mul_f32 v[60:61], v[60:61], v[216:217]
	v_pk_mul_f32 v[62:63], v[62:63], v[218:219]
	v_pk_mul_f32 v[56:57], v[56:57], v[220:221]
	v_pk_mul_f32 v[58:59], v[58:59], v[222:223]
	v_lshlrev_b32_e32 v216, 16, v232
	v_and_b32_e32 v217, 0xffff0000, v232
	v_lshlrev_b32_e32 v218, 16, v233
	v_and_b32_e32 v219, 0xffff0000, v233
	v_lshlrev_b32_e32 v220, 16, v234
	v_and_b32_e32 v221, 0xffff0000, v234
	v_lshlrev_b32_e32 v222, 16, v235
	v_and_b32_e32 v223, 0xffff0000, v235
	v_pk_add_f32 v[60:61], v[60:61], v[216:217]
	v_pk_add_f32 v[62:63], v[62:63], v[218:219]
	v_pk_add_f32 v[56:57], v[56:57], v[220:221]
	v_pk_add_f32 v[58:59], v[58:59], v[222:223]
	v_cvt_pk_bf16_f32 v124, v60, v61
	v_cvt_pk_bf16_f32 v125, v62, v63
	v_cvt_pk_bf16_f32 v126, v56, v57
	v_cvt_pk_bf16_f32 v127, v58, v59
	v_mov_b32_dpp v88, v120 row_ror:8 row_mask:0xf bank_mask:0xf
	v_mov_b32_dpp v89, v121 row_ror:8 row_mask:0xf bank_mask:0xf
	v_mov_b32_dpp v90, v122 row_ror:8 row_mask:0xf bank_mask:0xf
	v_mov_b32_dpp v91, v123 row_ror:8 row_mask:0xf bank_mask:0xf
	v_lshlrev_b32_e32 v216, 16, v92
	v_and_b32_e32 v217, 0xffff0000, v92
	v_lshlrev_b32_e32 v218, 16, v93
	v_and_b32_e32 v219, 0xffff0000, v93
	v_lshlrev_b32_e32 v220, 16, v94
	v_and_b32_e32 v221, 0xffff0000, v94
	v_lshlrev_b32_e32 v222, 16, v95
	v_and_b32_e32 v223, 0xffff0000, v95
	v_pk_mul_f32 v[28:29], v[28:29], v[216:217]
	v_pk_mul_f32 v[30:31], v[30:31], v[218:219]
	v_pk_mul_f32 v[24:25], v[24:25], v[220:221]
	v_pk_mul_f32 v[26:27], v[26:27], v[222:223]
	v_lshlrev_b32_e32 v216, 16, v88
	v_and_b32_e32 v217, 0xffff0000, v88
	v_lshlrev_b32_e32 v218, 16, v89
	v_and_b32_e32 v219, 0xffff0000, v89
	v_lshlrev_b32_e32 v220, 16, v90
	v_and_b32_e32 v221, 0xffff0000, v90
	v_lshlrev_b32_e32 v222, 16, v91
	v_and_b32_e32 v223, 0xffff0000, v91
	v_pk_add_f32 v[28:29], v[28:29], v[216:217]
	v_pk_add_f32 v[30:31], v[30:31], v[218:219]
	v_pk_add_f32 v[24:25], v[24:25], v[220:221]
	v_pk_add_f32 v[26:27], v[26:27], v[222:223]
	v_cvt_pk_bf16_f32 v92, v28, v29
	v_cvt_pk_bf16_f32 v93, v30, v31
	v_cvt_pk_bf16_f32 v94, v24, v25
	v_cvt_pk_bf16_f32 v95, v26, v27
	s_waitcnt vmcnt(16)
; __device__ __forceinline__ u32x4 pack8(const f32x4& a, const f32x4& b) { u32x4 w; w.x = pk2(a[0], a[1]); w.y = pk2(a[2], a[3]); w.z = pk2(b[0], b[1]); w.w = pk2(b[2], b[3]); return w; }
; __device__ __forceinline__ void unpack8(const u32x4& w, f32x4& a, f32x4& b) { a[0] = bflo(w.x); a[1] = bfhi(w.x); a[2] = bflo(w.y); a[3] = bfhi(w.y); b[0] = bflo(w.z); b[1] = bfhi(w.z); b[2] = bflo(w.w); b[3] = bfhi(w.w); }
;     __device__ __forceinline__ void operator()(const f32x4 (&acc)[2][2][4][2], const Unit& u, int wr, int wc, int fr, int fq) const {
;     ...
;                     for (int bj = 0; bj < 2; ++bj) { gw[m][bj] = *(const u32x4*)(tmpb + ((ai * 4 + m) * 2 + bj) * 8192 + voff);
;                         if (br > 0) pw[m][bj] = *(const u32x4*)(MRG + (size_t)(lrow0 + ai * HALF + m * 16) * 1024 + col0 + 128 * bj); }
; #pragma unroll
;                 for (int m = 0; m < 4; ++m)
; #pragma unroll
;                     for (int bj = 0; bj < 2; ++bj) { f32x4 g0, g1; unpack8(gw[m][bj], g0, g1);
;                         f32x4 v0 = acc[ai][bj][m][0] * g0, v1 = acc[ai][bj][m][1] * g1;
;                         if (br > 0) { f32x4 p0, p1; unpack8(pw[m][bj], p0, p1); v0 += p0; v1 += p1; }
;                         *(u32x4*)(MRG + (size_t)(lrow0 + ai * HALF + m * 16) * 1024 + col0 + 128 * bj) = pack8(v0, v1); }
	v_cndmask_b32_e64 v232, v112, v80, s[42:43]
	v_cndmask_b32_e64 v233, v113, v81, s[42:43]
	v_cndmask_b32_e64 v234, v114, v82, s[42:43]
	v_cndmask_b32_e64 v235, v115, v83, s[42:43]
	v_cndmask_b32_e64 v112, v80, v112, s[42:43]
	v_cndmask_b32_e64 v113, v81, v113, s[42:43]
	v_cndmask_b32_e64 v114, v82, v114, s[42:43]
	v_cndmask_b32_e64 v115, v83, v115, s[42:43]
	v_lshlrev_b32_e32 v216, 16, v116
	v_and_b32_e32 v217, 0xffff0000, v116
	v_lshlrev_b32_e32 v218, 16, v117
	v_and_b32_e32 v219, 0xffff0000, v117
	v_lshlrev_b32_e32 v220, 16, v118
	v_and_b32_e32 v221, 0xffff0000, v118
	v_lshlrev_b32_e32 v222, 16, v119
	v_and_b32_e32 v223, 0xffff0000, v119
	v_pk_mul_f32 v[52:53], v[52:53], v[216:217]
	v_pk_mul_f32 v[54:55], v[54:55], v[218:219]
	v_pk_mul_f32 v[48:49], v[48:49], v[220:221]
	v_pk_mul_f32 v[50:51], v[50:51], v[222:223]
	v_lshlrev_b32_e32 v216, 16, v232
	v_and_b32_e32 v217, 0xffff0000, v232
	v_lshlrev_b32_e32 v218, 16, v233
	v_and_b32_e32 v219, 0xffff0000, v233
	v_lshlrev_b32_e32 v220, 16, v234
	v_and_b32_e32 v221, 0xffff0000, v234
	v_lshlrev_b32_e32 v222, 16, v235
	v_and_b32_e32 v223, 0xffff0000, v235
	v_pk_add_f32 v[52:53], v[52:53], v[216:217]
	v_pk_add_f32 v[54:55], v[54:55], v[218:219]
	v_pk_add_f32 v[48:49], v[48:49], v[220:221]
	v_pk_add_f32 v[50:51], v[50:51], v[222:223]
	v_cvt_pk_bf16_f32 v116, v52, v53
	v_cvt_pk_bf16_f32 v117, v54, v55
	v_cvt_pk_bf16_f32 v118, v48, v49
	v_cvt_pk_bf16_f32 v119, v50, v51
	v_mov_b32_dpp v80, v112 row_ror:8 row_mask:0xf bank_mask:0xf
	v_mov_b32_dpp v81, v113 row_ror:8 row_mask:0xf bank_mask:0xf
	v_mov_b32_dpp v82, v114 row_ror:8 row_mask:0xf bank_mask:0xf
	v_mov_b32_dpp v83, v115 row_ror:8 row_mask:0xf bank_mask:0xf
	v_lshlrev_b32_e32 v216, 16, v84
	v_and_b32_e32 v217, 0xffff0000, v84
	v_lshlrev_b32_e32 v218, 16, v85
	v_and_b32_e32 v219, 0xffff0000, v85
	v_lshlrev_b32_e32 v220, 16, v86
	v_and_b32_e32 v221, 0xffff0000, v86
	v_lshlrev_b32_e32 v222, 16, v87
	v_and_b32_e32 v223, 0xffff0000, v87
	v_pk_mul_f32 v[20:21], v[20:21], v[216:217]
	v_pk_mul_f32 v[22:23], v[22:23], v[218:219]
	v_pk_mul_f32 v[16:17], v[16:17], v[220:221]
	v_pk_mul_f32 v[18:19], v[18:19], v[222:223]
	v_lshlrev_b32_e32 v216, 16, v80
	v_and_b32_e32 v217, 0xffff0000, v80
	v_lshlrev_b32_e32 v218, 16, v81
	v_and_b32_e32 v219, 0xffff0000, v81
	v_lshlrev_b32_e32 v220, 16, v82
	v_and_b32_e32 v221, 0xffff0000, v82
	v_lshlrev_b32_e32 v222, 16, v83
	v_and_b32_e32 v223, 0xffff0000, v83
	v_pk_add_f32 v[20:21], v[20:21], v[216:217]
	v_pk_add_f32 v[22:23], v[22:23], v[218:219]
	v_pk_add_f32 v[16:17], v[16:17], v[220:221]
	v_pk_add_f32 v[18:19], v[18:19], v[222:223]
	v_cvt_pk_bf16_f32 v84, v20, v21
	v_cvt_pk_bf16_f32 v85, v22, v23
	v_cvt_pk_bf16_f32 v86, v16, v17
	v_cvt_pk_bf16_f32 v87, v18, v19
	s_mov_b64 s[10:11], 0x40000
	v_lshl_add_u64 v[224:225], v[212:213], 0, s[10:11]
	s_mov_b64 s[10:11], 0x40000
	v_lshl_add_u64 v[250:251], v[252:253], 0, s[10:11]
	v_mov_b32_dpp v232, v92 row_ror:8 row_mask:0xf bank_mask:0xf
	v_mov_b32_dpp v233, v93 row_ror:8 row_mask:0xf bank_mask:0xf
	v_mov_b32_dpp v234, v94 row_ror:8 row_mask:0xf bank_mask:0xf
	v_mov_b32_dpp v235, v95 row_ror:8 row_mask:0xf bank_mask:0xf
	v_cndmask_b32_e64 v92, v124, v232, s[42:43]
	v_cndmask_b32_e64 v93, v125, v233, s[42:43]
	v_cndmask_b32_e64 v94, v126, v234, s[42:43]
	v_cndmask_b32_e64 v95, v127, v235, s[42:43]
	v_cndmask_b32_e64 v232, v232, v124, s[42:43]
	v_cndmask_b32_e64 v233, v233, v125, s[42:43]
	v_cndmask_b32_e64 v234, v234, v126, s[42:43]
	v_cndmask_b32_e64 v235, v235, v127, s[42:43]
	global_store_dwordx4 v[224:225], v[92:95], off
	global_store_dwordx4 v[250:251], v[232:235], off
	s_mov_b64 s[10:11], 0x48000
	v_lshl_add_u64 v[224:225], v[212:213], 0, s[10:11]
	s_mov_b64 s[10:11], 0x48000
	v_lshl_add_u64 v[250:251], v[252:253], 0, s[10:11]
	v_mov_b32_dpp v232, v84 row_ror:8 row_mask:0xf bank_mask:0xf
	v_mov_b32_dpp v233, v85 row_ror:8 row_mask:0xf bank_mask:0xf
	v_mov_b32_dpp v234, v86 row_ror:8 row_mask:0xf bank_mask:0xf
	v_mov_b32_dpp v235, v87 row_ror:8 row_mask:0xf bank_mask:0xf
	v_cndmask_b32_e64 v84, v116, v232, s[42:43]
	v_cndmask_b32_e64 v85, v117, v233, s[42:43]
	v_cndmask_b32_e64 v86, v118, v234, s[42:43]
	v_cndmask_b32_e64 v87, v119, v235, s[42:43]
	v_cndmask_b32_e64 v232, v232, v116, s[42:43]
	v_cndmask_b32_e64 v233, v233, v117, s[42:43]
	v_cndmask_b32_e64 v234, v234, v118, s[42:43]
	v_cndmask_b32_e64 v235, v235, v119, s[42:43]
	global_store_dwordx4 v[224:225], v[84:87], off
	global_store_dwordx4 v[250:251], v[232:235], off
	s_nop 1
	s_waitcnt vmcnt(12)
; __device__ __forceinline__ u32x4 pack8(const f32x4& a, const f32x4& b) { u32x4 w; w.x = pk2(a[0], a[1]); w.y = pk2(a[2], a[3]); w.z = pk2(b[0], b[1]); w.w = pk2(b[2], b[3]); return w; }
; __device__ __forceinline__ void unpack8(const u32x4& w, f32x4& a, f32x4& b) { a[0] = bflo(w.x); a[1] = bfhi(w.x); a[2] = bflo(w.y); a[3] = bfhi(w.y); b[0] = bflo(w.z); b[1] = bfhi(w.z); b[2] = bflo(w.w); b[3] = bfhi(w.w); }
;     __device__ __forceinline__ void operator()(const f32x4 (&acc)[2][2][4][2], const Unit& u, int wr, int wc, int fr, int fq) const {
;     ...
;                     for (int bj = 0; bj < 2; ++bj) { gw[m][bj] = *(const u32x4*)(tmpb + ((ai * 4 + m) * 2 + bj) * 8192 + voff);
;                         if (br > 0) pw[m][bj] = *(const u32x4*)(MRG + (size_t)(lrow0 + ai * HALF + m * 16) * 1024 + col0 + 128 * bj); }
; #pragma unroll
;                 for (int m = 0; m < 4; ++m)
; #pragma unroll
;                     for (int bj = 0; bj < 2; ++bj) { f32x4 g0, g1; unpack8(gw[m][bj], g0, g1);
;                         f32x4 v0 = acc[ai][bj][m][0] * g0, v1 = acc[ai][bj][m][1] * g1;
;                         if (br > 0) { f32x4 p0, p1; unpack8(pw[m][bj], p0, p1); v0 += p0; v1 += p1; }
;                         *(u32x4*)(MRG + (size_t)(lrow0 + ai * HALF + m * 16) * 1024 + col0 + 128 * bj) = pack8(v0, v1); }
	v_cndmask_b32_e64 v232, v104, v72, s[42:43]
	v_cndmask_b32_e64 v233, v105, v73, s[42:43]
	v_cndmask_b32_e64 v234, v106, v74, s[42:43]
	v_cndmask_b32_e64 v235, v107, v75, s[42:43]
	v_cndmask_b32_e64 v104, v72, v104, s[42:43]
	v_cndmask_b32_e64 v105, v73, v105, s[42:43]
	v_cndmask_b32_e64 v106, v74, v106, s[42:43]
	v_cndmask_b32_e64 v107, v75, v107, s[42:43]
	v_lshlrev_b32_e32 v216, 16, v108
	v_and_b32_e32 v217, 0xffff0000, v108
	v_lshlrev_b32_e32 v218, 16, v109
	v_and_b32_e32 v219, 0xffff0000, v109
	v_lshlrev_b32_e32 v220, 16, v110
	v_and_b32_e32 v221, 0xffff0000, v110
	v_lshlrev_b32_e32 v222, 16, v111
	v_and_b32_e32 v223, 0xffff0000, v111
	v_pk_mul_f32 v[44:45], v[44:45], v[216:217]
	v_pk_mul_f32 v[46:47], v[46:47], v[218:219]
	v_pk_mul_f32 v[40:41], v[40:41], v[220:221]
	v_pk_mul_f32 v[42:43], v[42:43], v[222:223]
	v_lshlrev_b32_e32 v216, 16, v232
	v_and_b32_e32 v217, 0xffff0000, v232
	v_lshlrev_b32_e32 v218, 16, v233
	v_and_b32_e32 v219, 0xffff0000, v233
	v_lshlrev_b32_e32 v220, 16, v234
	v_and_b32_e32 v221, 0xffff0000, v234
	v_lshlrev_b32_e32 v222, 16, v235
	v_and_b32_e32 v223, 0xffff0000, v235
	v_pk_add_f32 v[44:45], v[44:45], v[216:217]
	v_pk_add_f32 v[46:47], v[46:47], v[218:219]
	v_pk_add_f32 v[40:41], v[40:41], v[220:221]
	v_pk_add_f32 v[42:43], v[42:43], v[222:223]
	v_cvt_pk_bf16_f32 v108, v44, v45
	v_cvt_pk_bf16_f32 v109, v46, v47
	v_cvt_pk_bf16_f32 v110, v40, v41
	v_cvt_pk_bf16_f32 v111, v42, v43
	v_mov_b32_dpp v72, v104 row_ror:8 row_mask:0xf bank_mask:0xf
	v_mov_b32_dpp v73, v105 row_ror:8 row_mask:0xf bank_mask:0xf
	v_mov_b32_dpp v74, v106 row_ror:8 row_mask:0xf bank_mask:0xf
	v_mov_b32_dpp v75, v107 row_ror:8 row_mask:0xf bank_mask:0xf
	v_lshlrev_b32_e32 v216, 16, v76
	v_and_b32_e32 v217, 0xffff0000, v76
	v_lshlrev_b32_e32 v218, 16, v77
	v_and_b32_e32 v219, 0xffff0000, v77
	v_lshlrev_b32_e32 v220, 16, v78
	v_and_b32_e32 v221, 0xffff0000, v78
	v_lshlrev_b32_e32 v222, 16, v79
	v_and_b32_e32 v223, 0xffff0000, v79
	v_pk_mul_f32 v[12:13], v[12:13], v[216:217]
	v_pk_mul_f32 v[14:15], v[14:15], v[218:219]
	v_pk_mul_f32 v[8:9], v[8:9], v[220:221]
	v_pk_mul_f32 v[10:11], v[10:11], v[222:223]
	v_lshlrev_b32_e32 v216, 16, v72
	v_and_b32_e32 v217, 0xffff0000, v72
	v_lshlrev_b32_e32 v218, 16, v73
	v_and_b32_e32 v219, 0xffff0000, v73
	v_lshlrev_b32_e32 v220, 16, v74
	v_and_b32_e32 v221, 0xffff0000, v74
	v_lshlrev_b32_e32 v222, 16, v75
	v_and_b32_e32 v223, 0xffff0000, v75
	v_pk_add_f32 v[12:13], v[12:13], v[216:217]
	v_pk_add_f32 v[14:15], v[14:15], v[218:219]
	v_pk_add_f32 v[8:9], v[8:9], v[220:221]
	v_pk_add_f32 v[10:11], v[10:11], v[222:223]
	v_cvt_pk_bf16_f32 v76, v12, v13
	v_cvt_pk_bf16_f32 v77, v14, v15
	v_cvt_pk_bf16_f32 v78, v8, v9
	v_cvt_pk_bf16_f32 v79, v10, v11
	s_waitcnt vmcnt(8)
; __device__ __forceinline__ u32x4 pack8(const f32x4& a, const f32x4& b) { u32x4 w; w.x = pk2(a[0], a[1]); w.y = pk2(a[2], a[3]); w.z = pk2(b[0], b[1]); w.w = pk2(b[2], b[3]); return w; }
; __device__ __forceinline__ void unpack8(const u32x4& w, f32x4& a, f32x4& b) { a[0] = bflo(w.x); a[1] = bfhi(w.x); a[2] = bflo(w.y); a[3] = bfhi(w.y); b[0] = bflo(w.z); b[1] = bfhi(w.z); b[2] = bflo(w.w); b[3] = bfhi(w.w); }
;     __device__ __forceinline__ void operator()(const f32x4 (&acc)[2][2][4][2], const Unit& u, int wr, int wc, int fr, int fq) const {
;     ...
;                     for (int bj = 0; bj < 2; ++bj) { gw[m][bj] = *(const u32x4*)(tmpb + ((ai * 4 + m) * 2 + bj) * 8192 + voff);
;                         if (br > 0) pw[m][bj] = *(const u32x4*)(MRG + (size_t)(lrow0 + ai * HALF + m * 16) * 1024 + col0 + 128 * bj); }
; #pragma unroll
;                 for (int m = 0; m < 4; ++m)
; #pragma unroll
;                     for (int bj = 0; bj < 2; ++bj) { f32x4 g0, g1; unpack8(gw[m][bj], g0, g1);
;                         f32x4 v0 = acc[ai][bj][m][0] * g0, v1 = acc[ai][bj][m][1] * g1;
;                         if (br > 0) { f32x4 p0, p1; unpack8(pw[m][bj], p0, p1); v0 += p0; v1 += p1; }
;                         *(u32x4*)(MRG + (size_t)(lrow0 + ai * HALF + m * 16) * 1024 + col0 + 128 * bj) = pack8(v0, v1); }
	v_cndmask_b32_e64 v232, v96, v64, s[42:43]
	v_cndmask_b32_e64 v233, v97, v65, s[42:43]
	v_cndmask_b32_e64 v234, v98, v66, s[42:43]
	v_cndmask_b32_e64 v235, v99, v67, s[42:43]
	v_cndmask_b32_e64 v96, v64, v96, s[42:43]
	v_cndmask_b32_e64 v97, v65, v97, s[42:43]
	v_cndmask_b32_e64 v98, v66, v98, s[42:43]
	v_cndmask_b32_e64 v99, v67, v99, s[42:43]
	v_lshlrev_b32_e32 v216, 16, v100
	v_and_b32_e32 v217, 0xffff0000, v100
	v_lshlrev_b32_e32 v218, 16, v101
	v_and_b32_e32 v219, 0xffff0000, v101
	v_lshlrev_b32_e32 v220, 16, v102
	v_and_b32_e32 v221, 0xffff0000, v102
	v_lshlrev_b32_e32 v222, 16, v103
	v_and_b32_e32 v223, 0xffff0000, v103
	v_pk_mul_f32 v[36:37], v[36:37], v[216:217]
	v_pk_mul_f32 v[38:39], v[38:39], v[218:219]
	v_pk_mul_f32 v[32:33], v[32:33], v[220:221]
	v_pk_mul_f32 v[34:35], v[34:35], v[222:223]
	v_lshlrev_b32_e32 v216, 16, v232
	v_and_b32_e32 v217, 0xffff0000, v232
	v_lshlrev_b32_e32 v218, 16, v233
	v_and_b32_e32 v219, 0xffff0000, v233
	v_lshlrev_b32_e32 v220, 16, v234
	v_and_b32_e32 v221, 0xffff0000, v234
	v_lshlrev_b32_e32 v222, 16, v235
	v_and_b32_e32 v223, 0xffff0000, v235
	v_pk_add_f32 v[36:37], v[36:37], v[216:217]
	v_pk_add_f32 v[38:39], v[38:39], v[218:219]
	v_pk_add_f32 v[32:33], v[32:33], v[220:221]
	v_pk_add_f32 v[34:35], v[34:35], v[222:223]
	v_cvt_pk_bf16_f32 v100, v36, v37
	v_cvt_pk_bf16_f32 v101, v38, v39
	v_cvt_pk_bf16_f32 v102, v32, v33
	v_cvt_pk_bf16_f32 v103, v34, v35
	v_mov_b32_dpp v64, v96 row_ror:8 row_mask:0xf bank_mask:0xf
	v_mov_b32_dpp v65, v97 row_ror:8 row_mask:0xf bank_mask:0xf
	v_mov_b32_dpp v66, v98 row_ror:8 row_mask:0xf bank_mask:0xf
	v_mov_b32_dpp v67, v99 row_ror:8 row_mask:0xf bank_mask:0xf
	v_lshlrev_b32_e32 v216, 16, v68
	v_and_b32_e32 v217, 0xffff0000, v68
	v_lshlrev_b32_e32 v218, 16, v69
	v_and_b32_e32 v219, 0xffff0000, v69
	v_lshlrev_b32_e32 v220, 16, v70
	v_and_b32_e32 v221, 0xffff0000, v70
	v_lshlrev_b32_e32 v222, 16, v71
	v_and_b32_e32 v223, 0xffff0000, v71
	v_pk_mul_f32 v[4:5], v[4:5], v[216:217]
	v_pk_mul_f32 v[6:7], v[6:7], v[218:219]
	v_pk_mul_f32 v[0:1], v[0:1], v[220:221]
	v_pk_mul_f32 v[2:3], v[2:3], v[222:223]
	v_lshlrev_b32_e32 v216, 16, v64
	v_and_b32_e32 v217, 0xffff0000, v64
	v_lshlrev_b32_e32 v218, 16, v65
	v_and_b32_e32 v219, 0xffff0000, v65
	v_lshlrev_b32_e32 v220, 16, v66
	v_and_b32_e32 v221, 0xffff0000, v66
	v_lshlrev_b32_e32 v222, 16, v67
	v_and_b32_e32 v223, 0xffff0000, v67
	v_pk_add_f32 v[4:5], v[4:5], v[216:217]
	v_pk_add_f32 v[6:7], v[6:7], v[218:219]
	v_pk_add_f32 v[0:1], v[0:1], v[220:221]
	v_pk_add_f32 v[2:3], v[2:3], v[222:223]
	v_cvt_pk_bf16_f32 v68, v4, v5
	v_cvt_pk_bf16_f32 v69, v6, v7
	v_cvt_pk_bf16_f32 v70, v0, v1
	v_cvt_pk_bf16_f32 v71, v2, v3
	s_mov_b64 s[10:11], 0x50000
	v_lshl_add_u64 v[224:225], v[212:213], 0, s[10:11]
	s_mov_b64 s[10:11], 0x50000
	v_lshl_add_u64 v[250:251], v[252:253], 0, s[10:11]
	v_mov_b32_dpp v232, v76 row_ror:8 row_mask:0xf bank_mask:0xf
	v_mov_b32_dpp v233, v77 row_ror:8 row_mask:0xf bank_mask:0xf
	v_mov_b32_dpp v234, v78 row_ror:8 row_mask:0xf bank_mask:0xf
	v_mov_b32_dpp v235, v79 row_ror:8 row_mask:0xf bank_mask:0xf
	v_cndmask_b32_e64 v76, v108, v232, s[42:43]
	v_cndmask_b32_e64 v77, v109, v233, s[42:43]
	v_cndmask_b32_e64 v78, v110, v234, s[42:43]
	v_cndmask_b32_e64 v79, v111, v235, s[42:43]
	v_cndmask_b32_e64 v232, v232, v108, s[42:43]
	v_cndmask_b32_e64 v233, v233, v109, s[42:43]
	v_cndmask_b32_e64 v234, v234, v110, s[42:43]
	v_cndmask_b32_e64 v235, v235, v111, s[42:43]
	global_store_dwordx4 v[224:225], v[76:79], off
	global_store_dwordx4 v[250:251], v[232:235], off
	s_mov_b64 s[10:11], 0x58000
	v_lshl_add_u64 v[224:225], v[212:213], 0, s[10:11]
	s_mov_b64 s[10:11], 0x58000
	v_lshl_add_u64 v[250:251], v[252:253], 0, s[10:11]
	v_mov_b32_dpp v232, v68 row_ror:8 row_mask:0xf bank_mask:0xf
	v_mov_b32_dpp v233, v69 row_ror:8 row_mask:0xf bank_mask:0xf
	v_mov_b32_dpp v234, v70 row_ror:8 row_mask:0xf bank_mask:0xf
	v_mov_b32_dpp v235, v71 row_ror:8 row_mask:0xf bank_mask:0xf
	v_cndmask_b32_e64 v68, v100, v232, s[42:43]
	v_cndmask_b32_e64 v69, v101, v233, s[42:43]
	v_cndmask_b32_e64 v70, v102, v234, s[42:43]
	v_cndmask_b32_e64 v71, v103, v235, s[42:43]
	v_cndmask_b32_e64 v232, v232, v100, s[42:43]
	v_cndmask_b32_e64 v233, v233, v101, s[42:43]
	v_cndmask_b32_e64 v234, v234, v102, s[42:43]
	v_cndmask_b32_e64 v235, v235, v103, s[42:43]
	global_store_dwordx4 v[224:225], v[68:71], off
	global_store_dwordx4 v[250:251], v[232:235], off
	s_nop 1

; __device__ __forceinline__ float row_rstd(const float* ssp, int row, int fq) {
;     const f32x4 t = *((const f32x4*)(ssp + (size_t)row * 16) + fq); float s = (t[0] + t[1]) + (t[2] + t[3]); s += __shfl_xor(s, 16); s += __shfl_xor(s, 32); return rsqrtf(s * (1.0f / DM) + EPS); }
;     __device__ __forceinline__ void operator()(const f32x4 (&acc)[2][2][4][2], const Unit& u, int wr, int wc, int fr, int fq) const {
;     ...
;             float rx[2][4];
; #pragma unroll
;             for (int ai = 0; ai < 2; ++ai)
; #pragma unroll
;                 for (int m = 0; m < 4; ++m) rx[ai][m] = row_rstd(ssp, row0 + ai * HALF + m * 16, fq);
.LBB0_558:
	s_and_b64 vcc, exec, s[18:19]
	s_cbranch_vccz .LBB0_560
	v_and_b32_e32 v129, 64, v229
	v_xor_b32_e32 v128, 16, v229
	v_add_u32_e32 v129, 64, v129
	v_cmp_lt_i32_e32 vcc, v128, v129
	v_ashrrev_i32_e32 v211, 31, v210
	s_mov_b32 s10, 0x358637bd
	v_cndmask_b32_e32 v128, v229, v128, vcc
	v_lshlrev_b32_e32 v140, 2, v128
	v_xor_b32_e32 v128, 32, v229
	v_cmp_lt_i32_e32 vcc, v128, v129
	v_mov_b32_e32 v209, v193
	s_nop 0
	v_cndmask_b32_e32 v128, v229, v128, vcc
	v_lshlrev_b32_e32 v141, 2, v128
	v_lshlrev_b64 v[128:129], 6, v[210:211]
	v_lshl_add_u64 v[130:131], v[202:203], 0, v[128:129]
	global_load_dwordx4 v[156:159], v[130:131], off
	global_load_dwordx4 v[160:163], v[130:131], off offset:1024
	global_load_dwordx4 v[164:167], v[130:131], off offset:2048
	global_load_dwordx4 v[168:171], v[130:131], off offset:3072
	v_add_co_u32_e32 v188, vcc, 0x2000, v130
	s_nop 1
	v_addc_co_u32_e32 v189, vcc, 0, v131, vcc
	global_load_dwordx4 v[172:175], v[188:189], off
	global_load_dwordx4 v[176:179], v[188:189], off offset:1024
	global_load_dwordx4 v[180:183], v[188:189], off offset:2048
	global_load_dwordx4 v[184:187], v[188:189], off offset:3072
	s_waitcnt vmcnt(7)
	v_mov_b32_e32 v128, v157
	v_mov_b32_e32 v129, v158
	v_mov_b32_e32 v157, v159
	v_pk_add_f32 v[128:129], v[128:129], v[156:157]
	s_waitcnt vmcnt(6)
	v_mov_b32_e32 v136, v161
	v_mov_b32_e32 v137, v162
	v_mov_b32_e32 v161, v163
	v_pk_add_f32 v[132:133], v[136:137], v[160:161]
	v_mov_b32_e32 v135, v128
	v_mov_b32_e32 v134, v132
	v_mov_b32_e32 v128, v133
	v_pk_add_f32 v[128:129], v[134:135], v[128:129]
	ds_bpermute_b32 v133, v140, v129
	ds_bpermute_b32 v132, v140, v128
	s_waitcnt lgkmcnt(0)
	v_pk_add_f32 v[128:129], v[128:129], v[132:133]
	ds_bpermute_b32 v133, v141, v129
	ds_bpermute_b32 v132, v141, v128
	s_waitcnt lgkmcnt(0)
	v_pk_add_f32 v[132:133], v[128:129], v[132:133]
	v_mov_b64_e32 v[128:129], s[10:11]
	v_pk_fma_f32 v[132:133], v[132:133], s[38:39], v[128:129] op_sel_hi:[1,0,0]
	s_and_b32 s10, 0xffff, s52
	v_mul_f32_e32 v134, 0x4b800000, v133
	v_cmp_gt_f32_e64 s[42:43], s99, v133
	v_cmp_gt_f32_e32 vcc, s99, v132
	s_lshl_b32 s10, s10, 12
	v_cndmask_b32_e64 v133, v133, v134, s[42:43]
	v_rsq_f32_e32 v133, v133
	s_add_u32 s10, s63, s10
	s_addc_u32 s11, s64, 0
	v_mul_f32_e32 v134, 0x45800000, v133
	v_cndmask_b32_e64 v147, v133, v134, s[42:43]
	v_mul_f32_e32 v133, 0x4b800000, v132
	v_cndmask_b32_e32 v132, v132, v133, vcc
	v_rsq_f32_e32 v132, v132
	s_nop 0
	v_mul_f32_e32 v133, 0x45800000, v132
	v_cndmask_b32_e32 v145, v132, v133, vcc
	s_waitcnt vmcnt(5)
	v_mov_b32_e32 v136, v165
	v_mov_b32_e32 v137, v166
	v_mov_b32_e32 v165, v167
	v_pk_add_f32 v[136:137], v[136:137], v[164:165]
	s_waitcnt vmcnt(4)
	v_mov_b32_e32 v138, v169
	v_mov_b32_e32 v139, v170
	v_mov_b32_e32 v169, v171
	v_pk_add_f32 v[132:133], v[138:139], v[168:169]
	v_mov_b32_e32 v135, v136
	v_mov_b32_e32 v134, v132
	v_mov_b32_e32 v136, v133
	v_pk_add_f32 v[132:133], v[134:135], v[136:137]
	ds_bpermute_b32 v135, v140, v133
	ds_bpermute_b32 v134, v140, v132
	s_waitcnt lgkmcnt(0)
	v_pk_add_f32 v[132:133], v[132:133], v[134:135]
	ds_bpermute_b32 v135, v141, v133
	ds_bpermute_b32 v134, v141, v132
	s_waitcnt lgkmcnt(0)
	v_pk_add_f32 v[132:133], v[132:133], v[134:135]
	s_nop 0
	v_pk_fma_f32 v[132:133], v[132:133], s[38:39], v[128:129] op_sel_hi:[1,0,0]
	s_nop 0
	v_mul_f32_e32 v134, 0x4b800000, v133
	v_cmp_gt_f32_e64 s[42:43], s99, v133
	v_cmp_gt_f32_e32 vcc, s99, v132
	s_nop 0
	v_cndmask_b32_e64 v133, v133, v134, s[42:43]
	v_rsq_f32_e32 v133, v133
	s_nop 0
	v_mul_f32_e32 v134, 0x45800000, v133
	v_cndmask_b32_e64 v146, v133, v134, s[42:43]
	v_mul_f32_e32 v133, 0x4b800000, v132
	v_cndmask_b32_e32 v132, v132, v133, vcc
	v_rsq_f32_e32 v132, v132
	s_nop 0
	v_mul_f32_e32 v133, 0x45800000, v132
	v_cndmask_b32_e32 v143, v132, v133, vcc
	s_waitcnt vmcnt(3)
	v_mov_b32_e32 v136, v173
	v_mov_b32_e32 v137, v174
	v_mov_b32_e32 v173, v175
	v_pk_add_f32 v[136:137], v[136:137], v[172:173]
	s_waitcnt vmcnt(2)
	v_mov_b32_e32 v138, v177
	v_mov_b32_e32 v139, v178
	v_mov_b32_e32 v177, v179
	v_pk_add_f32 v[130:131], v[138:139], v[176:177]
	v_mov_b32_e32 v133, v136
	v_mov_b32_e32 v132, v130
	v_mov_b32_e32 v136, v131
	v_pk_add_f32 v[130:131], v[132:133], v[136:137]
	ds_bpermute_b32 v133, v140, v131
	ds_bpermute_b32 v132, v140, v130
	v_lshl_add_u64 v[138:139], v[208:209], 2, s[10:11]
	s_mov_b32 s10, 0x8000
	s_waitcnt lgkmcnt(0)
	v_pk_add_f32 v[130:131], v[130:131], v[132:133]
	ds_bpermute_b32 v133, v141, v131
	ds_bpermute_b32 v132, v141, v130
	s_waitcnt lgkmcnt(0)
	v_pk_add_f32 v[130:131], v[130:131], v[132:133]
	s_nop 0
	v_pk_fma_f32 v[130:131], v[130:131], s[38:39], v[128:129] op_sel_hi:[1,0,0]
	s_nop 0
	v_mul_f32_e32 v132, 0x4b800000, v131
	v_cmp_gt_f32_e64 s[42:43], s99, v131
	v_cmp_gt_f32_e32 vcc, s99, v130
	s_nop 0
	v_cndmask_b32_e64 v131, v131, v132, s[42:43]
	v_rsq_f32_e32 v131, v131
	s_nop 0
	v_mul_f32_e32 v132, 0x45800000, v131
	v_cndmask_b32_e64 v144, v131, v132, s[42:43]
	v_mul_f32_e32 v131, 0x4b800000, v130
	v_cndmask_b32_e32 v130, v130, v131, vcc
	v_rsq_f32_e32 v130, v130
	s_nop 0
	v_mul_f32_e32 v131, 0x45800000, v130
	v_cndmask_b32_e32 v142, v130, v131, vcc
	s_waitcnt vmcnt(1)
	v_mov_b32_e32 v136, v181
	v_mov_b32_e32 v137, v182
	v_mov_b32_e32 v181, v183
	v_pk_add_f32 v[136:137], v[136:137], v[180:181]
	s_waitcnt vmcnt(0)
	v_mov_b32_e32 v134, v185
	v_mov_b32_e32 v135, v186
	v_mov_b32_e32 v185, v187
	v_pk_add_f32 v[130:131], v[134:135], v[184:185]
	v_mov_b32_e32 v133, v136
	v_mov_b32_e32 v132, v130
	v_mov_b32_e32 v136, v131
	v_pk_add_f32 v[130:131], v[132:133], v[136:137]
	ds_bpermute_b32 v133, v140, v131
	ds_bpermute_b32 v132, v140, v130
	v_lshl_add_u64 v[136:137], s[30:31], 0, v[192:193]
	s_waitcnt lgkmcnt(0)
; __device__ __forceinline__ u32x4 pack8(const f32x4& a, const f32x4& b) { u32x4 w; w.x = pk2(a[0], a[1]); w.y = pk2(a[2], a[3]); w.z = pk2(b[0], b[1]); w.w = pk2(b[2], b[3]); return w; }
; __device__ __forceinline__ float sigm(float x) { return __builtin_amdgcn_rcpf(1.0f + __builtin_amdgcn_exp2f(x * -1.4426950408889634f)); }
;     __device__ __forceinline__ void operator()(const f32x4 (&acc)[2][2][4][2], const Unit& u, int wr, int wc, int fr, int fq) const {
;     ...
; #pragma unroll
;             for (int bj = 0; bj < 2; ++bj) {
;                 const f32x4 bv0 = *(const f32x4*)(gb + br * 1024 + col0 + 128 * bj), bv1 = *(const f32x4*)(gb + br * 1024 + col0 + 128 * bj + 4);
; #pragma unroll
;                 for (int ai = 0; ai < 2; ++ai)
; #pragma unroll
;                     for (int m = 0; m < 4; ++m) {
;                         const f32x4 a0 = acc[ai][bj][m][0] * rx[ai][m] + bv0, a1 = acc[ai][bj][m][1] * rx[ai][m] + bv1; f32x4 o0, o1;
; #pragma unroll
;                         for (int e = 0; e < 4; ++e) { o0[e] = sigm(a0[e]); o1[e] = sigm(a1[e]); }
;                         *(u32x4*)(tmpb + ((ai * 4 + m) * 2 + bj) * 8192 + voff) = pack8(o0, o1); }
;                 asm volatile("" ::: "memory"); }
	v_pk_add_f32 v[130:131], v[130:131], v[132:133]
	ds_bpermute_b32 v133, v141, v131
	ds_bpermute_b32 v132, v141, v130
	s_waitcnt lgkmcnt(0)
	v_pk_add_f32 v[130:131], v[130:131], v[132:133]
	s_nop 0
	v_pk_fma_f32 v[128:129], v[130:131], s[38:39], v[128:129] op_sel_hi:[1,0,0]
	s_nop 0
	v_mul_f32_e32 v130, 0x4b800000, v129
	v_cmp_gt_f32_e64 s[42:43], s99, v129
	v_cmp_gt_f32_e32 vcc, s99, v128
	s_nop 0
	v_cndmask_b32_e64 v129, v129, v130, s[42:43]
	v_rsq_f32_e32 v129, v129
	s_nop 0
	v_mul_f32_e32 v130, 0x45800000, v129
	v_cndmask_b32_e64 v141, v129, v130, s[42:43]
	v_mul_f32_e32 v129, 0x4b800000, v128
	v_cndmask_b32_e32 v128, v128, v129, vcc
	v_rsq_f32_e32 v128, v128
	s_nop 0
	v_mul_f32_e32 v129, 0x45800000, v128
	v_cndmask_b32_e32 v140, v128, v129, vcc
	global_load_dwordx4 v[128:131], v[138:139], off offset:16
	global_load_dwordx4 v[132:135], v[138:139], off
	global_load_dwordx4 v[156:159], v[138:139], off offset:144
	global_load_dwordx4 v[160:163], v[138:139], off offset:128
	s_waitcnt vmcnt(3)
	v_fma_f32 v149, v120, v147, v128
	v_mul_f32_e32 v149, 0xbfb8aa3b, v149
	v_exp_f32_e32 v149, v149
	s_waitcnt vmcnt(2)
	v_fma_f32 v148, v124, v147, v132
	v_fma_f32 v151, v121, v147, v129
	v_fma_f32 v152, v126, v147, v134
	v_add_f32_e32 v149, 1.0, v149
	v_rcp_f32_e32 v150, v149
	v_fma_f32 v149, v125, v147, v133
	v_fma_f32 v153, v122, v147, v130
	v_fma_f32 v154, v127, v147, v135
	v_fma_f32 v155, v123, v147, v131
	v_mul_f32_e32 v148, 0xbfb8aa3b, v148
	v_mul_f32_e32 v149, 0xbfb8aa3b, v149
	v_mul_f32_e32 v151, 0xbfb8aa3b, v151
	v_mul_f32_e32 v152, 0xbfb8aa3b, v152
	v_mul_f32_e32 v153, 0xbfb8aa3b, v153
	v_mul_f32_e32 v154, 0xbfb8aa3b, v154
	v_mul_f32_e32 v155, 0xbfb8aa3b, v155
	v_exp_f32_e32 v148, v148
	v_exp_f32_e32 v149, v149
	v_exp_f32_e32 v151, v151
	v_exp_f32_e32 v152, v152
	v_exp_f32_e32 v153, v153
	v_exp_f32_e32 v154, v154
	v_exp_f32_e32 v155, v155
	v_add_f32_e32 v148, 1.0, v148
	v_add_f32_e32 v149, 1.0, v149
	v_add_f32_e32 v151, 1.0, v151
	v_add_f32_e32 v152, 1.0, v152
	v_add_f32_e32 v153, 1.0, v153
	v_add_f32_e32 v154, 1.0, v154
	v_add_f32_e32 v155, 1.0, v155
	v_rcp_f32_e32 v148, v148
	v_rcp_f32_e32 v149, v149
	v_rcp_f32_e32 v151, v151
	v_rcp_f32_e32 v152, v152
	v_rcp_f32_e32 v153, v153
	v_rcp_f32_e32 v154, v154
	v_rcp_f32_e32 v155, v155
	v_cvt_pk_bf16_f32 v148, v148, v149
	v_cvt_pk_bf16_f32 v150, v150, v151
	v_cvt_pk_bf16_f32 v149, v152, v154
	v_cvt_pk_bf16_f32 v151, v153, v155
	global_store_dwordx4 v192, v[148:151], s[30:31]
	v_fma_f32 v152, v118, v145, v134
	v_fma_f32 v154, v119, v145, v135
	v_fma_f32 v149, v112, v145, v128
	v_mul_f32_e32 v149, 0xbfb8aa3b, v149
	v_exp_f32_e32 v149, v149
	v_fma_f32 v148, v116, v145, v132
	v_mul_f32_e32 v148, 0xbfb8aa3b, v148
	v_fma_f32 v151, v113, v145, v129
	v_add_f32_e32 v149, 1.0, v149
	v_rcp_f32_e32 v150, v149
	v_fma_f32 v149, v117, v145, v133
	v_mul_f32_e32 v149, 0xbfb8aa3b, v149
	v_mul_f32_e32 v152, 0xbfb8aa3b, v152
	v_fma_f32 v153, v114, v145, v130
	v_mul_f32_e32 v154, 0xbfb8aa3b, v154
	v_fma_f32 v155, v115, v145, v131
	v_exp_f32_e32 v148, v148
	v_exp_f32_e32 v149, v149
	v_mul_f32_e32 v151, 0xbfb8aa3b, v151
	v_exp_f32_e32 v152, v152
	v_mul_f32_e32 v153, 0xbfb8aa3b, v153
	v_exp_f32_e32 v154, v154
	v_mul_f32_e32 v155, 0xbfb8aa3b, v155
	v_exp_f32_e32 v151, v151
	v_exp_f32_e32 v153, v153
	v_exp_f32_e32 v155, v155
	v_add_f32_e32 v148, 1.0, v148
	v_add_f32_e32 v149, 1.0, v149
	v_add_f32_e32 v152, 1.0, v152
	v_add_f32_e32 v154, 1.0, v154
	v_rcp_f32_e32 v148, v148
	v_rcp_f32_e32 v149, v149
	v_add_f32_e32 v151, 1.0, v151
	v_rcp_f32_e32 v152, v152
	v_add_f32_e32 v153, 1.0, v153
	v_rcp_f32_e32 v154, v154
	v_add_f32_e32 v155, 1.0, v155
	v_rcp_f32_e32 v151, v151
	v_rcp_f32_e32 v153, v153
	v_rcp_f32_e32 v155, v155
	v_cvt_pk_bf16_f32 v148, v148, v149
	v_cvt_pk_bf16_f32 v149, v152, v154
	v_add_co_u32_e32 v152, vcc, s83, v136
	v_cvt_pk_bf16_f32 v150, v150, v151
	v_cvt_pk_bf16_f32 v151, v153, v155
	v_addc_co_u32_e32 v153, vcc, 0, v137, vcc
	global_store_dwordx4 v[152:153], v[148:151], off
	v_fma_f32 v152, v110, v146, v134
	v_fma_f32 v154, v111, v146, v135
	v_fma_f32 v149, v104, v146, v128
	v_mul_f32_e32 v149, 0xbfb8aa3b, v149
	v_exp_f32_e32 v149, v149
	v_fma_f32 v148, v108, v146, v132
	v_mul_f32_e32 v148, 0xbfb8aa3b, v148
	v_fma_f32 v151, v105, v146, v129
	v_add_f32_e32 v149, 1.0, v149
	v_rcp_f32_e32 v150, v149
	v_fma_f32 v149, v109, v146, v133
	v_mul_f32_e32 v149, 0xbfb8aa3b, v149
	v_mul_f32_e32 v152, 0xbfb8aa3b, v152
	v_fma_f32 v153, v106, v146, v130
	v_mul_f32_e32 v154, 0xbfb8aa3b, v154
	v_fma_f32 v155, v107, v146, v131
	v_exp_f32_e32 v148, v148
	v_exp_f32_e32 v149, v149
	v_mul_f32_e32 v151, 0xbfb8aa3b, v151
	v_exp_f32_e32 v152, v152
	v_mul_f32_e32 v153, 0xbfb8aa3b, v153
	v_exp_f32_e32 v154, v154
	v_mul_f32_e32 v155, 0xbfb8aa3b, v155
	v_exp_f32_e32 v151, v151
	v_exp_f32_e32 v153, v153
	v_exp_f32_e32 v155, v155
	v_add_f32_e32 v148, 1.0, v148
	v_add_f32_e32 v149, 1.0, v149
	v_add_f32_e32 v152, 1.0, v152
	v_add_f32_e32 v154, 1.0, v154
	v_rcp_f32_e32 v148, v148
	v_rcp_f32_e32 v149, v149
	v_add_f32_e32 v151, 1.0, v151
	v_rcp_f32_e32 v152, v152
	v_add_f32_e32 v153, 1.0, v153
	v_rcp_f32_e32 v154, v154
	v_add_f32_e32 v155, 1.0, v155
	v_rcp_f32_e32 v151, v151
	v_rcp_f32_e32 v153, v153
	v_rcp_f32_e32 v155, v155
	v_cvt_pk_bf16_f32 v148, v148, v149
	v_cvt_pk_bf16_f32 v149, v152, v154
	v_add_co_u32_e32 v152, vcc, s10, v136
	v_cvt_pk_bf16_f32 v150, v150, v151
	v_cvt_pk_bf16_f32 v151, v153, v155
	v_addc_co_u32_e32 v153, vcc, 0, v137, vcc
	global_store_dwordx4 v[152:153], v[148:151], off
	v_fma_f32 v152, v102, v143, v134
	v_fma_f32 v154, v103, v143, v135
	v_fma_f32 v149, v96, v143, v128
	v_mul_f32_e32 v149, 0xbfb8aa3b, v149
; __device__ __forceinline__ u32x4 pack8(const f32x4& a, const f32x4& b) { u32x4 w; w.x = pk2(a[0], a[1]); w.y = pk2(a[2], a[3]); w.z = pk2(b[0], b[1]); w.w = pk2(b[2], b[3]); return w; }
; __device__ __forceinline__ float sigm(float x) { return __builtin_amdgcn_rcpf(1.0f + __builtin_amdgcn_exp2f(x * -1.4426950408889634f)); }
;     __device__ __forceinline__ void operator()(const f32x4 (&acc)[2][2][4][2], const Unit& u, int wr, int wc, int fr, int fq) const {
;     ...
;             for (int bj = 0; bj < 2; ++bj) {
;                 const f32x4 bv0 = *(const f32x4*)(gb + br * 1024 + col0 + 128 * bj), bv1 = *(const f32x4*)(gb + br * 1024 + col0 + 128 * bj + 4);
; #pragma unroll
;                 for (int ai = 0; ai < 2; ++ai)
; #pragma unroll
;                     for (int m = 0; m < 4; ++m) {
;                         const f32x4 a0 = acc[ai][bj][m][0] * rx[ai][m] + bv0, a1 = acc[ai][bj][m][1] * rx[ai][m] + bv1; f32x4 o0, o1;
; #pragma unroll
;                         for (int e = 0; e < 4; ++e) { o0[e] = sigm(a0[e]); o1[e] = sigm(a1[e]); }
;                         *(u32x4*)(tmpb + ((ai * 4 + m) * 2 + bj) * 8192 + voff) = pack8(o0, o1); }
;                 asm volatile("" ::: "memory"); }
	v_exp_f32_e32 v149, v149
	v_fma_f32 v148, v100, v143, v132
	v_mul_f32_e32 v148, 0xbfb8aa3b, v148
	v_fma_f32 v151, v97, v143, v129
	v_add_f32_e32 v149, 1.0, v149
	v_rcp_f32_e32 v150, v149
	v_fma_f32 v149, v101, v143, v133
	v_mul_f32_e32 v149, 0xbfb8aa3b, v149
	v_mul_f32_e32 v152, 0xbfb8aa3b, v152
	v_fma_f32 v153, v98, v143, v130
	v_mul_f32_e32 v154, 0xbfb8aa3b, v154
	v_fma_f32 v155, v99, v143, v131
	v_exp_f32_e32 v148, v148
	v_exp_f32_e32 v149, v149
	v_mul_f32_e32 v151, 0xbfb8aa3b, v151
	v_exp_f32_e32 v152, v152
	v_mul_f32_e32 v153, 0xbfb8aa3b, v153
	v_exp_f32_e32 v154, v154
	v_mul_f32_e32 v155, 0xbfb8aa3b, v155
	v_exp_f32_e32 v151, v151
	v_exp_f32_e32 v153, v153
	v_exp_f32_e32 v155, v155
	v_add_f32_e32 v148, 1.0, v148
	v_add_f32_e32 v149, 1.0, v149
	v_add_f32_e32 v152, 1.0, v152
	v_add_f32_e32 v154, 1.0, v154
	v_rcp_f32_e32 v148, v148
	v_rcp_f32_e32 v149, v149
	v_add_f32_e32 v151, 1.0, v151
	v_rcp_f32_e32 v152, v152
	v_add_f32_e32 v153, 1.0, v153
	v_rcp_f32_e32 v154, v154
	v_add_f32_e32 v155, 1.0, v155
	v_rcp_f32_e32 v151, v151
	v_rcp_f32_e32 v153, v153
	v_rcp_f32_e32 v155, v155
	s_mov_b32 s10, 0xc000
	v_cvt_pk_bf16_f32 v148, v148, v149
	v_cvt_pk_bf16_f32 v149, v152, v154
	v_add_co_u32_e32 v152, vcc, s10, v136
	v_cvt_pk_bf16_f32 v150, v150, v151
	v_cvt_pk_bf16_f32 v151, v153, v155
	v_addc_co_u32_e32 v153, vcc, 0, v137, vcc
	global_store_dwordx4 v[152:153], v[148:151], off
	v_fma_f32 v152, v62, v144, v134
	v_fma_f32 v154, v63, v144, v135
	v_fma_f32 v149, v56, v144, v128
	v_mul_f32_e32 v149, 0xbfb8aa3b, v149
	v_exp_f32_e32 v149, v149
	v_fma_f32 v148, v60, v144, v132
	v_mul_f32_e32 v148, 0xbfb8aa3b, v148
	v_fma_f32 v151, v57, v144, v129
	v_add_f32_e32 v149, 1.0, v149
	v_rcp_f32_e32 v150, v149
	v_fma_f32 v149, v61, v144, v133
	v_mul_f32_e32 v149, 0xbfb8aa3b, v149
	v_mul_f32_e32 v152, 0xbfb8aa3b, v152
	v_fma_f32 v153, v58, v144, v130
	v_mul_f32_e32 v154, 0xbfb8aa3b, v154
	v_fma_f32 v155, v59, v144, v131
	v_exp_f32_e32 v148, v148
	v_exp_f32_e32 v149, v149
	v_mul_f32_e32 v151, 0xbfb8aa3b, v151
	v_exp_f32_e32 v152, v152
	v_mul_f32_e32 v153, 0xbfb8aa3b, v153
	v_exp_f32_e32 v154, v154
	v_mul_f32_e32 v155, 0xbfb8aa3b, v155
	v_exp_f32_e32 v151, v151
	v_exp_f32_e32 v153, v153
	v_exp_f32_e32 v155, v155
	v_add_f32_e32 v148, 1.0, v148
	v_add_f32_e32 v149, 1.0, v149
	v_add_f32_e32 v152, 1.0, v152
	v_add_f32_e32 v154, 1.0, v154
	v_rcp_f32_e32 v148, v148
	v_rcp_f32_e32 v149, v149
	v_add_f32_e32 v151, 1.0, v151
	v_rcp_f32_e32 v152, v152
	v_add_f32_e32 v153, 1.0, v153
	v_rcp_f32_e32 v154, v154
	v_add_f32_e32 v155, 1.0, v155
	v_rcp_f32_e32 v151, v151
	v_rcp_f32_e32 v153, v153
	v_rcp_f32_e32 v155, v155
	v_cvt_pk_bf16_f32 v148, v148, v149
	v_cvt_pk_bf16_f32 v149, v152, v154
	v_add_co_u32_e32 v152, vcc, s4, v136
	v_cvt_pk_bf16_f32 v150, v150, v151
	v_cvt_pk_bf16_f32 v151, v153, v155
	v_addc_co_u32_e32 v153, vcc, 0, v137, vcc
	global_store_dwordx4 v[152:153], v[148:151], off
	v_fma_f32 v152, v54, v142, v134
	v_fma_f32 v154, v55, v142, v135
	v_fma_f32 v149, v48, v142, v128
	v_mul_f32_e32 v149, 0xbfb8aa3b, v149
	v_exp_f32_e32 v149, v149
	v_fma_f32 v148, v52, v142, v132
	v_mul_f32_e32 v148, 0xbfb8aa3b, v148
	v_fma_f32 v151, v49, v142, v129
	v_add_f32_e32 v149, 1.0, v149
	v_rcp_f32_e32 v150, v149
	v_fma_f32 v149, v53, v142, v133
	v_mul_f32_e32 v149, 0xbfb8aa3b, v149
	v_mul_f32_e32 v152, 0xbfb8aa3b, v152
	v_fma_f32 v153, v50, v142, v130
	v_mul_f32_e32 v154, 0xbfb8aa3b, v154
	v_fma_f32 v155, v51, v142, v131
	v_exp_f32_e32 v148, v148
	v_exp_f32_e32 v149, v149
	v_mul_f32_e32 v151, 0xbfb8aa3b, v151
	v_exp_f32_e32 v152, v152
	v_mul_f32_e32 v153, 0xbfb8aa3b, v153
	v_exp_f32_e32 v154, v154
	v_mul_f32_e32 v155, 0xbfb8aa3b, v155
	v_exp_f32_e32 v151, v151
	v_exp_f32_e32 v153, v153
	v_exp_f32_e32 v155, v155
	v_add_f32_e32 v148, 1.0, v148
	v_add_f32_e32 v149, 1.0, v149
	v_add_f32_e32 v152, 1.0, v152
	v_add_f32_e32 v154, 1.0, v154
	v_rcp_f32_e32 v148, v148
	v_rcp_f32_e32 v149, v149
	v_add_f32_e32 v151, 1.0, v151
	v_rcp_f32_e32 v152, v152
	v_add_f32_e32 v153, 1.0, v153
	v_rcp_f32_e32 v154, v154
	v_add_f32_e32 v155, 1.0, v155
	v_rcp_f32_e32 v151, v151
	v_rcp_f32_e32 v153, v153
	v_rcp_f32_e32 v155, v155
	v_cvt_pk_bf16_f32 v148, v148, v149
	v_cvt_pk_bf16_f32 v149, v152, v154
	v_add_co_u32_e32 v152, vcc, s6, v136
	v_cvt_pk_bf16_f32 v150, v150, v151
	v_cvt_pk_bf16_f32 v151, v153, v155
	v_addc_co_u32_e32 v153, vcc, 0, v137, vcc
	global_store_dwordx4 v[152:153], v[148:151], off
	v_fma_f32 v152, v46, v141, v134
	v_fma_f32 v154, v47, v141, v135
	v_fma_f32 v149, v40, v141, v128
	v_mul_f32_e32 v149, 0xbfb8aa3b, v149
	v_exp_f32_e32 v149, v149
	v_fma_f32 v148, v44, v141, v132
	v_mul_f32_e32 v148, 0xbfb8aa3b, v148
	v_fma_f32 v151, v41, v141, v129
	v_add_f32_e32 v149, 1.0, v149
	v_rcp_f32_e32 v150, v149
	v_fma_f32 v149, v45, v141, v133
	v_mul_f32_e32 v149, 0xbfb8aa3b, v149
	v_mul_f32_e32 v152, 0xbfb8aa3b, v152
	v_fma_f32 v153, v42, v141, v130
	v_mul_f32_e32 v154, 0xbfb8aa3b, v154
	v_fma_f32 v155, v43, v141, v131
	v_exp_f32_e32 v148, v148
	v_exp_f32_e32 v149, v149
	v_mul_f32_e32 v151, 0xbfb8aa3b, v151
	v_exp_f32_e32 v152, v152
	v_mul_f32_e32 v153, 0xbfb8aa3b, v153
	v_exp_f32_e32 v154, v154
	v_mul_f32_e32 v155, 0xbfb8aa3b, v155
	v_exp_f32_e32 v151, v151
	v_exp_f32_e32 v153, v153
	v_exp_f32_e32 v155, v155
	v_add_f32_e32 v148, 1.0, v148
	v_add_f32_e32 v149, 1.0, v149
	v_add_f32_e32 v152, 1.0, v152
	v_add_f32_e32 v154, 1.0, v154
	v_fma_f32 v128, v32, v140, v128
	v_rcp_f32_e32 v148, v148
	v_rcp_f32_e32 v149, v149
	v_add_f32_e32 v151, 1.0, v151
	v_rcp_f32_e32 v152, v152
	v_add_f32_e32 v153, 1.0, v153
	v_rcp_f32_e32 v154, v154
	v_add_f32_e32 v155, 1.0, v155
	v_mul_f32_e32 v128, 0xbfb8aa3b, v128
; __device__ __forceinline__ u32x4 pack8(const f32x4& a, const f32x4& b) { u32x4 w; w.x = pk2(a[0], a[1]); w.y = pk2(a[2], a[3]); w.z = pk2(b[0], b[1]); w.w = pk2(b[2], b[3]); return w; }
; __device__ __forceinline__ float sigm(float x) { return __builtin_amdgcn_rcpf(1.0f + __builtin_amdgcn_exp2f(x * -1.4426950408889634f)); }
;     __device__ __forceinline__ void operator()(const f32x4 (&acc)[2][2][4][2], const Unit& u, int wr, int wc, int fr, int fq) const {
;     ...
;             for (int bj = 0; bj < 2; ++bj) {
;                 const f32x4 bv0 = *(const f32x4*)(gb + br * 1024 + col0 + 128 * bj), bv1 = *(const f32x4*)(gb + br * 1024 + col0 + 128 * bj + 4);
; #pragma unroll
;                 for (int ai = 0; ai < 2; ++ai)
; #pragma unroll
;                     for (int m = 0; m < 4; ++m) {
;                         const f32x4 a0 = acc[ai][bj][m][0] * rx[ai][m] + bv0, a1 = acc[ai][bj][m][1] * rx[ai][m] + bv1; f32x4 o0, o1;
; #pragma unroll
;                         for (int e = 0; e < 4; ++e) { o0[e] = sigm(a0[e]); o1[e] = sigm(a1[e]); }
;                         *(u32x4*)(tmpb + ((ai * 4 + m) * 2 + bj) * 8192 + voff) = pack8(o0, o1); }
;                 asm volatile("" ::: "memory"); }
	v_fma_f32 v129, v33, v140, v129
	v_rcp_f32_e32 v151, v151
	v_rcp_f32_e32 v153, v153
	v_rcp_f32_e32 v155, v155
	v_exp_f32_e32 v128, v128
	v_mul_f32_e32 v129, 0xbfb8aa3b, v129
	v_fma_f32 v130, v34, v140, v130
	v_exp_f32_e32 v129, v129
	v_mul_f32_e32 v130, 0xbfb8aa3b, v130
	v_exp_f32_e32 v130, v130
	v_cvt_pk_bf16_f32 v148, v148, v149
	v_cvt_pk_bf16_f32 v149, v152, v154
	v_add_co_u32_e32 v152, vcc, s79, v136
	v_cvt_pk_bf16_f32 v150, v150, v151
	v_cvt_pk_bf16_f32 v151, v153, v155
	v_addc_co_u32_e32 v153, vcc, 0, v137, vcc
	v_add_f32_e32 v128, 1.0, v128
	global_store_dwordx4 v[152:153], v[148:151], off
	v_fma_f32 v132, v36, v140, v132
	v_add_f32_e32 v129, 1.0, v129
	v_rcp_f32_e32 v148, v128
	v_fma_f32 v128, v37, v140, v133
	v_mul_f32_e32 v132, 0xbfb8aa3b, v132
	v_mul_f32_e32 v128, 0xbfb8aa3b, v128
	v_rcp_f32_e32 v133, v129
	v_fma_f32 v129, v38, v140, v134
	v_add_f32_e32 v130, 1.0, v130
	v_fmac_f32_e32 v135, v39, v140
	v_fmac_f32_e32 v131, v35, v140
	v_exp_f32_e32 v132, v132
	v_exp_f32_e32 v128, v128
	v_mul_f32_e32 v129, 0xbfb8aa3b, v129
	v_rcp_f32_e32 v134, v130
	v_mul_f32_e32 v130, 0xbfb8aa3b, v135
	v_mul_f32_e32 v131, 0xbfb8aa3b, v131
	v_exp_f32_e32 v129, v129
	v_exp_f32_e32 v130, v130
	v_exp_f32_e32 v131, v131
	v_add_f32_e32 v132, 1.0, v132
	v_add_f32_e32 v128, 1.0, v128
	v_rcp_f32_e32 v132, v132
	v_rcp_f32_e32 v128, v128
	v_add_f32_e32 v129, 1.0, v129
	v_add_f32_e32 v130, 1.0, v130
	v_add_f32_e32 v131, 1.0, v131
	v_rcp_f32_e32 v129, v129
	v_rcp_f32_e32 v130, v130
	v_rcp_f32_e32 v131, v131
	v_cvt_pk_bf16_f32 v128, v132, v128
	v_add_co_u32_e32 v132, vcc, s87, v136
	v_cvt_pk_bf16_f32 v129, v129, v130
	v_cvt_pk_bf16_f32 v130, v148, v133
	v_cvt_pk_bf16_f32 v131, v134, v131
	v_addc_co_u32_e32 v133, vcc, 0, v137, vcc
	global_store_dwordx4 v[132:133], v[128:131], off
	s_movk_i32 s10, 0x6000
	s_waitcnt vmcnt(8)
	v_fma_f32 v149, v89, v147, v157
	v_mul_f32_e32 v149, 0xbfb8aa3b, v149
	v_exp_f32_e32 v149, v149
	s_waitcnt vmcnt(8)
	v_fma_f32 v138, v92, v147, v160
	v_fma_f32 v148, v93, v147, v161
	v_mul_f32_e32 v138, 0xbfb8aa3b, v138
	v_add_f32_e32 v149, 1.0, v149
	v_fma_f32 v139, v88, v147, v156
	v_mul_f32_e32 v148, 0xbfb8aa3b, v148
	v_rcp_f32_e32 v150, v149
	v_fma_f32 v149, v94, v147, v162
	v_fma_f32 v151, v90, v147, v158
	v_fma_f32 v152, v95, v147, v163
	v_fma_f32 v147, v91, v147, v159
	v_exp_f32_e32 v138, v138
	v_mul_f32_e32 v139, 0xbfb8aa3b, v139
	v_exp_f32_e32 v148, v148
	v_mul_f32_e32 v149, 0xbfb8aa3b, v149
	v_mul_f32_e32 v151, 0xbfb8aa3b, v151
	v_mul_f32_e32 v152, 0xbfb8aa3b, v152
	v_mul_f32_e32 v147, 0xbfb8aa3b, v147
	v_exp_f32_e32 v139, v139
	v_exp_f32_e32 v149, v149
	v_exp_f32_e32 v151, v151
	v_exp_f32_e32 v152, v152
	v_exp_f32_e32 v147, v147
	v_add_f32_e32 v138, 1.0, v138
	v_add_f32_e32 v148, 1.0, v148
	v_rcp_f32_e32 v138, v138
	v_add_f32_e32 v139, 1.0, v139
	v_rcp_f32_e32 v148, v148
	v_add_f32_e32 v149, 1.0, v149
	v_add_f32_e32 v151, 1.0, v151
	v_add_f32_e32 v152, 1.0, v152
	v_add_f32_e32 v147, 1.0, v147
	v_rcp_f32_e32 v139, v139
	v_rcp_f32_e32 v149, v149
	v_rcp_f32_e32 v151, v151
	v_rcp_f32_e32 v152, v152
	v_rcp_f32_e32 v147, v147
	v_cvt_pk_bf16_f32 v148, v138, v148
	v_add_co_u32_e32 v138, vcc, s82, v136
	v_cvt_pk_bf16_f32 v149, v149, v152
	v_cvt_pk_bf16_f32 v150, v139, v150
	v_cvt_pk_bf16_f32 v151, v151, v147
	v_addc_co_u32_e32 v139, vcc, 0, v137, vcc
	global_store_dwordx4 v[138:139], v[148:151], off
	v_fma_f32 v138, v84, v145, v160
	v_fma_f32 v147, v85, v145, v161
	v_fma_f32 v148, v81, v145, v157
	v_mul_f32_e32 v148, 0xbfb8aa3b, v148
	v_exp_f32_e32 v148, v148
	v_mul_f32_e32 v138, 0xbfb8aa3b, v138
	v_mul_f32_e32 v147, 0xbfb8aa3b, v147
	v_exp_f32_e32 v138, v138
	v_add_f32_e32 v148, 1.0, v148
	v_rcp_f32_e32 v150, v148
	v_fma_f32 v148, v86, v145, v162
	v_mul_f32_e32 v148, 0xbfb8aa3b, v148
	v_exp_f32_e32 v148, v148
	v_exp_f32_e32 v147, v147
	v_fma_f32 v139, v80, v145, v156
	v_add_f32_e32 v138, 1.0, v138
	v_add_f32_e32 v148, 1.0, v148
	v_rcp_f32_e32 v149, v148
	v_fma_f32 v148, v82, v145, v158
	v_mul_f32_e32 v148, 0xbfb8aa3b, v148
	v_exp_f32_e32 v148, v148
	v_mul_f32_e32 v139, 0xbfb8aa3b, v139
	v_add_f32_e32 v147, 1.0, v147
	v_rcp_f32_e32 v138, v138
	v_add_f32_e32 v148, 1.0, v148
	v_rcp_f32_e32 v151, v148
	v_fma_f32 v148, v87, v145, v163
	v_mul_f32_e32 v148, 0xbfb8aa3b, v148
	v_fma_f32 v145, v83, v145, v159
	v_exp_f32_e32 v148, v148
	v_mul_f32_e32 v145, 0xbfb8aa3b, v145
	v_exp_f32_e32 v139, v139
	v_rcp_f32_e32 v147, v147
	v_exp_f32_e32 v145, v145
	v_add_f32_e32 v148, 1.0, v148
	v_add_f32_e32 v139, 1.0, v139
	v_rcp_f32_e32 v152, v148
	v_add_f32_e32 v145, 1.0, v145
	v_cvt_pk_bf16_f32 v148, v138, v147
	v_fma_f32 v147, v73, v146, v157
	v_rcp_f32_e32 v139, v139
	v_rcp_f32_e32 v145, v145
	v_mul_f32_e32 v147, 0xbfb8aa3b, v147
	v_exp_f32_e32 v147, v147
	v_add_co_u32_e32 v138, vcc, s10, v136
	v_cvt_pk_bf16_f32 v149, v149, v152
	v_cvt_pk_bf16_f32 v150, v139, v150
	v_cvt_pk_bf16_f32 v151, v151, v145
	v_addc_co_u32_e32 v139, vcc, 0, v137, vcc
	global_store_dwordx4 v[138:139], v[148:151], off
	v_fma_f32 v138, v76, v146, v160
	v_fma_f32 v145, v77, v146, v161
	v_add_f32_e32 v147, 1.0, v147
	v_mul_f32_e32 v138, 0xbfb8aa3b, v138
	v_fma_f32 v139, v72, v146, v156
	v_mul_f32_e32 v145, 0xbfb8aa3b, v145
	v_rcp_f32_e32 v148, v147
	v_fma_f32 v147, v78, v146, v162
	v_fma_f32 v149, v74, v146, v158
	v_fma_f32 v150, v79, v146, v163
	v_fma_f32 v146, v75, v146, v159
	v_exp_f32_e32 v138, v138
	v_mul_f32_e32 v139, 0xbfb8aa3b, v139
	v_exp_f32_e32 v145, v145
	v_mul_f32_e32 v147, 0xbfb8aa3b, v147
	v_mul_f32_e32 v149, 0xbfb8aa3b, v149
	v_mul_f32_e32 v150, 0xbfb8aa3b, v150
	v_mul_f32_e32 v146, 0xbfb8aa3b, v146
	v_exp_f32_e32 v139, v139
	v_exp_f32_e32 v147, v147
	v_exp_f32_e32 v149, v149
; __device__ __forceinline__ u32x4 pack8(const f32x4& a, const f32x4& b) { u32x4 w; w.x = pk2(a[0], a[1]); w.y = pk2(a[2], a[3]); w.z = pk2(b[0], b[1]); w.w = pk2(b[2], b[3]); return w; }
; __device__ __forceinline__ float sigm(float x) { return __builtin_amdgcn_rcpf(1.0f + __builtin_amdgcn_exp2f(x * -1.4426950408889634f)); }
;     __device__ __forceinline__ void operator()(const f32x4 (&acc)[2][2][4][2], const Unit& u, int wr, int wc, int fr, int fq) const {
;     ...
;             for (int bj = 0; bj < 2; ++bj) {
;                 const f32x4 bv0 = *(const f32x4*)(gb + br * 1024 + col0 + 128 * bj), bv1 = *(const f32x4*)(gb + br * 1024 + col0 + 128 * bj + 4);
; #pragma unroll
;                 for (int ai = 0; ai < 2; ++ai)
; #pragma unroll
;                     for (int m = 0; m < 4; ++m) {
;                         const f32x4 a0 = acc[ai][bj][m][0] * rx[ai][m] + bv0, a1 = acc[ai][bj][m][1] * rx[ai][m] + bv1; f32x4 o0, o1;
; #pragma unroll
;                         for (int e = 0; e < 4; ++e) { o0[e] = sigm(a0[e]); o1[e] = sigm(a1[e]); }
;                         *(u32x4*)(tmpb + ((ai * 4 + m) * 2 + bj) * 8192 + voff) = pack8(o0, o1); }
;                 asm volatile("" ::: "memory"); }
	v_exp_f32_e32 v150, v150
	v_exp_f32_e32 v146, v146
	v_add_f32_e32 v138, 1.0, v138
	v_add_f32_e32 v145, 1.0, v145
	v_rcp_f32_e32 v138, v138
	v_add_f32_e32 v139, 1.0, v139
	v_rcp_f32_e32 v145, v145
	v_add_f32_e32 v147, 1.0, v147
	v_add_f32_e32 v149, 1.0, v149
	v_add_f32_e32 v150, 1.0, v150
	v_add_f32_e32 v146, 1.0, v146
	v_rcp_f32_e32 v139, v139
	v_rcp_f32_e32 v147, v147
	v_rcp_f32_e32 v149, v149
	v_rcp_f32_e32 v150, v150
	v_rcp_f32_e32 v151, v146
	s_mov_b32 s10, 0xa000
	v_cvt_pk_bf16_f32 v146, v138, v145
	v_add_co_u32_e32 v138, vcc, s10, v136
	v_cvt_pk_bf16_f32 v147, v147, v150
	v_cvt_pk_bf16_f32 v148, v139, v148
	v_cvt_pk_bf16_f32 v149, v149, v151
	v_addc_co_u32_e32 v139, vcc, 0, v137, vcc
	global_store_dwordx4 v[138:139], v[146:149], off
	v_fma_f32 v138, v68, v143, v160
	v_fma_f32 v145, v69, v143, v161
	v_fma_f32 v146, v65, v143, v157
	v_mul_f32_e32 v146, 0xbfb8aa3b, v146
	v_exp_f32_e32 v146, v146
	v_mul_f32_e32 v138, 0xbfb8aa3b, v138
	v_mul_f32_e32 v145, 0xbfb8aa3b, v145
	v_exp_f32_e32 v138, v138
	v_add_f32_e32 v146, 1.0, v146
	v_rcp_f32_e32 v148, v146
	v_fma_f32 v146, v70, v143, v162
	v_mul_f32_e32 v146, 0xbfb8aa3b, v146
	v_exp_f32_e32 v146, v146
	v_exp_f32_e32 v145, v145
	v_fma_f32 v139, v64, v143, v156
	v_add_f32_e32 v138, 1.0, v138
	v_add_f32_e32 v146, 1.0, v146
	v_rcp_f32_e32 v147, v146
	v_fma_f32 v146, v66, v143, v158
	v_mul_f32_e32 v146, 0xbfb8aa3b, v146
	v_exp_f32_e32 v146, v146
	v_mul_f32_e32 v139, 0xbfb8aa3b, v139
	v_add_f32_e32 v145, 1.0, v145
	v_rcp_f32_e32 v138, v138
	v_add_f32_e32 v146, 1.0, v146
	v_rcp_f32_e32 v149, v146
	v_fma_f32 v146, v71, v143, v163
	v_mul_f32_e32 v146, 0xbfb8aa3b, v146
	v_fma_f32 v143, v67, v143, v159
	v_exp_f32_e32 v146, v146
	v_mul_f32_e32 v143, 0xbfb8aa3b, v143
	v_exp_f32_e32 v139, v139
	v_rcp_f32_e32 v145, v145
	v_exp_f32_e32 v143, v143
	v_add_f32_e32 v146, 1.0, v146
	v_add_f32_e32 v139, 1.0, v139
	v_rcp_f32_e32 v150, v146
	v_add_f32_e32 v143, 1.0, v143
	v_cvt_pk_bf16_f32 v146, v138, v145
	v_fma_f32 v145, v25, v144, v157
	v_rcp_f32_e32 v139, v139
	v_rcp_f32_e32 v143, v143
	v_mul_f32_e32 v145, 0xbfb8aa3b, v145
	v_exp_f32_e32 v145, v145
	v_add_co_u32_e32 v138, vcc, s98, v136
	v_cvt_pk_bf16_f32 v147, v147, v150
	v_cvt_pk_bf16_f32 v148, v139, v148
	v_cvt_pk_bf16_f32 v149, v149, v143
	v_addc_co_u32_e32 v139, vcc, 0, v137, vcc
	global_store_dwordx4 v[138:139], v[146:149], off
	v_fma_f32 v138, v28, v144, v160
	v_fma_f32 v143, v29, v144, v161
	v_add_f32_e32 v145, 1.0, v145
	v_mul_f32_e32 v138, 0xbfb8aa3b, v138
	v_fma_f32 v139, v24, v144, v156
	v_mul_f32_e32 v143, 0xbfb8aa3b, v143
	v_rcp_f32_e32 v146, v145
	v_fma_f32 v145, v30, v144, v162
	v_fma_f32 v147, v26, v144, v158
	v_fma_f32 v148, v31, v144, v163
	v_fma_f32 v144, v27, v144, v159
	v_exp_f32_e32 v138, v138
	v_mul_f32_e32 v139, 0xbfb8aa3b, v139
	v_exp_f32_e32 v143, v143
	v_mul_f32_e32 v145, 0xbfb8aa3b, v145
	v_mul_f32_e32 v147, 0xbfb8aa3b, v147
	v_mul_f32_e32 v148, 0xbfb8aa3b, v148
	v_mul_f32_e32 v144, 0xbfb8aa3b, v144
	v_exp_f32_e32 v139, v139
	v_exp_f32_e32 v145, v145
	v_exp_f32_e32 v147, v147
	v_exp_f32_e32 v148, v148
	v_exp_f32_e32 v144, v144
	v_add_f32_e32 v138, 1.0, v138
	v_add_f32_e32 v143, 1.0, v143
	v_rcp_f32_e32 v138, v138
	v_add_f32_e32 v139, 1.0, v139
	v_rcp_f32_e32 v143, v143
	v_add_f32_e32 v145, 1.0, v145
	v_add_f32_e32 v147, 1.0, v147
	v_add_f32_e32 v148, 1.0, v148
	v_add_f32_e32 v144, 1.0, v144
	v_rcp_f32_e32 v139, v139
	v_rcp_f32_e32 v145, v145
	v_rcp_f32_e32 v147, v147
	v_rcp_f32_e32 v148, v148
	v_rcp_f32_e32 v149, v144
	v_cvt_pk_bf16_f32 v144, v138, v143
	v_add_co_u32_e32 v138, vcc, s5, v136
	v_cvt_pk_bf16_f32 v145, v145, v148
	v_cvt_pk_bf16_f32 v146, v139, v146
	v_cvt_pk_bf16_f32 v147, v147, v149
	v_addc_co_u32_e32 v139, vcc, 0, v137, vcc
	global_store_dwordx4 v[138:139], v[144:147], off
	v_fma_f32 v138, v20, v142, v160
	v_fma_f32 v143, v21, v142, v161
	v_mul_f32_e32 v138, 0xbfb8aa3b, v138
	v_fma_f32 v139, v16, v142, v156
	v_mul_f32_e32 v143, 0xbfb8aa3b, v143
	v_fma_f32 v144, v17, v142, v157
	v_fma_f32 v145, v22, v142, v162
	v_fma_f32 v146, v18, v142, v158
	v_fma_f32 v147, v23, v142, v163
	v_fma_f32 v142, v19, v142, v159
	v_exp_f32_e32 v138, v138
; __device__ __forceinline__ u32x4 pack8(const f32x4& a, const f32x4& b) { u32x4 w; w.x = pk2(a[0], a[1]); w.y = pk2(a[2], a[3]); w.z = pk2(b[0], b[1]); w.w = pk2(b[2], b[3]); return w; }
; __device__ __forceinline__ float sigm(float x) { return __builtin_amdgcn_rcpf(1.0f + __builtin_amdgcn_exp2f(x * -1.4426950408889634f)); }
;     __device__ __forceinline__ void operator()(const f32x4 (&acc)[2][2][4][2], const Unit& u, int wr, int wc, int fr, int fq) const {
;     ...
;             for (int bj = 0; bj < 2; ++bj) {
;                 const f32x4 bv0 = *(const f32x4*)(gb + br * 1024 + col0 + 128 * bj), bv1 = *(const f32x4*)(gb + br * 1024 + col0 + 128 * bj + 4);
; #pragma unroll
;                 for (int ai = 0; ai < 2; ++ai)
; #pragma unroll
;                     for (int m = 0; m < 4; ++m) {
;                         const f32x4 a0 = acc[ai][bj][m][0] * rx[ai][m] + bv0, a1 = acc[ai][bj][m][1] * rx[ai][m] + bv1; f32x4 o0, o1;
; #pragma unroll
;                         for (int e = 0; e < 4; ++e) { o0[e] = sigm(a0[e]); o1[e] = sigm(a1[e]); }
;                         *(u32x4*)(tmpb + ((ai * 4 + m) * 2 + bj) * 8192 + voff) = pack8(o0, o1); }
;                 asm volatile("" ::: "memory"); }
	v_mul_f32_e32 v139, 0xbfb8aa3b, v139
	v_exp_f32_e32 v143, v143
	v_mul_f32_e32 v144, 0xbfb8aa3b, v144
	v_mul_f32_e32 v145, 0xbfb8aa3b, v145
	v_mul_f32_e32 v146, 0xbfb8aa3b, v146
	v_mul_f32_e32 v147, 0xbfb8aa3b, v147
	v_mul_f32_e32 v142, 0xbfb8aa3b, v142
	v_exp_f32_e32 v139, v139
	v_exp_f32_e32 v144, v144
	v_exp_f32_e32 v145, v145
	v_exp_f32_e32 v146, v146
	v_exp_f32_e32 v147, v147
	v_exp_f32_e32 v142, v142
	v_add_f32_e32 v138, 1.0, v138
	v_add_f32_e32 v143, 1.0, v143
	v_rcp_f32_e32 v138, v138
	v_add_f32_e32 v139, 1.0, v139
	v_rcp_f32_e32 v143, v143
	v_add_f32_e32 v144, 1.0, v144
	v_add_f32_e32 v145, 1.0, v145
	v_add_f32_e32 v146, 1.0, v146
	v_add_f32_e32 v147, 1.0, v147
	v_add_f32_e32 v142, 1.0, v142
	v_rcp_f32_e32 v139, v139
	v_rcp_f32_e32 v144, v144
	v_rcp_f32_e32 v145, v145
	v_rcp_f32_e32 v146, v146
	v_rcp_f32_e32 v147, v147
	v_rcp_f32_e32 v148, v142
	v_cvt_pk_bf16_f32 v142, v138, v143
	v_add_co_u32_e32 v138, vcc, s7, v136
	v_cvt_pk_bf16_f32 v143, v145, v147
	v_cvt_pk_bf16_f32 v144, v139, v144
	v_cvt_pk_bf16_f32 v145, v146, v148
	v_addc_co_u32_e32 v139, vcc, 0, v137, vcc
	global_store_dwordx4 v[138:139], v[142:145], off
	v_fma_f32 v138, v12, v141, v160
	v_mul_f32_e32 v138, 0xbfb8aa3b, v138
	v_fma_f32 v143, v9, v141, v157
	v_mul_f32_e32 v143, 0xbfb8aa3b, v143
	v_exp_f32_e32 v143, v143
	v_fma_f32 v142, v13, v141, v161
	v_fma_f32 v139, v8, v141, v156
	v_mul_f32_e32 v142, 0xbfb8aa3b, v142
	v_add_f32_e32 v143, 1.0, v143
	v_rcp_f32_e32 v144, v143
	v_fma_f32 v143, v14, v141, v162
	v_fma_f32 v145, v10, v141, v158
	v_fma_f32 v146, v15, v141, v163
	v_fma_f32 v141, v11, v141, v159
	v_exp_f32_e32 v138, v138
	v_mul_f32_e32 v139, 0xbfb8aa3b, v139
	v_exp_f32_e32 v142, v142
	v_mul_f32_e32 v143, 0xbfb8aa3b, v143
	v_mul_f32_e32 v145, 0xbfb8aa3b, v145
	v_mul_f32_e32 v146, 0xbfb8aa3b, v146
	v_mul_f32_e32 v141, 0xbfb8aa3b, v141
	v_exp_f32_e32 v139, v139
	v_exp_f32_e32 v143, v143
	v_exp_f32_e32 v145, v145
	v_exp_f32_e32 v146, v146
	v_exp_f32_e32 v141, v141
	v_add_f32_e32 v138, 1.0, v138
	v_add_f32_e32 v142, 1.0, v142
	v_fma_f32 v128, v0, v140, v156
	v_rcp_f32_e32 v138, v138
	v_add_f32_e32 v139, 1.0, v139
	v_rcp_f32_e32 v142, v142
	v_add_f32_e32 v143, 1.0, v143
	v_add_f32_e32 v145, 1.0, v145
	v_add_f32_e32 v146, 1.0, v146
	v_add_f32_e32 v141, 1.0, v141
	v_mul_f32_e32 v128, 0xbfb8aa3b, v128
	v_fma_f32 v129, v1, v140, v157
	v_rcp_f32_e32 v139, v139
	v_rcp_f32_e32 v143, v143
	v_rcp_f32_e32 v145, v145
	v_rcp_f32_e32 v146, v146
	v_rcp_f32_e32 v141, v141
	v_exp_f32_e32 v128, v128
	v_mul_f32_e32 v129, 0xbfb8aa3b, v129
	v_fma_f32 v130, v2, v140, v158
	v_exp_f32_e32 v129, v129
	v_mul_f32_e32 v130, 0xbfb8aa3b, v130
	v_exp_f32_e32 v130, v130
	v_cvt_pk_bf16_f32 v142, v138, v142
	v_add_co_u32_e32 v138, vcc, s85, v136
	v_cvt_pk_bf16_f32 v143, v143, v146
	v_cvt_pk_bf16_f32 v144, v139, v144
	v_cvt_pk_bf16_f32 v145, v145, v141
	v_addc_co_u32_e32 v139, vcc, 0, v137, vcc
	v_add_f32_e32 v128, 1.0, v128
	global_store_dwordx4 v[138:139], v[142:145], off
	v_fma_f32 v132, v4, v140, v160
	v_rcp_f32_e32 v138, v128
	v_fma_f32 v128, v5, v140, v161
	v_add_f32_e32 v129, 1.0, v129
	v_mul_f32_e32 v132, 0xbfb8aa3b, v132
	v_mul_f32_e32 v128, 0xbfb8aa3b, v128
	v_rcp_f32_e32 v133, v129
	v_fma_f32 v129, v6, v140, v162
	v_add_f32_e32 v130, 1.0, v130
	v_fma_f32 v135, v7, v140, v163
	v_fma_f32 v131, v3, v140, v159
	v_exp_f32_e32 v132, v132
	v_exp_f32_e32 v128, v128
	v_mul_f32_e32 v129, 0xbfb8aa3b, v129
	v_rcp_f32_e32 v134, v130
	v_mul_f32_e32 v130, 0xbfb8aa3b, v135
	v_mul_f32_e32 v131, 0xbfb8aa3b, v131
	v_exp_f32_e32 v129, v129
	v_exp_f32_e32 v130, v130
	v_exp_f32_e32 v131, v131
	v_add_f32_e32 v132, 1.0, v132
	v_add_f32_e32 v128, 1.0, v128
	v_rcp_f32_e32 v132, v132
	v_rcp_f32_e32 v128, v128
	v_add_f32_e32 v129, 1.0, v129
	v_add_f32_e32 v130, 1.0, v130
	v_add_f32_e32 v131, 1.0, v131
	v_rcp_f32_e32 v129, v129
	v_rcp_f32_e32 v130, v130
	v_rcp_f32_e32 v131, v131
	v_cvt_pk_bf16_f32 v128, v132, v128
	v_add_co_u32_e32 v132, vcc, 0x1e000, v136
	v_cvt_pk_bf16_f32 v129, v129, v130
	v_cvt_pk_bf16_f32 v130, v138, v133
	v_cvt_pk_bf16_f32 v131, v134, v131
	v_addc_co_u32_e32 v133, vcc, 0, v137, vcc
	global_store_dwordx4 v[132:133], v[128:131], off
